# trailing half's restore-offset barrier moved from before the unit header to after it (flag in s32) so its header SALU overlaps the leading half's header + first load segment; on top of P8 de-renaming
# speedup vs baseline: 1.0049x; 1.0024x over previous
; #define LAS __attribute__((address_space(3)))
; __device__ __forceinline__ unsigned xb_add(unsigned* p, unsigned v) { return __hip_atomic_fetch_add(p, v, __ATOMIC_RELAXED, __HIP_MEMORY_SCOPE_AGENT); }
; __device__ __forceinline__ unsigned xb_xcc_id() { return (unsigned)__builtin_amdgcn_s_getreg((3 << 11) | 20) & 0xFu; }
; #define LAS __attribute__((address_space(3)))
; __device__ __forceinline__ XcdBarrier xcd_barrier_post(unsigned* bar, volatile LAS unsigned* st) {
;     XcdBarrier b; b.bar = bar; b.x = xb_xcc_id(); b.st = st;
;     if (threadIdx.x == 0) (void)xb_add(&bar[XB_XCNT(b.x)], 1u);
;     return b;
; __global__ void __launch_bounds__(512, 2) fwd(Args args) {
;     extern __shared__ __attribute__((aligned(16))) unsigned char lds[];
;     LAS unsigned char* L = (LAS unsigned char*)lds;
;     const int tid = threadIdx.x;
;     const int G = gridDim.x;
;     unsigned char* ws = args.ws;
;     for (int u = tid; u < (LDS_BYTES - LDSCTL_OFF) / 4; u += 512) ((LAS unsigned*)(L + LDSCTL_OFF))[u] = 0u;
;     __syncthreads();
;     const int lo = args.ph_lo, hi = args.ph_hi;
;     const bool use_bar = (hi - lo) > 1;
;     XcdBarrier bar; bar.bar = (unsigned*)(ws + WS_CTL) + CW_BAR; bar.x = 0; bar.st = (volatile LAS unsigned*)(L + LDSCTL_OFF);
;     if (use_bar) bar = xcd_barrier_post((unsigned*)(ws + WS_CTL) + CW_BAR, (volatile LAS unsigned*)(L + LDSCTL_OFF));
_Z3fwd4Args:
	s_mov_b32 s32, 0
	s_load_dword s3, s[0:1], 0xf0
	s_add_u32 s4, s0, 0xf0
	s_addc_u32 s5, s1, 0
	v_lshl_add_u32 v1, v0, 2, 0
	v_writelane_b32 v251, s4, 0
	v_add_u32_e32 v1, 0x20000, v1
	v_mov_b32_e32 v2, 0
	v_writelane_b32 v251, s5, 1
	ds_write2st64_b32 v1, v2, v2 offset1:8
	ds_write2st64_b32 v1, v2, v2 offset0:16 offset1:24
	v_or_b32_e32 v1, 0x800, v0
	s_mov_b64 s[4:5], -1
	s_and_saveexec_b64 s[6:7], s[4:5]
	v_lshl_add_u32 v3, v1, 2, 0
	v_add_u32_e32 v3, 0x20000, v3
	ds_write_b32 v3, v2
	s_or_b64 exec, exec, s[6:7]
	s_and_saveexec_b64 s[6:7], s[4:5]
	s_add_i32 s4, 0, 0x20000
	v_lshl_add_u32 v1, v1, 2, s4
	v_mov_b32_e32 v2, 0
	ds_write_b32 v1, v2 offset:2048
	s_or_b64 exec, exec, s[6:7]
	s_load_dwordx2 s[66:67], s[0:1], 0xe0
	v_or_b32_e32 v1, 0xc00, v0
	v_cmp_gt_u32_e64 s[4:5], 7, 6
	v_cmp_gt_u32_e64 s[8:9], 7, 5
	s_and_saveexec_b64 s[6:7], s[8:9]
	v_lshl_add_u32 v2, v1, 2, 0
	v_add_u32_e32 v2, 0x20000, v2
	v_mov_b32_e32 v3, 0
	ds_write_b32 v2, v3
	s_or_b64 exec, exec, s[6:7]
	s_load_dwordx8 s[8:15], s[0:1], 0xc0
	s_waitcnt lgkmcnt(0)
	v_writelane_b32 v251, s8, 2
	s_nop 1
	v_writelane_b32 v251, s9, 3
	v_writelane_b32 v251, s10, 4
	v_writelane_b32 v251, s11, 5
	v_writelane_b32 v251, s12, 6
	v_writelane_b32 v251, s13, 7
	v_writelane_b32 v251, s14, 8
	v_writelane_b32 v251, s15, 9
	s_and_saveexec_b64 s[6:7], s[4:5]
	s_add_i32 s4, 0, 0x20000
	v_lshl_add_u32 v1, v1, 2, s4
	v_mov_b32_e32 v2, 0
	ds_write_b32 v1, v2 offset:2048
	s_or_b64 exec, exec, s[6:7]
	s_load_dwordx16 s[44:59], s[0:1], 0x0
	s_load_dwordx16 s[4:19], s[0:1], 0x40
	v_cmp_eq_u32_e32 vcc, 0, v0
	s_waitcnt lgkmcnt(0)
	s_barrier
	v_writelane_b32 v251, s4, 10
	s_nop 1
	v_writelane_b32 v251, s5, 11
	v_writelane_b32 v251, s6, 12
	v_writelane_b32 v251, s7, 13
	v_writelane_b32 v251, s8, 14
	v_writelane_b32 v251, s9, 15
	v_writelane_b32 v251, s10, 16
	v_writelane_b32 v251, s11, 17
	v_writelane_b32 v251, s12, 18
	v_writelane_b32 v251, s13, 19
	v_writelane_b32 v251, s14, 20
	v_writelane_b32 v251, s15, 21
	v_writelane_b32 v251, s16, 22
	v_writelane_b32 v251, s17, 23
	v_writelane_b32 v251, s18, 24
	v_writelane_b32 v251, s19, 25
	s_load_dwordx16 s[4:19], s[0:1], 0x80
	s_sub_i32 s0, s67, s66
	s_mov_b32 s1, 0
	s_waitcnt lgkmcnt(0)
	v_writelane_b32 v251, s4, 26
	s_nop 1
	v_writelane_b32 v251, s5, 27
	v_writelane_b32 v251, s6, 28
	v_writelane_b32 v251, s7, 29
	v_writelane_b32 v251, s8, 30
	v_writelane_b32 v251, s9, 31
	v_writelane_b32 v251, s10, 32
	v_writelane_b32 v251, s11, 33
	v_writelane_b32 v251, s12, 34
	v_writelane_b32 v251, s13, 35
	v_writelane_b32 v251, s14, 36
	v_writelane_b32 v251, s15, 37
	v_writelane_b32 v251, s16, 38
	v_writelane_b32 v251, s17, 39
	v_writelane_b32 v251, s18, 40
	v_writelane_b32 v251, s19, 41
	s_nop 0
	v_readlane_b32 s4, v251, 2
	v_readlane_b32 s10, v251, 8
	v_readlane_b32 s11, v251, 9
	s_add_u32 s18, s10, 0x4000
	s_addc_u32 s19, s11, 0
	s_cmp_lt_i32 s0, 2
	s_mov_b32 s0, 0
	v_readlane_b32 s5, v251, 3
	v_readlane_b32 s6, v251, 4
	v_readlane_b32 s7, v251, 5
	v_readlane_b32 s8, v251, 6
	v_readlane_b32 s9, v251, 7
	s_cbranch_scc1 .LBB0_13
	s_getreg_b32 s0, hwreg(HW_REG_XCC_ID, 0, 4)
	s_and_b32 s0, s0, 15
	s_and_saveexec_b64 s[4:5], vcc
	s_cbranch_execz .LBB0_12
	s_mov_b64 s[6:7], exec
	v_mbcnt_lo_u32_b32 v1, s6, 0
	v_mbcnt_hi_u32_b32 v1, s7, v1
	v_cmp_eq_u32_e32 vcc, 0, v1
	s_and_b64 s[8:9], exec, vcc
	s_mov_b64 exec, s[8:9]
	s_cbranch_execz .LBB0_12
	s_lshl_b32 s8, s0, 8
	s_bcnt1_i32_b64 s6, s[6:7]
	v_mov_b32_e32 v1, s8
	v_mov_b32_e32 v2, s6
	global_atomic_add v1, v2, s[18:19] offset:1024

;     __host__ __device__ bool next(int i, Unit& u) const { return at((long)i * G + c, u); }
; #define PG8_STAGE(bufoff, gbase, voff) do { _Pragma("unroll") for (int _i = 0; _i < 2; ++_i) \
;         __builtin_amdgcn_global_load_lds((const unsigned*)((const char*)(gbase) + (voff)[_i]), (PG8_LAS unsigned*)(lds + (bufoff) + ldsw + _i * 8192), 16, 0, 0); } while (0)
; #define PG8_LDA(dst, b, h) do { _Pragma("unroll") for (int m = 0; m < 4; ++m) _Pragma("unroll") for (int k = 0; k < 2; ++k) dst[m][k] = *(const PG8_LAS bf16x8*)(lds + PG8_SA(b, h) + aoff + m * 2048 + k * 1024); } while (0)
; #define PG8_LDB(dst, b, h) do { _Pragma("unroll") for (int n = 0; n < 2; ++n) _Pragma("unroll") for (int k = 0; k < 2; ++k) dst[n][k] = *(const PG8_LAS bf16x8*)(lds + PG8_SB(b, h) + boff + n * 2048 + k * 1024); } while (0)
; #define PG8_WAIT_V(n) asm volatile("s_waitcnt vmcnt(" #n ")" ::: "memory")
; #define PG8_BAR __builtin_amdgcn_s_barrier()
; template <class Epi, class Sched, bool ALIGN_EPI = false, bool SP2 = false>
; __device__ __forceinline__ void gemm_phase(PG8_LAS unsigned char* lds, const Gemm g, const Sched& S, const Epi& E) {
;     ...
;         const bool has_next = S.next(ui + 1, nxt);
;         const char* nA = has_next ? (const char*)g.A + (size_t)nxt.pm * tstep + (size_t)nxt.k0 * kstep : cA; const char* nB = has_next ? (const char*)g.Bt + (size_t)nxt.pn * tstep + (size_t)nxt.k0 * kstep : cB;
;         const int nt = cur.nt;
;         for (int t = 0; t < nt; t += 2) {
;             const bool last = (t == nt - 2);
;             const char* a1 = cA + (size_t)(t + 1) * kstep;
;             const char* a2 = last ? nA : cA + (size_t)(t + 2) * kstep; const char* b2 = last ? nB : cB + (size_t)(t + 2) * kstep;
;             const char* a3 = a2 + kstep; const char* b3 = b2 + kstep;
;             if (last && has_next) S.a_ready(nxt);
;             if constexpr (SP2) {
;             PG8_LDB(B0, 0, 0); PG8_LDB(B1, 0, 1); PG8_SCHED; PG8_LDA(At, 0, 0); PG8_STAGE(PG8_SA(1, 1), a1 + hstep, voffA);
;             PG8_WAIT_V(8); PG8_WAIT_L(0); PG8_BAR; PG8_MMA(0, 0, At, B0); PG8_MMA(0, 1, At, B1); PG8_BAR; PG8_SCHED;
;             PG8_LDA(At, 0, 1); PG8_STAGE(PG8_SB(0, 0), b2, voffB); PG8_STAGE(PG8_SB(0, 1), b2 + hstep, voffB); PG8_STAGE(PG8_SA(0, 0), a2, voffA);
;             PG8_WAIT_V(8); PG8_WAIT_L(0); PG8_BAR; PG8_MMA(1, 0, At, B0); PG8_MMA(1, 1, At, B1); PG8_BAR; PG8_SCHED;
.LBB0_123:
	s_ashr_i32 s55, s54, 31
	s_lshl_b64 s[16:17], s[54:55], 21
	s_add_u32 s58, s4, s16
	s_addc_u32 s59, s5, s17
	s_and_b64 s[16:17], s[56:57], exec
	s_cselect_b32 s30, s59, s29
	s_cselect_b32 s31, s58, s28
	s_ashr_i32 s53, s52, 31
	s_lshl_b64 s[16:17], s[52:53], 21
	s_add_u32 s60, s6, s16
	s_addc_u32 s61, s7, s17
	s_and_b64 s[16:17], s[56:57], exec
	s_cselect_b32 s53, s61, s27
	s_cselect_b32 s55, s60, s26
	s_add_u32 vcc_lo, s26, 0x100
	s_addc_u32 s16, s27, 0
	s_add_u32 s62, s28, 0x100080
	s_addc_u32 s63, s29, 0
	s_mov_b32 s17, -2
	s_waitcnt vmcnt(0)
	s_cmp_lg_u32 s32, 0
	s_cbranch_scc0 .Lrb_skip_0
	s_mov_b32 s32, 0
	s_barrier
.Lrb_skip_0:
	s_add_u32 s26, s62, 0xfff00080
	s_addc_u32 s27, s63, -1
	s_add_i32 s65, 0, 0x10000
	s_cmp_eq_u32 s17, 60
	s_cselect_b32 s29, s30, s27
	s_cselect_b32 s28, s31, s26
	v_add_u32_e32 v170, s65, v182
	s_cselect_b32 s27, s53, s16
	s_cselect_b32 s26, s55, vcc_lo
	s_add_i32 s70, 0, 0x14000
	ds_read_b128 v[122:125], v170
	ds_read_b128 v[126:129], v170 offset:1024
	ds_read_b128 v[130:133], v170 offset:2048
	ds_read_b128 v[172:175], v170 offset:3072
	v_add_u32_e32 v170, s70, v182
	ds_read_b128 v[176:179], v170
	ds_read_b128 v[192:195], v170 offset:1024
	ds_read_b128 v[196:199], v170 offset:2048
	ds_read_b128 v[200:203], v170 offset:3072
	v_lshl_add_u64 v[180:181], s[62:63], 0, v[156:157]
	s_add_i32 m0, s10, 0xc000
	ds_read_b128 v[204:207], v191
	ds_read_b128 v[220:223], v191 offset:1024
	ds_read_b128 v[224:227], v191 offset:2048
	ds_read_b128 v[228:231], v191 offset:3072
	ds_read_b128 v[232:235], v191 offset:4096
	ds_read_b128 v[236:239], v191 offset:5120
	ds_read_b128 v[240:243], v191 offset:6144
	ds_read_b128 v[244:247], v191 offset:7168
	global_load_lds_dwordx4 v[180:181], off
	v_lshl_add_u64 v[180:181], s[62:63], 0, v[154:155]
	s_add_i32 m0, s10, 0xe000
	s_nop 0
	global_load_lds_dwordx4 v[180:181], off
	s_waitcnt vmcnt(8)
	s_waitcnt lgkmcnt(0)
	s_setprio 1
	s_barrier
	v_mfma_f32_16x16x32_bf16 v[118:121], v[122:125], v[204:207], 0
	v_mfma_f32_16x16x32_bf16 v[138:141], v[130:133], v[204:207], 0
	v_mfma_f32_16x16x32_bf16 v[102:105], v[122:125], v[224:227], 0
	v_mfma_f32_16x16x32_bf16 v[114:117], v[130:133], v[224:227], 0
	v_mfma_f32_16x16x32_bf16 v[86:89], v[122:125], v[232:235], 0
	v_mfma_f32_16x16x32_bf16 v[98:101], v[130:133], v[232:235], 0
	v_mfma_f32_16x16x32_bf16 v[70:73], v[122:125], v[240:243], 0
	v_mfma_f32_16x16x32_bf16 v[82:85], v[130:133], v[240:243], 0
	v_mfma_f32_16x16x32_bf16 v[118:121], v[126:129], v[220:223], v[118:121]
	v_mfma_f32_16x16x32_bf16 v[138:141], v[172:175], v[220:223], v[138:141]
	v_mfma_f32_16x16x32_bf16 v[102:105], v[126:129], v[228:231], v[102:105]
	v_mfma_f32_16x16x32_bf16 v[114:117], v[172:175], v[228:231], v[114:117]
	v_mfma_f32_16x16x32_bf16 v[86:89], v[126:129], v[236:239], v[86:89]
	v_mfma_f32_16x16x32_bf16 v[98:101], v[172:175], v[236:239], v[98:101]
	v_mfma_f32_16x16x32_bf16 v[70:73], v[126:129], v[244:247], v[70:73]
	v_mfma_f32_16x16x32_bf16 v[82:85], v[172:175], v[244:247], v[82:85]
	v_mfma_f32_16x16x32_bf16 v[134:137], v[176:179], v[204:207], 0
	v_mfma_f32_16x16x32_bf16 v[110:113], v[196:199], v[204:207], 0
	v_mfma_f32_16x16x32_bf16 v[106:109], v[176:179], v[224:227], 0
	v_mfma_f32_16x16x32_bf16 v[94:97], v[196:199], v[224:227], 0
	v_mfma_f32_16x16x32_bf16 v[90:93], v[176:179], v[232:235], 0
	v_mfma_f32_16x16x32_bf16 v[78:81], v[196:199], v[232:235], 0
	v_mfma_f32_16x16x32_bf16 v[74:77], v[176:179], v[240:243], 0
	v_mfma_f32_16x16x32_bf16 v[66:69], v[196:199], v[240:243], 0
	v_mfma_f32_16x16x32_bf16 v[134:137], v[192:195], v[220:223], v[134:137]
	v_mfma_f32_16x16x32_bf16 v[110:113], v[200:203], v[220:223], v[110:113]
	v_mfma_f32_16x16x32_bf16 v[106:109], v[192:195], v[228:231], v[106:109]
	v_mfma_f32_16x16x32_bf16 v[94:97], v[200:203], v[228:231], v[94:97]
	v_mfma_f32_16x16x32_bf16 v[90:93], v[192:195], v[236:239], v[90:93]
	v_mfma_f32_16x16x32_bf16 v[78:81], v[200:203], v[236:239], v[78:81]
	v_mfma_f32_16x16x32_bf16 v[74:77], v[192:195], v[244:247], v[74:77]
	v_mfma_f32_16x16x32_bf16 v[66:69], v[200:203], v[244:247], v[66:69]
	s_barrier
	s_setprio 0
	s_add_i32 s65, s65, s9
	v_lshl_add_u64 v[180:181], s[26:27], 0, v[158:159]
	s_mov_b32 m0, s65
	ds_read_b128 v[204:207], v191 offset:16384
	ds_read_b128 v[220:223], v191 offset:17408
	ds_read_b128 v[224:227], v191 offset:18432
	ds_read_b128 v[228:231], v191 offset:19456
	ds_read_b128 v[232:235], v191 offset:20480
	ds_read_b128 v[236:239], v191 offset:21504
	ds_read_b128 v[240:243], v191 offset:22528
	ds_read_b128 v[244:247], v191 offset:23552
	global_load_lds_dwordx4 v[180:181], off
	s_add_i32 m0, s65, 0x2000
	s_add_u32 s68, s26, 0x100000
	v_lshl_add_u64 v[208:209], s[26:27], 0, v[142:143]
	s_addc_u32 s69, s27, 0
	s_add_i32 s65, s70, s9
	global_load_lds_dwordx4 v[208:209], off
	v_lshl_add_u64 v[248:249], s[68:69], 0, v[158:159]
	s_mov_b32 m0, s65
	v_lshl_add_u64 v[170:171], s[28:29], 0, v[144:145]
	global_load_lds_dwordx4 v[248:249], off
	v_lshl_add_u64 v[248:249], s[68:69], 0, v[142:143]
	s_add_i32 m0, s65, 0x2000
	s_nop 0
	global_load_lds_dwordx4 v[248:249], off
	v_lshl_add_u64 v[248:249], s[28:29], 0, v[146:147]
	s_mov_b32 m0, s10
	s_nop 0
	global_load_lds_dwordx4 v[248:249], off
	s_mov_b32 m0, s11
	s_nop 0
	global_load_lds_dwordx4 v[170:171], off
	s_waitcnt vmcnt(8)
	s_waitcnt lgkmcnt(0)
	s_setprio 1
	s_barrier
; #define PG8_STAGE(bufoff, gbase, voff) do { _Pragma("unroll") for (int _i = 0; _i < 2; ++_i) \
;         __builtin_amdgcn_global_load_lds((const unsigned*)((const char*)(gbase) + (voff)[_i]), (PG8_LAS unsigned*)(lds + (bufoff) + ldsw + _i * 8192), 16, 0, 0); } while (0)
; #define PG8_LDA(dst, b, h) do { _Pragma("unroll") for (int m = 0; m < 4; ++m) _Pragma("unroll") for (int k = 0; k < 2; ++k) dst[m][k] = *(const PG8_LAS bf16x8*)(lds + PG8_SA(b, h) + aoff + m * 2048 + k * 1024); } while (0)
; #define PG8_LDB(dst, b, h) do { _Pragma("unroll") for (int n = 0; n < 2; ++n) _Pragma("unroll") for (int k = 0; k < 2; ++k) dst[n][k] = *(const PG8_LAS bf16x8*)(lds + PG8_SB(b, h) + boff + n * 2048 + k * 1024); } while (0)
; #define PG8_MMA(ai, bj, At, Bt) do { __builtin_amdgcn_s_setprio(1); _Pragma("unroll") for (int m = 0; m < 4; ++m) _Pragma("unroll") for (int n = 0; n < 2; ++n) _Pragma("unroll") for (int k = 0; k < 2; ++k) \
;         acc[ai][bj][m][n] = __builtin_amdgcn_mfma_f32_16x16x32_bf16(Bt[n][k], At[m][k], acc[ai][bj][m][n], 0, 0, 0); __builtin_amdgcn_s_setprio(0); } while (0)
; #define PG8_WAIT_V(n) asm volatile("s_waitcnt vmcnt(" #n ")" ::: "memory")
; #define PG8_WAIT_L(n) asm volatile("s_waitcnt lgkmcnt(" #n ")" ::: "memory")
; #define PG8_BAR __builtin_amdgcn_s_barrier()
; #define PG8_SCHED __builtin_amdgcn_sched_barrier(0)
; template <class Epi, class Sched, bool ALIGN_EPI = false, bool SP2 = false>
; __device__ __forceinline__ void gemm_phase(PG8_LAS unsigned char* lds, const Gemm g, const Sched& S, const Epi& E) {
;     ...
;             PG8_WAIT_V(8); PG8_WAIT_L(0); PG8_BAR; PG8_MMA(0, 0, At, B0); PG8_MMA(0, 1, At, B1); PG8_BAR; PG8_SCHED;
;             PG8_LDA(At, 0, 1); PG8_STAGE(PG8_SB(0, 0), b2, voffB); PG8_STAGE(PG8_SB(0, 1), b2 + hstep, voffB); PG8_STAGE(PG8_SA(0, 0), a2, voffA);
;             PG8_WAIT_V(8); PG8_WAIT_L(0); PG8_BAR; PG8_MMA(1, 0, At, B0); PG8_MMA(1, 1, At, B1); PG8_BAR; PG8_SCHED;
;             PG8_LDB(B0, 1, 0); PG8_LDB(B1, 1, 1); PG8_SCHED; PG8_LDA(At, 1, 0); PG8_STAGE(PG8_SA(0, 1), a2 + hstep, voffA);
;             PG8_WAIT_V(8); PG8_WAIT_L(0); PG8_BAR; PG8_MMA(0, 0, At, B0); PG8_MMA(0, 1, At, B1); PG8_BAR; PG8_SCHED;
	v_mfma_f32_16x16x32_bf16 v[54:57], v[122:125], v[204:207], 0
	v_mfma_f32_16x16x32_bf16 v[62:65], v[130:133], v[204:207], 0
	v_mfma_f32_16x16x32_bf16 v[38:41], v[122:125], v[224:227], 0
	v_mfma_f32_16x16x32_bf16 v[50:53], v[130:133], v[224:227], 0
	v_mfma_f32_16x16x32_bf16 v[22:25], v[122:125], v[232:235], 0
	v_mfma_f32_16x16x32_bf16 v[34:37], v[130:133], v[232:235], 0
	v_mfma_f32_16x16x32_bf16 v[6:9], v[122:125], v[240:243], 0
	v_mfma_f32_16x16x32_bf16 v[18:21], v[130:133], v[240:243], 0
	v_mfma_f32_16x16x32_bf16 v[54:57], v[126:129], v[220:223], v[54:57]
	v_mfma_f32_16x16x32_bf16 v[62:65], v[172:175], v[220:223], v[62:65]
	v_mfma_f32_16x16x32_bf16 v[38:41], v[126:129], v[228:231], v[38:41]
	v_mfma_f32_16x16x32_bf16 v[50:53], v[172:175], v[228:231], v[50:53]
	v_mfma_f32_16x16x32_bf16 v[22:25], v[126:129], v[236:239], v[22:25]
	v_mfma_f32_16x16x32_bf16 v[34:37], v[172:175], v[236:239], v[34:37]
	v_mfma_f32_16x16x32_bf16 v[6:9], v[126:129], v[244:247], v[6:9]
	v_mfma_f32_16x16x32_bf16 v[18:21], v[172:175], v[244:247], v[18:21]
	v_mfma_f32_16x16x32_bf16 v[58:61], v[176:179], v[204:207], 0
	v_mfma_f32_16x16x32_bf16 v[46:49], v[196:199], v[204:207], 0
	v_mfma_f32_16x16x32_bf16 v[42:45], v[176:179], v[224:227], 0
	v_mfma_f32_16x16x32_bf16 v[30:33], v[196:199], v[224:227], 0
	v_mfma_f32_16x16x32_bf16 v[26:29], v[176:179], v[232:235], 0
	v_mfma_f32_16x16x32_bf16 v[14:17], v[196:199], v[232:235], 0
	v_mfma_f32_16x16x32_bf16 v[10:13], v[176:179], v[240:243], 0
	v_mfma_f32_16x16x32_bf16 v[2:5], v[196:199], v[240:243], 0
	v_mfma_f32_16x16x32_bf16 v[58:61], v[192:195], v[220:223], v[58:61]
	v_mfma_f32_16x16x32_bf16 v[46:49], v[200:203], v[220:223], v[46:49]
	v_mfma_f32_16x16x32_bf16 v[42:45], v[192:195], v[228:231], v[42:45]
	v_mfma_f32_16x16x32_bf16 v[30:33], v[200:203], v[228:231], v[30:33]
	v_mfma_f32_16x16x32_bf16 v[26:29], v[192:195], v[236:239], v[26:29]
	v_mfma_f32_16x16x32_bf16 v[14:17], v[200:203], v[236:239], v[14:17]
	v_mfma_f32_16x16x32_bf16 v[10:13], v[192:195], v[244:247], v[10:13]
	v_mfma_f32_16x16x32_bf16 v[2:5], v[200:203], v[244:247], v[2:5]
	s_barrier
	s_setprio 0
	s_add_i32 s65, 0, 0x18000
	s_add_i32 s68, 0, 0x1c000
	v_add_u32_e32 v172, s65, v182
	v_add_u32_e32 v200, s68, v182
	ds_read_b128 v[122:125], v172
	ds_read_b128 v[126:129], v172 offset:1024
	ds_read_b128 v[130:133], v172 offset:2048
	ds_read_b128 v[172:175], v172 offset:3072
	ds_read_b128 v[176:179], v200
	ds_read_b128 v[192:195], v200 offset:1024
	ds_read_b128 v[196:199], v200 offset:2048
	ds_read_b128 v[200:203], v200 offset:3072
	s_add_u32 s28, s28, 0x100000
	s_addc_u32 s29, s29, 0
	s_mov_b32 m0, s12
	v_lshl_add_u64 v[210:211], s[28:29], 0, v[146:147]
	ds_read_b128 v[204:207], v191 offset:32768
	ds_read_b128 v[220:223], v191 offset:33792
	ds_read_b128 v[224:227], v191 offset:34816
	ds_read_b128 v[228:231], v191 offset:35840
	ds_read_b128 v[232:235], v191 offset:36864
	ds_read_b128 v[236:239], v191 offset:37888
	ds_read_b128 v[240:243], v191 offset:38912
	ds_read_b128 v[244:247], v191 offset:39936
	global_load_lds_dwordx4 v[210:211], off
	v_lshl_add_u64 v[210:211], s[28:29], 0, v[144:145]
	s_mov_b32 m0, s13
	s_nop 0
	global_load_lds_dwordx4 v[210:211], off
	s_waitcnt vmcnt(8)
	s_waitcnt lgkmcnt(0)
	s_setprio 1
	s_barrier
	v_mfma_f32_16x16x32_bf16 v[118:121], v[122:125], v[204:207], v[118:121]
	v_mfma_f32_16x16x32_bf16 v[138:141], v[130:133], v[204:207], v[138:141]
	v_mfma_f32_16x16x32_bf16 v[102:105], v[122:125], v[224:227], v[102:105]
	v_mfma_f32_16x16x32_bf16 v[114:117], v[130:133], v[224:227], v[114:117]
	v_mfma_f32_16x16x32_bf16 v[86:89], v[122:125], v[232:235], v[86:89]
	v_mfma_f32_16x16x32_bf16 v[98:101], v[130:133], v[232:235], v[98:101]
	v_mfma_f32_16x16x32_bf16 v[70:73], v[122:125], v[240:243], v[70:73]
	v_mfma_f32_16x16x32_bf16 v[82:85], v[130:133], v[240:243], v[82:85]
	v_mfma_f32_16x16x32_bf16 v[118:121], v[126:129], v[220:223], v[118:121]
	v_mfma_f32_16x16x32_bf16 v[138:141], v[172:175], v[220:223], v[138:141]
	v_mfma_f32_16x16x32_bf16 v[102:105], v[126:129], v[228:231], v[102:105]
	v_mfma_f32_16x16x32_bf16 v[114:117], v[172:175], v[228:231], v[114:117]
	v_mfma_f32_16x16x32_bf16 v[86:89], v[126:129], v[236:239], v[86:89]
	v_mfma_f32_16x16x32_bf16 v[98:101], v[172:175], v[236:239], v[98:101]
	v_mfma_f32_16x16x32_bf16 v[70:73], v[126:129], v[244:247], v[70:73]
	v_mfma_f32_16x16x32_bf16 v[82:85], v[172:175], v[244:247], v[82:85]
	v_mfma_f32_16x16x32_bf16 v[134:137], v[176:179], v[204:207], v[134:137]
	v_mfma_f32_16x16x32_bf16 v[110:113], v[196:199], v[204:207], v[110:113]
	v_mfma_f32_16x16x32_bf16 v[106:109], v[176:179], v[224:227], v[106:109]
	v_mfma_f32_16x16x32_bf16 v[94:97], v[196:199], v[224:227], v[94:97]
	v_mfma_f32_16x16x32_bf16 v[90:93], v[176:179], v[232:235], v[90:93]
	v_mfma_f32_16x16x32_bf16 v[78:81], v[196:199], v[232:235], v[78:81]
	v_mfma_f32_16x16x32_bf16 v[74:77], v[176:179], v[240:243], v[74:77]
	v_mfma_f32_16x16x32_bf16 v[66:69], v[196:199], v[240:243], v[66:69]
	v_mfma_f32_16x16x32_bf16 v[134:137], v[192:195], v[220:223], v[134:137]
	v_mfma_f32_16x16x32_bf16 v[110:113], v[200:203], v[220:223], v[110:113]
	v_mfma_f32_16x16x32_bf16 v[106:109], v[192:195], v[228:231], v[106:109]
	v_mfma_f32_16x16x32_bf16 v[94:97], v[200:203], v[228:231], v[94:97]
	v_mfma_f32_16x16x32_bf16 v[90:93], v[192:195], v[236:239], v[90:93]
	v_mfma_f32_16x16x32_bf16 v[78:81], v[200:203], v[236:239], v[78:81]
	v_mfma_f32_16x16x32_bf16 v[74:77], v[192:195], v[244:247], v[74:77]
	v_mfma_f32_16x16x32_bf16 v[66:69], v[200:203], v[244:247], v[66:69]
	s_barrier
; #define PG8_STAGE(bufoff, gbase, voff) do { _Pragma("unroll") for (int _i = 0; _i < 2; ++_i) \
;         __builtin_amdgcn_global_load_lds((const unsigned*)((const char*)(gbase) + (voff)[_i]), (PG8_LAS unsigned*)(lds + (bufoff) + ldsw + _i * 8192), 16, 0, 0); } while (0)
; #define PG8_LDA(dst, b, h) do { _Pragma("unroll") for (int m = 0; m < 4; ++m) _Pragma("unroll") for (int k = 0; k < 2; ++k) dst[m][k] = *(const PG8_LAS bf16x8*)(lds + PG8_SA(b, h) + aoff + m * 2048 + k * 1024); } while (0)
; #define PG8_MMA(ai, bj, At, Bt) do { __builtin_amdgcn_s_setprio(1); _Pragma("unroll") for (int m = 0; m < 4; ++m) _Pragma("unroll") for (int n = 0; n < 2; ++n) _Pragma("unroll") for (int k = 0; k < 2; ++k) \
;         acc[ai][bj][m][n] = __builtin_amdgcn_mfma_f32_16x16x32_bf16(Bt[n][k], At[m][k], acc[ai][bj][m][n], 0, 0, 0); __builtin_amdgcn_s_setprio(0); } while (0)
; #define PG8_WAIT_V(n) asm volatile("s_waitcnt vmcnt(" #n ")" ::: "memory")
; #define PG8_WAIT_L(n) asm volatile("s_waitcnt lgkmcnt(" #n ")" ::: "memory")
; #define PG8_BAR __builtin_amdgcn_s_barrier()
; #define PG8_SCHED __builtin_amdgcn_sched_barrier(0)
; template <class Epi, class Sched, bool ALIGN_EPI = false, bool SP2 = false>
; __device__ __forceinline__ void gemm_phase(PG8_LAS unsigned char* lds, const Gemm g, const Sched& S, const Epi& E) {
;     ...
;             PG8_WAIT_V(8); PG8_WAIT_L(0); PG8_BAR; PG8_MMA(0, 0, At, B0); PG8_MMA(0, 1, At, B1); PG8_BAR; PG8_SCHED;
;             PG8_LDA(At, 1, 1); PG8_STAGE(PG8_SB(1, 0), b3, voffB); PG8_STAGE(PG8_SB(1, 1), b3 + hstep, voffB); PG8_STAGE(PG8_SA(1, 0), a3, voffA);
;             PG8_WAIT_V(8); PG8_WAIT_L(0); PG8_BAR; PG8_MMA(1, 0, At, B0); PG8_MMA(1, 1, At, B1); PG8_BAR; PG8_SCHED;
	s_setprio 0
	s_add_i32 s28, s65, s9
	v_lshl_add_u64 v[180:181], v[180:181], 0, s[96:97]
	s_mov_b32 m0, s28
	ds_read_b128 v[204:207], v191 offset:49152
	ds_read_b128 v[220:223], v191 offset:50176
	ds_read_b128 v[224:227], v191 offset:51200
	ds_read_b128 v[228:231], v191 offset:52224
	ds_read_b128 v[232:235], v191 offset:53248
	ds_read_b128 v[236:239], v191 offset:54272
	ds_read_b128 v[240:243], v191 offset:55296
	ds_read_b128 v[244:247], v191 offset:56320
	global_load_lds_dwordx4 v[180:181], off
	s_add_i32 m0, s28, 0x2000
	s_add_u32 s26, s26, 0x100080
	v_lshl_add_u64 v[180:181], v[208:209], 0, s[96:97]
	s_addc_u32 s27, s27, 0
	s_add_i32 s28, s68, s9
	global_load_lds_dwordx4 v[180:181], off
	v_lshl_add_u64 v[180:181], s[26:27], 0, v[158:159]
	s_mov_b32 m0, s28
	v_lshl_add_u64 v[170:171], v[170:171], 0, s[96:97]
	global_load_lds_dwordx4 v[180:181], off
	v_lshl_add_u64 v[180:181], s[26:27], 0, v[142:143]
	s_add_i32 m0, s28, 0x2000
	s_nop 0
	global_load_lds_dwordx4 v[180:181], off
	v_lshl_add_u64 v[180:181], v[248:249], 0, s[96:97]
	s_mov_b32 m0, s0
	s_nop 0
	global_load_lds_dwordx4 v[180:181], off
	s_mov_b32 m0, s34
	s_nop 0
	global_load_lds_dwordx4 v[170:171], off
	s_waitcnt vmcnt(8)
	s_waitcnt lgkmcnt(0)
	s_setprio 1
	s_barrier
	v_mfma_f32_16x16x32_bf16 v[54:57], v[122:125], v[204:207], v[54:57]
	v_mfma_f32_16x16x32_bf16 v[62:65], v[130:133], v[204:207], v[62:65]
	v_mfma_f32_16x16x32_bf16 v[38:41], v[122:125], v[224:227], v[38:41]
	v_mfma_f32_16x16x32_bf16 v[50:53], v[130:133], v[224:227], v[50:53]
	v_mfma_f32_16x16x32_bf16 v[22:25], v[122:125], v[232:235], v[22:25]
	v_mfma_f32_16x16x32_bf16 v[34:37], v[130:133], v[232:235], v[34:37]
	v_mfma_f32_16x16x32_bf16 v[6:9], v[122:125], v[240:243], v[6:9]
	v_mfma_f32_16x16x32_bf16 v[18:21], v[130:133], v[240:243], v[18:21]
	v_mfma_f32_16x16x32_bf16 v[54:57], v[126:129], v[220:223], v[54:57]
	v_mfma_f32_16x16x32_bf16 v[62:65], v[172:175], v[220:223], v[62:65]
	v_mfma_f32_16x16x32_bf16 v[38:41], v[126:129], v[228:231], v[38:41]
	v_mfma_f32_16x16x32_bf16 v[50:53], v[172:175], v[228:231], v[50:53]
	v_mfma_f32_16x16x32_bf16 v[22:25], v[126:129], v[236:239], v[22:25]
	v_mfma_f32_16x16x32_bf16 v[34:37], v[172:175], v[236:239], v[34:37]
	v_mfma_f32_16x16x32_bf16 v[6:9], v[126:129], v[244:247], v[6:9]
	v_mfma_f32_16x16x32_bf16 v[18:21], v[172:175], v[244:247], v[18:21]
	v_mfma_f32_16x16x32_bf16 v[58:61], v[176:179], v[204:207], v[58:61]
	v_mfma_f32_16x16x32_bf16 v[46:49], v[196:199], v[204:207], v[46:49]
	v_mfma_f32_16x16x32_bf16 v[42:45], v[176:179], v[224:227], v[42:45]
	v_mfma_f32_16x16x32_bf16 v[30:33], v[196:199], v[224:227], v[30:33]
	v_mfma_f32_16x16x32_bf16 v[26:29], v[176:179], v[232:235], v[26:29]
	v_mfma_f32_16x16x32_bf16 v[14:17], v[196:199], v[232:235], v[14:17]
	v_mfma_f32_16x16x32_bf16 v[10:13], v[176:179], v[240:243], v[10:13]
	v_mfma_f32_16x16x32_bf16 v[2:5], v[196:199], v[240:243], v[2:5]
	v_mfma_f32_16x16x32_bf16 v[58:61], v[192:195], v[220:223], v[58:61]
	v_mfma_f32_16x16x32_bf16 v[46:49], v[200:203], v[220:223], v[46:49]
	v_mfma_f32_16x16x32_bf16 v[42:45], v[192:195], v[228:231], v[42:45]
	v_mfma_f32_16x16x32_bf16 v[30:33], v[200:203], v[228:231], v[30:33]
	v_mfma_f32_16x16x32_bf16 v[26:29], v[192:195], v[236:239], v[26:29]
	v_mfma_f32_16x16x32_bf16 v[14:17], v[200:203], v[236:239], v[14:17]
	v_mfma_f32_16x16x32_bf16 v[10:13], v[192:195], v[244:247], v[10:13]
	v_mfma_f32_16x16x32_bf16 v[2:5], v[200:203], v[244:247], v[2:5]
	s_barrier
	s_setprio 0
	s_add_i32 s17, s17, 2
	s_add_u32 vcc_lo, vcc_lo, 0x100
	s_addc_u32 s16, s16, 0
	s_add_u32 s62, s62, 0x100
	s_addc_u32 s63, s63, 0
	s_cmp_gt_u32 s17, 61
	s_cbranch_scc1 .Lpeel_exit_0

; __device__ __forceinline__ unsigned cvt_pk_bf16(float lo, float hi) { unsigned r; asm volatile("v_cvt_pk_bf16_f32 %0, %1, %2" : "=v"(r) : "v"(lo), "v"(hi)); return r; }
; #define PG8_BAR __builtin_amdgcn_s_barrier()
;     __device__ __forceinline__ void operator()(const f32x4 (&acc)[2][2][4][2], const Unit& u, int wr, int wc, int fr, int fq) const {
;     ...
;                 { const f32x4 uu = acc[ai][1][m][1]; u32x2 w; w.x = cvt_pk_bf16(uu[0], uu[1]); w.y = cvt_pk_bf16(uu[2], uu[3]); *(u32x2*)(U + row * ldu + ch0) = w; }
;                 zp = z;
; template <class Epi, class Sched, bool ALIGN_EPI = false, bool SP2 = false>
; __device__ __forceinline__ void gemm_phase(PG8_LAS unsigned char* lds, const Gemm g, const Sched& S, const Epi& E) {
;     ...
;         if (!has_next) break;
; #pragma unroll
;         for (int a = 0; a < 2; ++a)
; #pragma unroll
;             for (int b = 0; b < 2; ++b)
; #pragma unroll
;                 for (int m = 0; m < 4; ++m)
; #pragma unroll
;                     for (int n = 0; n < 2; ++n) acc[a][b][m][n] = (f32x4){0.f, 0.f, 0.f, 0.f};
;         cur = nxt; cA = nA; cB = nB; ++ui;
;         if constexpr (ALIGN_EPI) { if (wr == 1) PG8_BAR; }
.LBB0_139:
	s_or_b64 exec, exec, s[28:29]
	v_cvt_pk_bf16_f32 v2, v2, v3
	v_cvt_pk_bf16_f32 v3, v4, v5
	v_lshlrev_b64 v[4:5], 12, v[14:15]
	v_lshl_add_u64 v[4:5], s[22:23], 0, v[4:5]
	v_lshl_add_u64 v[4:5], v[172:173], 1, v[4:5]
	s_andn2_b64 vcc, exec, s[56:57]
	s_mov_b64 s[26:27], -1
	flat_store_dwordx2 v[4:5], v[2:3]
	s_cbranch_vccnz .LBB0_113
	s_andn2_b64 vcc, exec, s[20:21]
	s_cbranch_vccnz .LBB0_112
	s_mov_b32 s32, 1
	s_branch .LBB0_112

;     __host__ __device__ bool next(int i, Unit& u) const { return at((long)i * G + c, u); }
; #define PG8_STAGE(bufoff, gbase, voff) do { _Pragma("unroll") for (int _i = 0; _i < 2; ++_i) \
;         __builtin_amdgcn_global_load_lds((const unsigned*)((const char*)(gbase) + (voff)[_i]), (PG8_LAS unsigned*)(lds + (bufoff) + ldsw + _i * 8192), 16, 0, 0); } while (0)
; #define PG8_LDA(dst, b, h) do { _Pragma("unroll") for (int m = 0; m < 4; ++m) _Pragma("unroll") for (int k = 0; k < 2; ++k) dst[m][k] = *(const PG8_LAS bf16x8*)(lds + PG8_SA(b, h) + aoff + m * 2048 + k * 1024); } while (0)
; #define PG8_LDB(dst, b, h) do { _Pragma("unroll") for (int n = 0; n < 2; ++n) _Pragma("unroll") for (int k = 0; k < 2; ++k) dst[n][k] = *(const PG8_LAS bf16x8*)(lds + PG8_SB(b, h) + boff + n * 2048 + k * 1024); } while (0)
; #define PG8_WAIT_V(n) asm volatile("s_waitcnt vmcnt(" #n ")" ::: "memory")
; #define PG8_BAR __builtin_amdgcn_s_barrier()
; template <class Epi, class Sched, bool ALIGN_EPI = false, bool SP2 = false>
; __device__ __forceinline__ void gemm_phase(PG8_LAS unsigned char* lds, const Gemm g, const Sched& S, const Epi& E) {
;     ...
;         const bool has_next = S.next(ui + 1, nxt);
;         const char* nA = has_next ? (const char*)g.A + (size_t)nxt.pm * tstep + (size_t)nxt.k0 * kstep : cA; const char* nB = has_next ? (const char*)g.Bt + (size_t)nxt.pn * tstep + (size_t)nxt.k0 * kstep : cB;
;         const int nt = cur.nt;
;         for (int t = 0; t < nt; t += 2) {
;             const bool last = (t == nt - 2);
;             const char* a1 = cA + (size_t)(t + 1) * kstep;
;             const char* a2 = last ? nA : cA + (size_t)(t + 2) * kstep; const char* b2 = last ? nB : cB + (size_t)(t + 2) * kstep;
;             const char* a3 = a2 + kstep; const char* b3 = b2 + kstep;
;             if (last && has_next) S.a_ready(nxt);
;             if constexpr (SP2) {
;             PG8_LDB(B0, 0, 0); PG8_LDB(B1, 0, 1); PG8_SCHED; PG8_LDA(At, 0, 0); PG8_STAGE(PG8_SA(1, 1), a1 + hstep, voffA);
;             PG8_WAIT_V(8); PG8_WAIT_L(0); PG8_BAR; PG8_MMA(0, 0, At, B0); PG8_MMA(0, 1, At, B1); PG8_BAR; PG8_SCHED;
;             PG8_LDA(At, 0, 1); PG8_STAGE(PG8_SB(0, 0), b2, voffB); PG8_STAGE(PG8_SB(0, 1), b2 + hstep, voffB); PG8_STAGE(PG8_SA(0, 0), a2, voffA);
;             PG8_WAIT_V(8); PG8_WAIT_L(0); PG8_BAR; PG8_MMA(1, 0, At, B0); PG8_MMA(1, 1, At, B1); PG8_BAR; PG8_SCHED;
.LBB0_418:
	s_ashr_i32 s41, s40, 31
	s_lshl_b64 s[16:17], s[40:41], 20
	s_add_u32 s44, s20, s16
	s_addc_u32 s45, s21, s17
	s_and_b64 s[16:17], s[42:43], exec
	s_cselect_b32 s15, s45, s29
	s_cselect_b32 s30, s44, s28
	s_ashr_i32 s39, s38, 31
	s_lshl_b64 s[16:17], s[38:39], 20
	s_add_u32 s46, s0, s16
	s_addc_u32 s47, s4, s17
	s_and_b64 s[16:17], s[42:43], exec
	s_cselect_b32 s31, s47, s27
	s_cselect_b32 s34, s46, s26
	s_add_u32 s35, s26, 0x100
	s_addc_u32 s16, s27, 0
	s_add_u32 s48, s28, 0x80080
	s_addc_u32 s49, s29, 0
	s_mov_b32 s17, -2
	s_waitcnt vmcnt(0)
	s_waitcnt vmcnt(0)
	s_cmp_lg_u32 s32, 0
	s_cbranch_scc0 .Lrb_skip_1
	s_mov_b32 s32, 0
	s_barrier
.Lrb_skip_1:
	s_add_u32 s26, s48, 0xfff80080
	s_addc_u32 s27, s49, -1
	s_add_i32 s39, 0, 0x10000
	s_cmp_eq_u32 s17, 28
	s_cselect_b32 s29, s15, s27
	s_cselect_b32 s28, s30, s26
	s_cselect_b32 s27, s31, s16
	s_cselect_b32 s26, s34, s35
	s_add_i32 s41, 0, 0x14000
	v_add_u32_e32 v142, s39, v190
	v_add_u32_e32 v170, s41, v190
	ds_read_b128 v[130:133], v142
	ds_read_b128 v[134:137], v142 offset:1024
	ds_read_b128 v[138:141], v142 offset:2048
	ds_read_b128 v[142:145], v142 offset:3072
	ds_read_b128 v[146:149], v170
	ds_read_b128 v[150:153], v170 offset:1024
	ds_read_b128 v[178:181], v170 offset:2048
	ds_read_b128 v[182:185], v170 offset:3072
	v_lshl_add_u64 v[170:171], s[48:49], 0, v[176:177]
	s_add_i32 m0, s6, 0xc000
	ds_read_b128 v[186:189], v192
	ds_read_b128 v[194:197], v192 offset:1024
	ds_read_b128 v[198:201], v192 offset:2048
	ds_read_b128 v[202:205], v192 offset:3072
	ds_read_b128 v[206:209], v192 offset:4096
	ds_read_b128 v[220:223], v192 offset:5120
	ds_read_b128 v[224:227], v192 offset:6144
	ds_read_b128 v[228:231], v192 offset:7168
	global_load_lds_dwordx4 v[170:171], off
	v_lshl_add_u64 v[170:171], s[48:49], 0, v[174:175]
	s_add_i32 m0, s6, 0xe000
	s_nop 0
	global_load_lds_dwordx4 v[170:171], off
	s_waitcnt vmcnt(8)
	s_waitcnt lgkmcnt(0)
	s_setprio 1
	s_barrier
	v_mfma_f32_16x16x32_bf16 v[126:129], v[130:133], v[186:189], 0
	v_mfma_f32_16x16x32_bf16 v[122:125], v[138:141], v[186:189], 0
	v_mfma_f32_16x16x32_bf16 v[110:113], v[130:133], v[198:201], 0
	v_mfma_f32_16x16x32_bf16 v[106:109], v[138:141], v[198:201], 0
	v_mfma_f32_16x16x32_bf16 v[94:97], v[130:133], v[206:209], 0
	v_mfma_f32_16x16x32_bf16 v[90:93], v[138:141], v[206:209], 0
	v_mfma_f32_16x16x32_bf16 v[78:81], v[130:133], v[224:227], 0
	v_mfma_f32_16x16x32_bf16 v[74:77], v[138:141], v[224:227], 0
	v_mfma_f32_16x16x32_bf16 v[126:129], v[134:137], v[194:197], v[126:129]
	v_mfma_f32_16x16x32_bf16 v[122:125], v[142:145], v[194:197], v[122:125]
	v_mfma_f32_16x16x32_bf16 v[110:113], v[134:137], v[202:205], v[110:113]
	v_mfma_f32_16x16x32_bf16 v[106:109], v[142:145], v[202:205], v[106:109]
	v_mfma_f32_16x16x32_bf16 v[94:97], v[134:137], v[220:223], v[94:97]
	v_mfma_f32_16x16x32_bf16 v[90:93], v[142:145], v[220:223], v[90:93]
	v_mfma_f32_16x16x32_bf16 v[78:81], v[134:137], v[228:231], v[78:81]
	v_mfma_f32_16x16x32_bf16 v[74:77], v[142:145], v[228:231], v[74:77]
	v_mfma_f32_16x16x32_bf16 v[118:121], v[146:149], v[186:189], 0
	v_mfma_f32_16x16x32_bf16 v[114:117], v[178:181], v[186:189], 0
	v_mfma_f32_16x16x32_bf16 v[102:105], v[146:149], v[198:201], 0
	v_mfma_f32_16x16x32_bf16 v[98:101], v[178:181], v[198:201], 0
	v_mfma_f32_16x16x32_bf16 v[86:89], v[146:149], v[206:209], 0
	v_mfma_f32_16x16x32_bf16 v[82:85], v[178:181], v[206:209], 0
	v_mfma_f32_16x16x32_bf16 v[70:73], v[146:149], v[224:227], 0
	v_mfma_f32_16x16x32_bf16 v[66:69], v[178:181], v[224:227], 0
	v_mfma_f32_16x16x32_bf16 v[118:121], v[150:153], v[194:197], v[118:121]
	v_mfma_f32_16x16x32_bf16 v[114:117], v[182:185], v[194:197], v[114:117]
	v_mfma_f32_16x16x32_bf16 v[102:105], v[150:153], v[202:205], v[102:105]
	v_mfma_f32_16x16x32_bf16 v[98:101], v[182:185], v[202:205], v[98:101]
	v_mfma_f32_16x16x32_bf16 v[86:89], v[150:153], v[220:223], v[86:89]
	v_mfma_f32_16x16x32_bf16 v[82:85], v[182:185], v[220:223], v[82:85]
	v_mfma_f32_16x16x32_bf16 v[70:73], v[150:153], v[228:231], v[70:73]
	v_mfma_f32_16x16x32_bf16 v[66:69], v[182:185], v[228:231], v[66:69]
	s_barrier
	s_setprio 0
	s_add_i32 s39, s39, s5
	v_lshl_add_u64 v[170:171], s[26:27], 0, v[158:159]
	s_mov_b32 m0, s39
	ds_read_b128 v[186:189], v192 offset:16384
	ds_read_b128 v[194:197], v192 offset:17408
	ds_read_b128 v[198:201], v192 offset:18432
	ds_read_b128 v[202:205], v192 offset:19456
	ds_read_b128 v[206:209], v192 offset:20480
	ds_read_b128 v[220:223], v192 offset:21504
	ds_read_b128 v[224:227], v192 offset:22528
	ds_read_b128 v[228:231], v192 offset:23552
	global_load_lds_dwordx4 v[170:171], off
	s_add_i32 m0, s39, 0x2000
	s_add_u32 s50, s26, 0x80000
	v_lshl_add_u64 v[210:211], s[26:27], 0, v[154:155]
	s_addc_u32 s51, s27, 0
	s_add_i32 s39, s41, s5
	global_load_lds_dwordx4 v[210:211], off
	v_lshl_add_u64 v[232:233], s[50:51], 0, v[158:159]
	s_mov_b32 m0, s39
	v_lshl_add_u64 v[234:235], s[28:29], 0, v[156:157]
	global_load_lds_dwordx4 v[232:233], off
	v_lshl_add_u64 v[232:233], s[50:51], 0, v[154:155]
	s_add_i32 m0, s39, 0x2000
	s_nop 0
	global_load_lds_dwordx4 v[232:233], off
	v_lshl_add_u64 v[232:233], s[28:29], 0, v[172:173]
	s_mov_b32 m0, s6
	s_nop 0
	global_load_lds_dwordx4 v[232:233], off
	s_mov_b32 m0, s7
	s_nop 0
	global_load_lds_dwordx4 v[234:235], off
	s_waitcnt vmcnt(8)
	s_waitcnt lgkmcnt(0)
	s_setprio 1
	s_barrier
; #define PG8_STAGE(bufoff, gbase, voff) do { _Pragma("unroll") for (int _i = 0; _i < 2; ++_i) \
;         __builtin_amdgcn_global_load_lds((const unsigned*)((const char*)(gbase) + (voff)[_i]), (PG8_LAS unsigned*)(lds + (bufoff) + ldsw + _i * 8192), 16, 0, 0); } while (0)
; #define PG8_LDA(dst, b, h) do { _Pragma("unroll") for (int m = 0; m < 4; ++m) _Pragma("unroll") for (int k = 0; k < 2; ++k) dst[m][k] = *(const PG8_LAS bf16x8*)(lds + PG8_SA(b, h) + aoff + m * 2048 + k * 1024); } while (0)
; #define PG8_LDB(dst, b, h) do { _Pragma("unroll") for (int n = 0; n < 2; ++n) _Pragma("unroll") for (int k = 0; k < 2; ++k) dst[n][k] = *(const PG8_LAS bf16x8*)(lds + PG8_SB(b, h) + boff + n * 2048 + k * 1024); } while (0)
; #define PG8_MMA(ai, bj, At, Bt) do { __builtin_amdgcn_s_setprio(1); _Pragma("unroll") for (int m = 0; m < 4; ++m) _Pragma("unroll") for (int n = 0; n < 2; ++n) _Pragma("unroll") for (int k = 0; k < 2; ++k) \
;         acc[ai][bj][m][n] = __builtin_amdgcn_mfma_f32_16x16x32_bf16(Bt[n][k], At[m][k], acc[ai][bj][m][n], 0, 0, 0); __builtin_amdgcn_s_setprio(0); } while (0)
; #define PG8_WAIT_V(n) asm volatile("s_waitcnt vmcnt(" #n ")" ::: "memory")
; #define PG8_WAIT_L(n) asm volatile("s_waitcnt lgkmcnt(" #n ")" ::: "memory")
; #define PG8_BAR __builtin_amdgcn_s_barrier()
; #define PG8_SCHED __builtin_amdgcn_sched_barrier(0)
; template <class Epi, class Sched, bool ALIGN_EPI = false, bool SP2 = false>
; __device__ __forceinline__ void gemm_phase(PG8_LAS unsigned char* lds, const Gemm g, const Sched& S, const Epi& E) {
;     ...
;             PG8_WAIT_V(8); PG8_WAIT_L(0); PG8_BAR; PG8_MMA(0, 0, At, B0); PG8_MMA(0, 1, At, B1); PG8_BAR; PG8_SCHED;
;             PG8_LDA(At, 0, 1); PG8_STAGE(PG8_SB(0, 0), b2, voffB); PG8_STAGE(PG8_SB(0, 1), b2 + hstep, voffB); PG8_STAGE(PG8_SA(0, 0), a2, voffA);
;             PG8_WAIT_V(8); PG8_WAIT_L(0); PG8_BAR; PG8_MMA(1, 0, At, B0); PG8_MMA(1, 1, At, B1); PG8_BAR; PG8_SCHED;
;             PG8_LDB(B0, 1, 0); PG8_LDB(B1, 1, 1); PG8_SCHED; PG8_LDA(At, 1, 0); PG8_STAGE(PG8_SA(0, 1), a2 + hstep, voffA);
;             PG8_WAIT_V(8); PG8_WAIT_L(0); PG8_BAR; PG8_MMA(0, 0, At, B0); PG8_MMA(0, 1, At, B1); PG8_BAR; PG8_SCHED;
	v_mfma_f32_16x16x32_bf16 v[62:65], v[130:133], v[186:189], 0
	v_mfma_f32_16x16x32_bf16 v[58:61], v[138:141], v[186:189], 0
	v_mfma_f32_16x16x32_bf16 v[46:49], v[130:133], v[198:201], 0
	v_mfma_f32_16x16x32_bf16 v[42:45], v[138:141], v[198:201], 0
	v_mfma_f32_16x16x32_bf16 v[30:33], v[130:133], v[206:209], 0
	v_mfma_f32_16x16x32_bf16 v[26:29], v[138:141], v[206:209], 0
	v_mfma_f32_16x16x32_bf16 v[14:17], v[130:133], v[224:227], 0
	v_mfma_f32_16x16x32_bf16 v[10:13], v[138:141], v[224:227], 0
	v_mfma_f32_16x16x32_bf16 v[62:65], v[134:137], v[194:197], v[62:65]
	v_mfma_f32_16x16x32_bf16 v[58:61], v[142:145], v[194:197], v[58:61]
	v_mfma_f32_16x16x32_bf16 v[46:49], v[134:137], v[202:205], v[46:49]
	v_mfma_f32_16x16x32_bf16 v[42:45], v[142:145], v[202:205], v[42:45]
	v_mfma_f32_16x16x32_bf16 v[30:33], v[134:137], v[220:223], v[30:33]
	v_mfma_f32_16x16x32_bf16 v[26:29], v[142:145], v[220:223], v[26:29]
	v_mfma_f32_16x16x32_bf16 v[14:17], v[134:137], v[228:231], v[14:17]
	v_mfma_f32_16x16x32_bf16 v[10:13], v[142:145], v[228:231], v[10:13]
	v_mfma_f32_16x16x32_bf16 v[54:57], v[146:149], v[186:189], 0
	v_mfma_f32_16x16x32_bf16 v[50:53], v[178:181], v[186:189], 0
	v_mfma_f32_16x16x32_bf16 v[38:41], v[146:149], v[198:201], 0
	v_mfma_f32_16x16x32_bf16 v[34:37], v[178:181], v[198:201], 0
	v_mfma_f32_16x16x32_bf16 v[22:25], v[146:149], v[206:209], 0
	v_mfma_f32_16x16x32_bf16 v[18:21], v[178:181], v[206:209], 0
	v_mfma_f32_16x16x32_bf16 v[6:9], v[146:149], v[224:227], 0
	v_mfma_f32_16x16x32_bf16 v[2:5], v[178:181], v[224:227], 0
	v_mfma_f32_16x16x32_bf16 v[54:57], v[150:153], v[194:197], v[54:57]
	v_mfma_f32_16x16x32_bf16 v[50:53], v[182:185], v[194:197], v[50:53]
	v_mfma_f32_16x16x32_bf16 v[38:41], v[150:153], v[202:205], v[38:41]
	v_mfma_f32_16x16x32_bf16 v[34:37], v[182:185], v[202:205], v[34:37]
	v_mfma_f32_16x16x32_bf16 v[22:25], v[150:153], v[220:223], v[22:25]
	v_mfma_f32_16x16x32_bf16 v[18:21], v[182:185], v[220:223], v[18:21]
	v_mfma_f32_16x16x32_bf16 v[6:9], v[150:153], v[228:231], v[6:9]
	v_mfma_f32_16x16x32_bf16 v[2:5], v[182:185], v[228:231], v[2:5]
	s_barrier
	s_setprio 0
	s_add_i32 s39, 0, 0x18000
	s_add_i32 s41, 0, 0x1c000
	v_add_u32_e32 v142, s39, v190
	v_add_u32_e32 v182, s41, v190
	ds_read_b128 v[130:133], v142
	ds_read_b128 v[134:137], v142 offset:1024
	ds_read_b128 v[138:141], v142 offset:2048
	ds_read_b128 v[142:145], v142 offset:3072
	ds_read_b128 v[146:149], v182
	ds_read_b128 v[150:153], v182 offset:1024
	ds_read_b128 v[178:181], v182 offset:2048
	ds_read_b128 v[182:185], v182 offset:3072
	s_add_u32 s28, s28, 0x80000
	s_addc_u32 s29, s29, 0
	s_mov_b32 m0, s8
	v_lshl_add_u64 v[236:237], s[28:29], 0, v[172:173]
	ds_read_b128 v[186:189], v192 offset:32768
	ds_read_b128 v[194:197], v192 offset:33792
	ds_read_b128 v[198:201], v192 offset:34816
	ds_read_b128 v[202:205], v192 offset:35840
	ds_read_b128 v[206:209], v192 offset:36864
	ds_read_b128 v[220:223], v192 offset:37888
	ds_read_b128 v[224:227], v192 offset:38912
	ds_read_b128 v[228:231], v192 offset:39936
	global_load_lds_dwordx4 v[236:237], off
	v_lshl_add_u64 v[236:237], s[28:29], 0, v[156:157]
	s_mov_b32 m0, s9
	s_nop 0
	global_load_lds_dwordx4 v[236:237], off
	s_waitcnt vmcnt(8)
	s_waitcnt lgkmcnt(0)
	s_setprio 1
	s_barrier
	v_mfma_f32_16x16x32_bf16 v[126:129], v[130:133], v[186:189], v[126:129]
	v_mfma_f32_16x16x32_bf16 v[122:125], v[138:141], v[186:189], v[122:125]
	v_mfma_f32_16x16x32_bf16 v[110:113], v[130:133], v[198:201], v[110:113]
	v_mfma_f32_16x16x32_bf16 v[106:109], v[138:141], v[198:201], v[106:109]
	v_mfma_f32_16x16x32_bf16 v[94:97], v[130:133], v[206:209], v[94:97]
	v_mfma_f32_16x16x32_bf16 v[90:93], v[138:141], v[206:209], v[90:93]
	v_mfma_f32_16x16x32_bf16 v[78:81], v[130:133], v[224:227], v[78:81]
	v_mfma_f32_16x16x32_bf16 v[74:77], v[138:141], v[224:227], v[74:77]
	v_mfma_f32_16x16x32_bf16 v[126:129], v[134:137], v[194:197], v[126:129]
	v_mfma_f32_16x16x32_bf16 v[122:125], v[142:145], v[194:197], v[122:125]
	v_mfma_f32_16x16x32_bf16 v[110:113], v[134:137], v[202:205], v[110:113]
	v_mfma_f32_16x16x32_bf16 v[106:109], v[142:145], v[202:205], v[106:109]
	v_mfma_f32_16x16x32_bf16 v[94:97], v[134:137], v[220:223], v[94:97]
	v_mfma_f32_16x16x32_bf16 v[90:93], v[142:145], v[220:223], v[90:93]
	v_mfma_f32_16x16x32_bf16 v[78:81], v[134:137], v[228:231], v[78:81]
	v_mfma_f32_16x16x32_bf16 v[74:77], v[142:145], v[228:231], v[74:77]
	v_mfma_f32_16x16x32_bf16 v[118:121], v[146:149], v[186:189], v[118:121]
	v_mfma_f32_16x16x32_bf16 v[114:117], v[178:181], v[186:189], v[114:117]
	v_mfma_f32_16x16x32_bf16 v[102:105], v[146:149], v[198:201], v[102:105]
	v_mfma_f32_16x16x32_bf16 v[98:101], v[178:181], v[198:201], v[98:101]
	v_mfma_f32_16x16x32_bf16 v[86:89], v[146:149], v[206:209], v[86:89]
	v_mfma_f32_16x16x32_bf16 v[82:85], v[178:181], v[206:209], v[82:85]
	v_mfma_f32_16x16x32_bf16 v[70:73], v[146:149], v[224:227], v[70:73]
	v_mfma_f32_16x16x32_bf16 v[66:69], v[178:181], v[224:227], v[66:69]
	v_mfma_f32_16x16x32_bf16 v[118:121], v[150:153], v[194:197], v[118:121]
	v_mfma_f32_16x16x32_bf16 v[114:117], v[182:185], v[194:197], v[114:117]
	v_mfma_f32_16x16x32_bf16 v[102:105], v[150:153], v[202:205], v[102:105]
	v_mfma_f32_16x16x32_bf16 v[98:101], v[182:185], v[202:205], v[98:101]
	v_mfma_f32_16x16x32_bf16 v[86:89], v[150:153], v[220:223], v[86:89]
	v_mfma_f32_16x16x32_bf16 v[82:85], v[182:185], v[220:223], v[82:85]
	v_mfma_f32_16x16x32_bf16 v[70:73], v[150:153], v[228:231], v[70:73]
	v_mfma_f32_16x16x32_bf16 v[66:69], v[182:185], v[228:231], v[66:69]
	s_barrier
; #define PG8_STAGE(bufoff, gbase, voff) do { _Pragma("unroll") for (int _i = 0; _i < 2; ++_i) \
;         __builtin_amdgcn_global_load_lds((const unsigned*)((const char*)(gbase) + (voff)[_i]), (PG8_LAS unsigned*)(lds + (bufoff) + ldsw + _i * 8192), 16, 0, 0); } while (0)
; #define PG8_LDA(dst, b, h) do { _Pragma("unroll") for (int m = 0; m < 4; ++m) _Pragma("unroll") for (int k = 0; k < 2; ++k) dst[m][k] = *(const PG8_LAS bf16x8*)(lds + PG8_SA(b, h) + aoff + m * 2048 + k * 1024); } while (0)
; #define PG8_MMA(ai, bj, At, Bt) do { __builtin_amdgcn_s_setprio(1); _Pragma("unroll") for (int m = 0; m < 4; ++m) _Pragma("unroll") for (int n = 0; n < 2; ++n) _Pragma("unroll") for (int k = 0; k < 2; ++k) \
;         acc[ai][bj][m][n] = __builtin_amdgcn_mfma_f32_16x16x32_bf16(Bt[n][k], At[m][k], acc[ai][bj][m][n], 0, 0, 0); __builtin_amdgcn_s_setprio(0); } while (0)
; #define PG8_WAIT_V(n) asm volatile("s_waitcnt vmcnt(" #n ")" ::: "memory")
; #define PG8_WAIT_L(n) asm volatile("s_waitcnt lgkmcnt(" #n ")" ::: "memory")
; #define PG8_BAR __builtin_amdgcn_s_barrier()
; #define PG8_SCHED __builtin_amdgcn_sched_barrier(0)
; template <class Epi, class Sched, bool ALIGN_EPI = false, bool SP2 = false>
; __device__ __forceinline__ void gemm_phase(PG8_LAS unsigned char* lds, const Gemm g, const Sched& S, const Epi& E) {
;     ...
;             PG8_WAIT_V(8); PG8_WAIT_L(0); PG8_BAR; PG8_MMA(0, 0, At, B0); PG8_MMA(0, 1, At, B1); PG8_BAR; PG8_SCHED;
;             PG8_LDA(At, 1, 1); PG8_STAGE(PG8_SB(1, 0), b3, voffB); PG8_STAGE(PG8_SB(1, 1), b3 + hstep, voffB); PG8_STAGE(PG8_SA(1, 0), a3, voffA);
;             PG8_WAIT_V(8); PG8_WAIT_L(0); PG8_BAR; PG8_MMA(1, 0, At, B0); PG8_MMA(1, 1, At, B1); PG8_BAR; PG8_SCHED;
	s_setprio 0
	s_add_i32 s28, s39, s5
	v_lshl_add_u64 v[170:171], v[170:171], 0, s[96:97]
	s_mov_b32 m0, s28
	ds_read_b128 v[186:189], v192 offset:49152
	ds_read_b128 v[194:197], v192 offset:50176
	ds_read_b128 v[198:201], v192 offset:51200
	ds_read_b128 v[202:205], v192 offset:52224
	ds_read_b128 v[206:209], v192 offset:53248
	ds_read_b128 v[220:223], v192 offset:54272
	ds_read_b128 v[224:227], v192 offset:55296
	ds_read_b128 v[228:231], v192 offset:56320
	global_load_lds_dwordx4 v[170:171], off
	s_add_i32 m0, s28, 0x2000
	s_add_u32 s26, s26, 0x80080
	v_lshl_add_u64 v[170:171], v[210:211], 0, s[96:97]
	s_addc_u32 s27, s27, 0
	s_add_i32 s28, s41, s5
	global_load_lds_dwordx4 v[170:171], off
	v_lshl_add_u64 v[170:171], s[26:27], 0, v[158:159]
	s_mov_b32 m0, s28
	s_nop 0
	global_load_lds_dwordx4 v[170:171], off
	v_lshl_add_u64 v[170:171], s[26:27], 0, v[154:155]
	s_add_i32 m0, s28, 0x2000
	s_nop 0
	global_load_lds_dwordx4 v[170:171], off
	v_lshl_add_u64 v[170:171], v[232:233], 0, s[96:97]
	s_mov_b32 m0, s10
	s_nop 0
	global_load_lds_dwordx4 v[170:171], off
	v_lshl_add_u64 v[170:171], v[234:235], 0, s[96:97]
	s_mov_b32 m0, s11
	s_nop 0
	global_load_lds_dwordx4 v[170:171], off
	s_waitcnt vmcnt(8)
	s_waitcnt lgkmcnt(0)
	s_setprio 1
	s_barrier
	v_mfma_f32_16x16x32_bf16 v[62:65], v[130:133], v[186:189], v[62:65]
	v_mfma_f32_16x16x32_bf16 v[58:61], v[138:141], v[186:189], v[58:61]
	v_mfma_f32_16x16x32_bf16 v[46:49], v[130:133], v[198:201], v[46:49]
	v_mfma_f32_16x16x32_bf16 v[42:45], v[138:141], v[198:201], v[42:45]
	v_mfma_f32_16x16x32_bf16 v[30:33], v[130:133], v[206:209], v[30:33]
	v_mfma_f32_16x16x32_bf16 v[26:29], v[138:141], v[206:209], v[26:29]
	v_mfma_f32_16x16x32_bf16 v[14:17], v[130:133], v[224:227], v[14:17]
	v_mfma_f32_16x16x32_bf16 v[10:13], v[138:141], v[224:227], v[10:13]
	v_mfma_f32_16x16x32_bf16 v[62:65], v[134:137], v[194:197], v[62:65]
	v_mfma_f32_16x16x32_bf16 v[58:61], v[142:145], v[194:197], v[58:61]
	v_mfma_f32_16x16x32_bf16 v[46:49], v[134:137], v[202:205], v[46:49]
	v_mfma_f32_16x16x32_bf16 v[42:45], v[142:145], v[202:205], v[42:45]
	v_mfma_f32_16x16x32_bf16 v[30:33], v[134:137], v[220:223], v[30:33]
	v_mfma_f32_16x16x32_bf16 v[26:29], v[142:145], v[220:223], v[26:29]
	v_mfma_f32_16x16x32_bf16 v[14:17], v[134:137], v[228:231], v[14:17]
	v_mfma_f32_16x16x32_bf16 v[10:13], v[142:145], v[228:231], v[10:13]
	v_mfma_f32_16x16x32_bf16 v[54:57], v[146:149], v[186:189], v[54:57]
	v_mfma_f32_16x16x32_bf16 v[50:53], v[178:181], v[186:189], v[50:53]
	v_mfma_f32_16x16x32_bf16 v[38:41], v[146:149], v[198:201], v[38:41]
	v_mfma_f32_16x16x32_bf16 v[34:37], v[178:181], v[198:201], v[34:37]
	v_mfma_f32_16x16x32_bf16 v[22:25], v[146:149], v[206:209], v[22:25]
	v_mfma_f32_16x16x32_bf16 v[18:21], v[178:181], v[206:209], v[18:21]
	v_mfma_f32_16x16x32_bf16 v[6:9], v[146:149], v[224:227], v[6:9]
	v_mfma_f32_16x16x32_bf16 v[2:5], v[178:181], v[224:227], v[2:5]
	v_mfma_f32_16x16x32_bf16 v[54:57], v[150:153], v[194:197], v[54:57]
	v_mfma_f32_16x16x32_bf16 v[50:53], v[182:185], v[194:197], v[50:53]
	v_mfma_f32_16x16x32_bf16 v[38:41], v[150:153], v[202:205], v[38:41]
	v_mfma_f32_16x16x32_bf16 v[34:37], v[182:185], v[202:205], v[34:37]
	v_mfma_f32_16x16x32_bf16 v[22:25], v[150:153], v[220:223], v[22:25]
	v_mfma_f32_16x16x32_bf16 v[18:21], v[182:185], v[220:223], v[18:21]
	v_mfma_f32_16x16x32_bf16 v[6:9], v[150:153], v[228:231], v[6:9]
	v_mfma_f32_16x16x32_bf16 v[2:5], v[182:185], v[228:231], v[2:5]
	s_barrier
	s_setprio 0
	s_add_i32 s17, s17, 2
	s_add_u32 s35, s35, 0x100
	s_addc_u32 s16, s16, 0
	s_add_u32 s48, s48, 0x100
	s_addc_u32 s49, s49, 0
	s_cmp_gt_u32 s17, 29
	s_cbranch_scc1 .Lpeel_exit_1

; __device__ __forceinline__ unsigned cvt_pk_bf16(float lo, float hi) { unsigned r; asm volatile("v_cvt_pk_bf16_f32 %0, %1, %2" : "=v"(r) : "v"(lo), "v"(hi)); return r; }
; __device__ __forceinline__ float bflo(unsigned w) { return __uint_as_float(w << 16); }
; __device__ __forceinline__ float bfhi(unsigned w) { return __uint_as_float(w & 0xffff0000u); }
; __device__ __forceinline__ float sigmoidf_(float x) { return __builtin_amdgcn_rcpf(1.0f + __expf(-x)); }
;     __device__ __forceinline__ void operator()(const f32x4 (&acc)[2][2][4][2], const Unit& u, int wr, int wc, int fr, int fq) const {
;         const int row0 = u.pm * BM + wr * 64 + fr; const int col0 = u.pn * BM + wc * 32 + 8 * fq;
; #pragma unroll
;         for (int ai = 0; ai < 2; ++ai) {
;             u32x4 gv[4][2];
; #pragma unroll
;             for (int m = 0; m < 4; ++m)
; #pragma unroll
;                 for (int bj = 0; bj < 2; ++bj) gv[m][bj] = *(const u32x4*)(Gb + (size_t)(row0 + ai * HALF + m * 16) * ldg + col0 + bj * HALF);
;             asm volatile("" : "+v"(gv[0][0]), "+v"(gv[0][1]), "+v"(gv[1][0]), "+v"(gv[1][1]), "+v"(gv[2][0]), "+v"(gv[2][1]), "+v"(gv[3][0]), "+v"(gv[3][1]));
; #pragma unroll
;             for (int m = 0; m < 4; ++m) { const size_t row = (size_t)(row0 + ai * HALF + m * 16);
; #pragma unroll
;                 for (int bj = 0; bj < 2; ++bj) { const f32x4 v0 = acc[ai][bj][m][0], v1 = acc[ai][bj][m][1];
;                     const u32x4 gq = gv[m][bj];
;                     u32x4 w;
;                     w.x = cvt_pk_bf16(bflo(gq.x) * sigmoidf_(v0[0]), bfhi(gq.x) * sigmoidf_(v0[1]));
;                     w.y = cvt_pk_bf16(bflo(gq.y) * sigmoidf_(v0[2]), bfhi(gq.y) * sigmoidf_(v0[3]));
;                     w.z = cvt_pk_bf16(bflo(gq.z) * sigmoidf_(v1[0]), bfhi(gq.z) * sigmoidf_(v1[1]));
;                     w.w = cvt_pk_bf16(bflo(gq.w) * sigmoidf_(v1[2]), bfhi(gq.w) * sigmoidf_(v1[3]));
;                     *(u32x4*)(O + row * ldc + ocol0 + col0 + bj * HALF) = w; } }
.LBB0_422:
	v_lshl_or_b32 v130, s13, 8, v191
	v_lshl_add_u32 v180, s14, 8, v161
	v_ashrrev_i32_e32 v131, 31, v130
	v_lshlrev_b64 v[178:179], 1, v[130:131]
	v_ashrrev_i32_e32 v181, 31, v180
	v_lshl_add_u64 v[182:183], s[20:21], 0, v[178:179]
	v_lshlrev_b64 v[130:131], 12, v[180:181]
	v_or_b32_e32 v188, 16, v180
	v_lshl_add_u64 v[130:131], v[182:183], 0, v[130:131]
	v_ashrrev_i32_e32 v189, 31, v188
	flat_load_dwordx4 v[194:197], v[130:131]
	flat_load_dwordx4 v[198:201], v[130:131] offset:256
	v_lshlrev_b64 v[130:131], 12, v[188:189]
	v_or_b32_e32 v186, 32, v180
	v_lshl_add_u64 v[130:131], v[182:183], 0, v[130:131]
	v_ashrrev_i32_e32 v187, 31, v186
	flat_load_dwordx4 v[150:153], v[130:131]
	flat_load_dwordx4 v[146:149], v[130:131] offset:256
	v_lshlrev_b64 v[130:131], 12, v[186:187]
	v_or_b32_e32 v184, 48, v180
	v_lshl_add_u64 v[130:131], v[182:183], 0, v[130:131]
	v_ashrrev_i32_e32 v185, 31, v184
	flat_load_dwordx4 v[142:145], v[130:131]
	flat_load_dwordx4 v[138:141], v[130:131] offset:256
	v_lshlrev_b64 v[130:131], 12, v[184:185]
	v_lshl_add_u64 v[130:131], v[182:183], 0, v[130:131]
	flat_load_dwordx4 v[134:137], v[130:131]
	s_nop 0
	flat_load_dwordx4 v[130:133], v[130:131] offset:256
	v_mul_f32_e32 v126, 0xbfb8aa3b, v126
	v_mul_f32_e32 v127, 0xbfb8aa3b, v127
	v_mul_f32_e32 v128, 0xbfb8aa3b, v128
	v_mul_f32_e32 v125, 0xbfb8aa3b, v125
	v_exp_f32_e32 v126, v126
	v_mul_f32_e32 v129, 0xbfb8aa3b, v129
	v_mul_f32_e32 v122, 0xbfb8aa3b, v122
	v_mul_f32_e32 v123, 0xbfb8aa3b, v123
	v_mul_f32_e32 v124, 0xbfb8aa3b, v124
	v_exp_f32_e32 v127, v127
	v_exp_f32_e32 v128, v128
	v_exp_f32_e32 v125, v125
	v_exp_f32_e32 v129, v129
	v_exp_f32_e32 v170, v122
	v_exp_f32_e32 v171, v123
	v_exp_f32_e32 v124, v124
	v_lshlrev_b64 v[122:123], 13, v[180:181]
	v_mul_f32_e32 v118, 0xbfb8aa3b, v118
	v_lshl_add_u64 v[122:123], s[24:25], 0, v[122:123]
	v_exp_f32_e32 v118, v118
	v_mul_f32_e32 v119, 0xbfb8aa3b, v119
	v_lshl_add_u64 v[122:123], v[122:123], 0, v[178:179]
	v_add_f32_e32 v181, 1.0, v126
	v_exp_f32_e32 v119, v119
	v_add_f32_e32 v193, 1.0, v127
	v_add_f32_e32 v202, 1.0, v128
	v_add_f32_e32 v125, 1.0, v125
	v_lshl_add_u64 v[126:127], v[122:123], 0, s[88:89]
	v_add_co_u32_e32 v128, vcc, s93, v122
	v_rcp_f32_e32 v122, v181
	v_add_f32_e32 v203, 1.0, v129
	v_add_f32_e32 v170, 1.0, v170
	v_add_f32_e32 v171, 1.0, v171
	v_add_f32_e32 v124, 1.0, v124
	v_addc_co_u32_e32 v129, vcc, 0, v123, vcc
	v_rcp_f32_e32 v123, v193
	v_rcp_f32_e32 v125, v125
	v_rcp_f32_e32 v181, v202
	v_rcp_f32_e32 v193, v203
	v_rcp_f32_e32 v170, v170
	v_rcp_f32_e32 v171, v171
	v_rcp_f32_e32 v124, v124
	v_add_f32_e32 v118, 1.0, v118
	v_rcp_f32_e32 v118, v118
	v_add_f32_e32 v119, 1.0, v119
	v_rcp_f32_e32 v119, v119
	v_mul_f32_e32 v120, 0xbfb8aa3b, v120
	v_exp_f32_e32 v120, v120
	v_mul_f32_e32 v121, 0xbfb8aa3b, v121
	v_exp_f32_e32 v121, v121
	v_mul_f32_e32 v114, 0xbfb8aa3b, v114
	v_exp_f32_e32 v114, v114
	v_mul_f32_e32 v115, 0xbfb8aa3b, v115
	v_exp_f32_e32 v115, v115
	v_mul_f32_e32 v116, 0xbfb8aa3b, v116
	v_add_f32_e32 v114, 1.0, v114
	v_rcp_f32_e32 v114, v114
	v_add_f32_e32 v115, 1.0, v115
	v_rcp_f32_e32 v115, v115
	v_exp_f32_e32 v116, v116
	v_mul_f32_e32 v117, 0xbfb8aa3b, v117
	v_exp_f32_e32 v117, v117
	v_mul_f32_e32 v110, 0xbfb8aa3b, v110
	v_exp_f32_e32 v110, v110
	v_mul_f32_e32 v111, 0xbfb8aa3b, v111
	s_waitcnt vmcnt(0) lgkmcnt(0)
	s_nop 0
	v_lshlrev_b32_e32 v202, 16, v194
	v_and_b32_e32 v194, 0xffff0000, v194
	v_lshlrev_b32_e32 v205, 16, v197
	v_and_b32_e32 v197, 0xffff0000, v197
	v_mul_f32_e32 v122, v122, v202
	v_lshlrev_b32_e32 v203, 16, v195
	v_and_b32_e32 v195, 0xffff0000, v195
	v_lshlrev_b32_e32 v204, 16, v196
	v_and_b32_e32 v196, 0xffff0000, v196
	v_mul_f32_e32 v123, v123, v194
	v_mul_f32_e32 v125, v125, v197
	v_cvt_pk_bf16_f32 v122, v122, v123
	v_mul_f32_e32 v181, v181, v203
	v_mul_f32_e32 v193, v193, v195
	v_mul_f32_e32 v170, v170, v204
	v_mul_f32_e32 v171, v171, v196
	v_mul_f32_e32 v194, v124, v205
	v_cvt_pk_bf16_f32 v123, v181, v193
	v_cvt_pk_bf16_f32 v124, v170, v171
	v_cvt_pk_bf16_f32 v125, v194, v125
	flat_store_dwordx4 v[128:129], v[122:125]
	v_exp_f32_e32 v111, v111
	v_add_f32_e32 v110, 1.0, v110
	v_lshlrev_b32_e32 v122, 16, v198
	v_mul_f32_e32 v118, v118, v122
	v_and_b32_e32 v122, 0xffff0000, v198
	v_mul_f32_e32 v119, v119, v122
	v_cvt_pk_bf16_f32 v118, v118, v119
	v_add_f32_e32 v119, 1.0, v120
	v_rcp_f32_e32 v119, v119
	v_add_f32_e32 v120, 1.0, v121
	v_rcp_f32_e32 v120, v120
	v_lshlrev_b32_e32 v121, 16, v199
	v_mul_f32_e32 v119, v119, v121
	v_and_b32_e32 v121, 0xffff0000, v199
	v_mul_f32_e32 v120, v120, v121
	v_cvt_pk_bf16_f32 v119, v119, v120
	v_lshlrev_b32_e32 v120, 16, v200
	v_mul_f32_e32 v114, v114, v120
	v_and_b32_e32 v120, 0xffff0000, v200
	v_mul_f32_e32 v115, v115, v120
	v_cvt_pk_bf16_f32 v120, v114, v115
	v_add_f32_e32 v114, 1.0, v116
	v_rcp_f32_e32 v114, v114
	v_add_f32_e32 v115, 1.0, v117
	v_rcp_f32_e32 v115, v115
	v_rcp_f32_e32 v110, v110
	v_add_f32_e32 v111, 1.0, v111
	v_lshlrev_b32_e32 v116, 16, v201
	v_rcp_f32_e32 v111, v111
	v_mul_f32_e32 v112, 0xbfb8aa3b, v112
	v_mul_f32_e32 v114, v114, v116
	v_and_b32_e32 v116, 0xffff0000, v201
	v_exp_f32_e32 v112, v112
	v_mul_f32_e32 v113, 0xbfb8aa3b, v113
	v_mul_f32_e32 v115, v115, v116
	v_cvt_pk_bf16_f32 v121, v114, v115
	v_lshlrev_b32_e32 v114, 16, v150
	v_exp_f32_e32 v113, v113
	v_mul_f32_e32 v110, v110, v114
	v_and_b32_e32 v114, 0xffff0000, v150
	v_mul_f32_e32 v106, 0xbfb8aa3b, v106
	v_mul_f32_e32 v111, v111, v114
	v_exp_f32_e32 v106, v106
	v_mul_f32_e32 v107, 0xbfb8aa3b, v107
	flat_store_dwordx4 v[126:127], v[118:121] offset:256
	v_cvt_pk_bf16_f32 v110, v110, v111
	v_add_f32_e32 v111, 1.0, v112
	v_exp_f32_e32 v107, v107
; __device__ __forceinline__ unsigned cvt_pk_bf16(float lo, float hi) { unsigned r; asm volatile("v_cvt_pk_bf16_f32 %0, %1, %2" : "=v"(r) : "v"(lo), "v"(hi)); return r; }
; __device__ __forceinline__ float bflo(unsigned w) { return __uint_as_float(w << 16); }
; __device__ __forceinline__ float bfhi(unsigned w) { return __uint_as_float(w & 0xffff0000u); }
; __device__ __forceinline__ float sigmoidf_(float x) { return __builtin_amdgcn_rcpf(1.0f + __expf(-x)); }
;     __device__ __forceinline__ void operator()(const f32x4 (&acc)[2][2][4][2], const Unit& u, int wr, int wc, int fr, int fq) const {
;     ...
;             for (int m = 0; m < 4; ++m) { const size_t row = (size_t)(row0 + ai * HALF + m * 16);
; #pragma unroll
;                 for (int bj = 0; bj < 2; ++bj) { const f32x4 v0 = acc[ai][bj][m][0], v1 = acc[ai][bj][m][1];
;                     const u32x4 gq = gv[m][bj];
;                     u32x4 w;
;                     w.x = cvt_pk_bf16(bflo(gq.x) * sigmoidf_(v0[0]), bfhi(gq.x) * sigmoidf_(v0[1]));
;                     w.y = cvt_pk_bf16(bflo(gq.y) * sigmoidf_(v0[2]), bfhi(gq.y) * sigmoidf_(v0[3]));
;                     w.z = cvt_pk_bf16(bflo(gq.z) * sigmoidf_(v1[0]), bfhi(gq.z) * sigmoidf_(v1[1]));
;                     w.w = cvt_pk_bf16(bflo(gq.w) * sigmoidf_(v1[2]), bfhi(gq.w) * sigmoidf_(v1[3]));
;                     *(u32x4*)(O + row * ldc + ocol0 + col0 + bj * HALF) = w; } }
	v_rcp_f32_e32 v111, v111
	v_add_f32_e32 v112, 1.0, v113
	v_rcp_f32_e32 v112, v112
	v_add_f32_e32 v106, 1.0, v106
	v_lshlrev_b32_e32 v113, 16, v151
	v_rcp_f32_e32 v106, v106
	v_add_f32_e32 v107, 1.0, v107
	v_mul_f32_e32 v108, 0xbfb8aa3b, v108
	v_mul_f32_e32 v111, v111, v113
	v_and_b32_e32 v113, 0xffff0000, v151
	v_rcp_f32_e32 v107, v107
	v_exp_f32_e32 v108, v108
	v_mul_f32_e32 v109, 0xbfb8aa3b, v109
	v_mul_f32_e32 v112, v112, v113
	v_exp_f32_e32 v109, v109
	v_cvt_pk_bf16_f32 v111, v111, v112
	v_lshlrev_b32_e32 v112, 16, v152
	v_mul_f32_e32 v106, v106, v112
	v_and_b32_e32 v112, 0xffff0000, v152
	v_mul_f32_e32 v107, v107, v112
	v_cvt_pk_bf16_f32 v112, v106, v107
	v_add_f32_e32 v106, 1.0, v108
	v_rcp_f32_e32 v106, v106
	v_add_f32_e32 v107, 1.0, v109
	v_rcp_f32_e32 v107, v107
	v_mul_f32_e32 v102, 0xbfb8aa3b, v102
	v_lshlrev_b32_e32 v108, 16, v153
	v_exp_f32_e32 v102, v102
	v_mul_f32_e32 v103, 0xbfb8aa3b, v103
	v_mul_f32_e32 v106, v106, v108
	v_and_b32_e32 v108, 0xffff0000, v153
	v_exp_f32_e32 v103, v103
	v_mul_f32_e32 v107, v107, v108
	v_cvt_pk_bf16_f32 v113, v106, v107
	v_lshlrev_b64 v[106:107], 13, v[188:189]
	v_lshl_add_u64 v[106:107], s[24:25], 0, v[106:107]
	v_add_f32_e32 v102, 1.0, v102
	v_lshl_add_u64 v[106:107], v[106:107], 0, v[178:179]
	v_rcp_f32_e32 v102, v102
	v_add_f32_e32 v103, 1.0, v103
	v_lshl_add_u64 v[108:109], v[106:107], 0, s[88:89]
	v_add_co_u32_e32 v106, vcc, s93, v106
	v_rcp_f32_e32 v103, v103
	v_mul_f32_e32 v104, 0xbfb8aa3b, v104
	v_addc_co_u32_e32 v107, vcc, 0, v107, vcc
	v_exp_f32_e32 v104, v104
	v_mul_f32_e32 v105, 0xbfb8aa3b, v105
	flat_store_dwordx4 v[106:107], v[110:113]
	v_lshlrev_b32_e32 v106, 16, v146
	v_exp_f32_e32 v105, v105
	v_mul_f32_e32 v102, v102, v106
	v_and_b32_e32 v106, 0xffff0000, v146
	v_mul_f32_e32 v98, 0xbfb8aa3b, v98
	v_mul_f32_e32 v103, v103, v106
	v_exp_f32_e32 v98, v98
	v_mul_f32_e32 v99, 0xbfb8aa3b, v99
	v_cvt_pk_bf16_f32 v102, v102, v103
	v_add_f32_e32 v103, 1.0, v104
	v_exp_f32_e32 v99, v99
	v_rcp_f32_e32 v103, v103
	v_add_f32_e32 v104, 1.0, v105
	v_rcp_f32_e32 v104, v104
	v_add_f32_e32 v98, 1.0, v98
	v_lshlrev_b32_e32 v105, 16, v147
	v_rcp_f32_e32 v98, v98
	v_add_f32_e32 v99, 1.0, v99
	v_mul_f32_e32 v100, 0xbfb8aa3b, v100
	v_mul_f32_e32 v103, v103, v105
	v_and_b32_e32 v105, 0xffff0000, v147
	v_rcp_f32_e32 v99, v99
	v_exp_f32_e32 v100, v100
	v_mul_f32_e32 v101, 0xbfb8aa3b, v101
	v_mul_f32_e32 v104, v104, v105
	v_exp_f32_e32 v101, v101
	v_mul_f32_e32 v94, 0xbfb8aa3b, v94
	v_cvt_pk_bf16_f32 v103, v103, v104
	v_lshlrev_b32_e32 v104, 16, v148
	v_exp_f32_e32 v94, v94
	v_mul_f32_e32 v95, 0xbfb8aa3b, v95
	v_mul_f32_e32 v98, v98, v104
	v_and_b32_e32 v104, 0xffff0000, v148
	v_exp_f32_e32 v95, v95
	v_mul_f32_e32 v99, v99, v104
	v_cvt_pk_bf16_f32 v104, v98, v99
	v_add_f32_e32 v98, 1.0, v100
	v_rcp_f32_e32 v98, v98
	v_add_f32_e32 v99, 1.0, v101
	v_rcp_f32_e32 v99, v99
	v_add_f32_e32 v94, 1.0, v94
	v_rcp_f32_e32 v94, v94
	v_add_f32_e32 v95, 1.0, v95
	v_lshlrev_b32_e32 v100, 16, v149
	v_rcp_f32_e32 v95, v95
	v_mul_f32_e32 v96, 0xbfb8aa3b, v96
	v_mul_f32_e32 v98, v98, v100
	v_and_b32_e32 v100, 0xffff0000, v149
	v_exp_f32_e32 v96, v96
	v_mul_f32_e32 v97, 0xbfb8aa3b, v97
	v_mul_f32_e32 v99, v99, v100
	v_cvt_pk_bf16_f32 v105, v98, v99
	v_lshlrev_b32_e32 v98, 16, v142
	v_exp_f32_e32 v97, v97
	v_mul_f32_e32 v94, v94, v98
	v_and_b32_e32 v98, 0xffff0000, v142
	v_mul_f32_e32 v90, 0xbfb8aa3b, v90
	v_mul_f32_e32 v95, v95, v98
	v_exp_f32_e32 v90, v90
	v_mul_f32_e32 v91, 0xbfb8aa3b, v91
	flat_store_dwordx4 v[108:109], v[102:105] offset:256
	v_cvt_pk_bf16_f32 v94, v94, v95
	v_add_f32_e32 v95, 1.0, v96
	v_exp_f32_e32 v91, v91
	v_rcp_f32_e32 v95, v95
	v_add_f32_e32 v96, 1.0, v97
	v_rcp_f32_e32 v96, v96
	v_add_f32_e32 v90, 1.0, v90
	v_lshlrev_b32_e32 v97, 16, v143
	v_rcp_f32_e32 v90, v90
	v_add_f32_e32 v91, 1.0, v91
	v_mul_f32_e32 v92, 0xbfb8aa3b, v92
	v_mul_f32_e32 v95, v95, v97
	v_and_b32_e32 v97, 0xffff0000, v143
	v_rcp_f32_e32 v91, v91
	v_exp_f32_e32 v92, v92
	v_mul_f32_e32 v93, 0xbfb8aa3b, v93
	v_mul_f32_e32 v96, v96, v97
	v_exp_f32_e32 v93, v93
	v_cvt_pk_bf16_f32 v95, v95, v96
	v_lshlrev_b32_e32 v96, 16, v144
	v_mul_f32_e32 v90, v90, v96
	v_and_b32_e32 v96, 0xffff0000, v144
	v_mul_f32_e32 v91, v91, v96
	v_cvt_pk_bf16_f32 v96, v90, v91
	v_add_f32_e32 v90, 1.0, v92
	v_rcp_f32_e32 v90, v90
	v_add_f32_e32 v91, 1.0, v93
	v_rcp_f32_e32 v91, v91
	v_mul_f32_e32 v86, 0xbfb8aa3b, v86
	v_lshlrev_b32_e32 v92, 16, v145
	v_exp_f32_e32 v86, v86
	v_mul_f32_e32 v87, 0xbfb8aa3b, v87
	v_mul_f32_e32 v90, v90, v92
	v_and_b32_e32 v92, 0xffff0000, v145
	v_exp_f32_e32 v87, v87
	v_mul_f32_e32 v91, v91, v92
	v_cvt_pk_bf16_f32 v97, v90, v91
	v_lshlrev_b64 v[90:91], 13, v[186:187]
	v_lshl_add_u64 v[90:91], s[24:25], 0, v[90:91]
	v_add_f32_e32 v86, 1.0, v86
	v_lshl_add_u64 v[90:91], v[90:91], 0, v[178:179]
	v_rcp_f32_e32 v86, v86
	v_add_f32_e32 v87, 1.0, v87
	v_lshl_add_u64 v[92:93], v[90:91], 0, s[88:89]
	v_add_co_u32_e32 v90, vcc, s93, v90
	v_rcp_f32_e32 v87, v87
	v_mul_f32_e32 v88, 0xbfb8aa3b, v88
	v_addc_co_u32_e32 v91, vcc, 0, v91, vcc
	v_exp_f32_e32 v88, v88
	v_mul_f32_e32 v89, 0xbfb8aa3b, v89
	flat_store_dwordx4 v[90:91], v[94:97]
	v_lshlrev_b32_e32 v90, 16, v138
	v_exp_f32_e32 v89, v89
	v_mul_f32_e32 v86, v86, v90
	v_and_b32_e32 v90, 0xffff0000, v138
	v_mul_f32_e32 v82, 0xbfb8aa3b, v82
	v_mul_f32_e32 v87, v87, v90
	v_exp_f32_e32 v82, v82
	v_mul_f32_e32 v83, 0xbfb8aa3b, v83
	v_cvt_pk_bf16_f32 v86, v86, v87
	v_add_f32_e32 v87, 1.0, v88
	v_exp_f32_e32 v83, v83
	v_rcp_f32_e32 v87, v87
	v_add_f32_e32 v88, 1.0, v89
	v_rcp_f32_e32 v88, v88
	v_add_f32_e32 v82, 1.0, v82
	v_lshlrev_b32_e32 v89, 16, v139
	v_rcp_f32_e32 v82, v82
; __device__ __forceinline__ unsigned cvt_pk_bf16(float lo, float hi) { unsigned r; asm volatile("v_cvt_pk_bf16_f32 %0, %1, %2" : "=v"(r) : "v"(lo), "v"(hi)); return r; }
; __device__ __forceinline__ float bflo(unsigned w) { return __uint_as_float(w << 16); }
; __device__ __forceinline__ float bfhi(unsigned w) { return __uint_as_float(w & 0xffff0000u); }
; __device__ __forceinline__ float sigmoidf_(float x) { return __builtin_amdgcn_rcpf(1.0f + __expf(-x)); }
;     __device__ __forceinline__ void operator()(const f32x4 (&acc)[2][2][4][2], const Unit& u, int wr, int wc, int fr, int fq) const {
;     ...
;                 for (int bj = 0; bj < 2; ++bj) gv[m][bj] = *(const u32x4*)(Gb + (size_t)(row0 + ai * HALF + m * 16) * ldg + col0 + bj * HALF);
;             asm volatile("" : "+v"(gv[0][0]), "+v"(gv[0][1]), "+v"(gv[1][0]), "+v"(gv[1][1]), "+v"(gv[2][0]), "+v"(gv[2][1]), "+v"(gv[3][0]), "+v"(gv[3][1]));
; #pragma unroll
;             for (int m = 0; m < 4; ++m) { const size_t row = (size_t)(row0 + ai * HALF + m * 16);
; #pragma unroll
;                 for (int bj = 0; bj < 2; ++bj) { const f32x4 v0 = acc[ai][bj][m][0], v1 = acc[ai][bj][m][1];
;                     const u32x4 gq = gv[m][bj];
;                     u32x4 w;
;                     w.x = cvt_pk_bf16(bflo(gq.x) * sigmoidf_(v0[0]), bfhi(gq.x) * sigmoidf_(v0[1]));
;                     w.y = cvt_pk_bf16(bflo(gq.y) * sigmoidf_(v0[2]), bfhi(gq.y) * sigmoidf_(v0[3]));
;                     w.z = cvt_pk_bf16(bflo(gq.z) * sigmoidf_(v1[0]), bfhi(gq.z) * sigmoidf_(v1[1]));
;                     w.w = cvt_pk_bf16(bflo(gq.w) * sigmoidf_(v1[2]), bfhi(gq.w) * sigmoidf_(v1[3]));
;                     *(u32x4*)(O + row * ldc + ocol0 + col0 + bj * HALF) = w; } }
	v_add_f32_e32 v83, 1.0, v83
	v_mul_f32_e32 v84, 0xbfb8aa3b, v84
	v_mul_f32_e32 v87, v87, v89
	v_and_b32_e32 v89, 0xffff0000, v139
	v_rcp_f32_e32 v83, v83
	v_exp_f32_e32 v84, v84
	v_mul_f32_e32 v85, 0xbfb8aa3b, v85
	v_mul_f32_e32 v88, v88, v89
	v_exp_f32_e32 v85, v85
	v_mul_f32_e32 v78, 0xbfb8aa3b, v78
	v_cvt_pk_bf16_f32 v87, v87, v88
	v_lshlrev_b32_e32 v88, 16, v140
	v_exp_f32_e32 v78, v78
	v_mul_f32_e32 v79, 0xbfb8aa3b, v79
	v_mul_f32_e32 v82, v82, v88
	v_and_b32_e32 v88, 0xffff0000, v140
	v_exp_f32_e32 v79, v79
	v_mul_f32_e32 v83, v83, v88
	v_cvt_pk_bf16_f32 v88, v82, v83
	v_add_f32_e32 v82, 1.0, v84
	v_rcp_f32_e32 v82, v82
	v_add_f32_e32 v83, 1.0, v85
	v_rcp_f32_e32 v83, v83
	v_add_f32_e32 v78, 1.0, v78
	v_rcp_f32_e32 v78, v78
	v_add_f32_e32 v79, 1.0, v79
	v_lshlrev_b32_e32 v84, 16, v141
	v_rcp_f32_e32 v79, v79
	v_mul_f32_e32 v80, 0xbfb8aa3b, v80
	v_mul_f32_e32 v82, v82, v84
	v_and_b32_e32 v84, 0xffff0000, v141
	v_exp_f32_e32 v80, v80
	v_mul_f32_e32 v81, 0xbfb8aa3b, v81
	v_mul_f32_e32 v83, v83, v84
	v_cvt_pk_bf16_f32 v89, v82, v83
	v_lshlrev_b32_e32 v82, 16, v134
	v_exp_f32_e32 v81, v81
	v_mul_f32_e32 v78, v78, v82
	v_and_b32_e32 v82, 0xffff0000, v134
	v_mul_f32_e32 v74, 0xbfb8aa3b, v74
	v_mul_f32_e32 v79, v79, v82
	v_exp_f32_e32 v74, v74
	v_mul_f32_e32 v75, 0xbfb8aa3b, v75
	flat_store_dwordx4 v[92:93], v[86:89] offset:256
	v_cvt_pk_bf16_f32 v78, v78, v79
	v_add_f32_e32 v79, 1.0, v80
	v_exp_f32_e32 v75, v75
	v_rcp_f32_e32 v79, v79
	v_add_f32_e32 v80, 1.0, v81
	v_rcp_f32_e32 v80, v80
	v_add_f32_e32 v74, 1.0, v74
	v_lshlrev_b32_e32 v81, 16, v135
	v_rcp_f32_e32 v74, v74
	v_add_f32_e32 v75, 1.0, v75
	v_mul_f32_e32 v76, 0xbfb8aa3b, v76
	v_mul_f32_e32 v79, v79, v81
	v_and_b32_e32 v81, 0xffff0000, v135
	v_rcp_f32_e32 v75, v75
	v_exp_f32_e32 v76, v76
	v_mul_f32_e32 v77, 0xbfb8aa3b, v77
	v_mul_f32_e32 v80, v80, v81
	v_exp_f32_e32 v77, v77
	v_cvt_pk_bf16_f32 v79, v79, v80
	v_lshlrev_b32_e32 v80, 16, v136
	v_mul_f32_e32 v74, v74, v80
	v_and_b32_e32 v80, 0xffff0000, v136
	v_mul_f32_e32 v75, v75, v80
	v_cvt_pk_bf16_f32 v80, v74, v75
	v_add_f32_e32 v74, 1.0, v76
	v_rcp_f32_e32 v74, v74
	v_add_f32_e32 v75, 1.0, v77
	v_rcp_f32_e32 v75, v75
	v_mul_f32_e32 v70, 0xbfb8aa3b, v70
	v_lshlrev_b32_e32 v76, 16, v137
	v_exp_f32_e32 v70, v70
	v_mul_f32_e32 v71, 0xbfb8aa3b, v71
	v_mul_f32_e32 v74, v74, v76
	v_and_b32_e32 v76, 0xffff0000, v137
	v_exp_f32_e32 v71, v71
	v_mul_f32_e32 v75, v75, v76
	v_cvt_pk_bf16_f32 v81, v74, v75
	v_lshlrev_b64 v[74:75], 13, v[184:185]
	v_lshl_add_u64 v[74:75], s[24:25], 0, v[74:75]
	v_add_f32_e32 v70, 1.0, v70
	v_lshl_add_u64 v[74:75], v[74:75], 0, v[178:179]
	v_rcp_f32_e32 v70, v70
	v_add_f32_e32 v71, 1.0, v71
	v_lshl_add_u64 v[76:77], v[74:75], 0, s[88:89]
	v_add_co_u32_e32 v74, vcc, s93, v74
	v_rcp_f32_e32 v71, v71
	v_mul_f32_e32 v72, 0xbfb8aa3b, v72
	v_addc_co_u32_e32 v75, vcc, 0, v75, vcc
	v_exp_f32_e32 v72, v72
	v_mul_f32_e32 v73, 0xbfb8aa3b, v73
	flat_store_dwordx4 v[74:75], v[78:81]
	v_lshlrev_b32_e32 v74, 16, v130
	v_exp_f32_e32 v73, v73
	v_mul_f32_e32 v70, v70, v74
	v_and_b32_e32 v74, 0xffff0000, v130
	v_mul_f32_e32 v66, 0xbfb8aa3b, v66
	v_mul_f32_e32 v71, v71, v74
	v_exp_f32_e32 v66, v66
	v_mul_f32_e32 v67, 0xbfb8aa3b, v67
	v_cvt_pk_bf16_f32 v70, v70, v71
	v_add_f32_e32 v71, 1.0, v72
	v_exp_f32_e32 v67, v67
	v_rcp_f32_e32 v71, v71
	v_add_f32_e32 v72, 1.0, v73
	v_rcp_f32_e32 v72, v72
	v_add_f32_e32 v66, 1.0, v66
	v_lshlrev_b32_e32 v73, 16, v131
	v_rcp_f32_e32 v66, v66
	v_add_f32_e32 v67, 1.0, v67
	v_mul_f32_e32 v68, 0xbfb8aa3b, v68
	v_mul_f32_e32 v71, v71, v73
	v_and_b32_e32 v73, 0xffff0000, v131
	v_rcp_f32_e32 v67, v67
	v_exp_f32_e32 v68, v68
	v_mul_f32_e32 v69, 0xbfb8aa3b, v69
	v_mul_f32_e32 v72, v72, v73
	v_exp_f32_e32 v69, v69
	v_cvt_pk_bf16_f32 v71, v71, v72
	v_lshlrev_b32_e32 v72, 16, v132
	v_mul_f32_e32 v66, v66, v72
	v_and_b32_e32 v72, 0xffff0000, v132
	v_mul_f32_e32 v67, v67, v72
	v_cvt_pk_bf16_f32 v72, v66, v67
	v_add_f32_e32 v66, 1.0, v68
	v_rcp_f32_e32 v66, v66
	v_add_f32_e32 v67, 1.0, v69
	v_rcp_f32_e32 v67, v67
	v_lshlrev_b32_e32 v68, 16, v133
	v_mul_f32_e32 v66, v66, v68
	v_and_b32_e32 v68, 0xffff0000, v133
	v_add_u32_e32 v104, 0x80, v180
	v_mul_f32_e32 v67, v67, v68
	v_ashrrev_i32_e32 v105, 31, v104
	v_cvt_pk_bf16_f32 v73, v66, v67
	v_lshlrev_b64 v[66:67], 12, v[104:105]
	v_add_u32_e32 v94, 0x90, v180
	flat_store_dwordx4 v[76:77], v[70:73] offset:256
	v_lshl_add_u64 v[66:67], v[182:183], 0, v[66:67]
	v_ashrrev_i32_e32 v95, 31, v94
	flat_load_dwordx4 v[96:99], v[66:67]
	flat_load_dwordx4 v[100:103], v[66:67] offset:256
	v_lshlrev_b64 v[66:67], 12, v[94:95]
	v_add_u32_e32 v92, 0xa0, v180
	v_lshl_add_u64 v[66:67], v[182:183], 0, v[66:67]
	v_ashrrev_i32_e32 v93, 31, v92
	flat_load_dwordx4 v[86:89], v[66:67]
	flat_load_dwordx4 v[82:85], v[66:67] offset:256
	v_lshlrev_b64 v[66:67], 12, v[92:93]
	v_add_u32_e32 v90, 0xb0, v180
	v_lshl_add_u64 v[66:67], v[182:183], 0, v[66:67]
	v_ashrrev_i32_e32 v91, 31, v90
	flat_load_dwordx4 v[78:81], v[66:67]
	flat_load_dwordx4 v[74:77], v[66:67] offset:256
	v_lshlrev_b64 v[66:67], 12, v[90:91]
	v_lshl_add_u64 v[66:67], v[182:183], 0, v[66:67]
	flat_load_dwordx4 v[70:73], v[66:67]
	s_nop 0
	flat_load_dwordx4 v[66:69], v[66:67] offset:256
	v_mul_f32_e32 v62, 0xbfb8aa3b, v62
	v_mul_f32_e32 v63, 0xbfb8aa3b, v63
	v_exp_f32_e32 v62, v62
	v_exp_f32_e32 v63, v63
	v_mul_f32_e32 v64, 0xbfb8aa3b, v64
	v_exp_f32_e32 v64, v64
	v_add_f32_e32 v62, 1.0, v62
	v_add_f32_e32 v63, 1.0, v63
	v_rcp_f32_e32 v62, v62
	v_rcp_f32_e32 v63, v63
	v_mul_f32_e32 v65, 0xbfb8aa3b, v65
	s_waitcnt vmcnt(0) lgkmcnt(0)
; __device__ __forceinline__ unsigned cvt_pk_bf16(float lo, float hi) { unsigned r; asm volatile("v_cvt_pk_bf16_f32 %0, %1, %2" : "=v"(r) : "v"(lo), "v"(hi)); return r; }
; __device__ __forceinline__ float bflo(unsigned w) { return __uint_as_float(w << 16); }
; __device__ __forceinline__ float bfhi(unsigned w) { return __uint_as_float(w & 0xffff0000u); }
; __device__ __forceinline__ float sigmoidf_(float x) { return __builtin_amdgcn_rcpf(1.0f + __expf(-x)); }
;     __device__ __forceinline__ void operator()(const f32x4 (&acc)[2][2][4][2], const Unit& u, int wr, int wc, int fr, int fq) const {
;     ...
;             for (int m = 0; m < 4; ++m) { const size_t row = (size_t)(row0 + ai * HALF + m * 16);
; #pragma unroll
;                 for (int bj = 0; bj < 2; ++bj) { const f32x4 v0 = acc[ai][bj][m][0], v1 = acc[ai][bj][m][1];
;                     const u32x4 gq = gv[m][bj];
;                     u32x4 w;
;                     w.x = cvt_pk_bf16(bflo(gq.x) * sigmoidf_(v0[0]), bfhi(gq.x) * sigmoidf_(v0[1]));
;                     w.y = cvt_pk_bf16(bflo(gq.y) * sigmoidf_(v0[2]), bfhi(gq.y) * sigmoidf_(v0[3]));
;                     w.z = cvt_pk_bf16(bflo(gq.z) * sigmoidf_(v1[0]), bfhi(gq.z) * sigmoidf_(v1[1]));
;                     w.w = cvt_pk_bf16(bflo(gq.w) * sigmoidf_(v1[2]), bfhi(gq.w) * sigmoidf_(v1[3]));
;                     *(u32x4*)(O + row * ldc + ocol0 + col0 + bj * HALF) = w; } }
	v_exp_f32_e32 v65, v65
	v_lshlrev_b32_e32 v106, 16, v96
	v_and_b32_e32 v96, 0xffff0000, v96
	v_mul_f32_e32 v58, 0xbfb8aa3b, v58
	v_mul_f32_e32 v62, v62, v106
	v_mul_f32_e32 v63, v63, v96
	v_exp_f32_e32 v58, v58
	v_mul_f32_e32 v59, 0xbfb8aa3b, v59
	v_cvt_pk_bf16_f32 v62, v62, v63
	v_add_f32_e32 v63, 1.0, v64
	v_exp_f32_e32 v59, v59
	v_rcp_f32_e32 v63, v63
	v_add_f32_e32 v64, 1.0, v65
	v_rcp_f32_e32 v64, v64
	v_add_f32_e32 v58, 1.0, v58
	v_lshlrev_b32_e32 v65, 16, v97
	v_rcp_f32_e32 v58, v58
	v_add_f32_e32 v59, 1.0, v59
	v_mul_f32_e32 v60, 0xbfb8aa3b, v60
	v_mul_f32_e32 v63, v63, v65
	v_and_b32_e32 v65, 0xffff0000, v97
	v_rcp_f32_e32 v59, v59
	v_exp_f32_e32 v60, v60
	v_mul_f32_e32 v61, 0xbfb8aa3b, v61
	v_mul_f32_e32 v64, v64, v65
	v_exp_f32_e32 v61, v61
	v_cvt_pk_bf16_f32 v63, v63, v64
	v_lshlrev_b32_e32 v64, 16, v98
	v_mul_f32_e32 v58, v58, v64
	v_and_b32_e32 v64, 0xffff0000, v98
	v_mul_f32_e32 v59, v59, v64
	v_cvt_pk_bf16_f32 v64, v58, v59
	v_add_f32_e32 v58, 1.0, v60
	v_rcp_f32_e32 v58, v58
	v_add_f32_e32 v59, 1.0, v61
	v_rcp_f32_e32 v59, v59
	v_mul_f32_e32 v54, 0xbfb8aa3b, v54
	v_lshlrev_b32_e32 v60, 16, v99
	v_exp_f32_e32 v54, v54
	v_mul_f32_e32 v55, 0xbfb8aa3b, v55
	v_mul_f32_e32 v58, v58, v60
	v_and_b32_e32 v60, 0xffff0000, v99
	v_exp_f32_e32 v55, v55
	v_mul_f32_e32 v59, v59, v60
	v_cvt_pk_bf16_f32 v65, v58, v59
	v_lshlrev_b64 v[58:59], 13, v[104:105]
	v_lshl_add_u64 v[58:59], s[24:25], 0, v[58:59]
	v_add_f32_e32 v54, 1.0, v54
	v_lshl_add_u64 v[58:59], v[58:59], 0, v[178:179]
	v_rcp_f32_e32 v54, v54
	v_add_f32_e32 v55, 1.0, v55
	v_lshl_add_u64 v[60:61], v[58:59], 0, s[88:89]
	v_add_co_u32_e32 v58, vcc, s93, v58
	v_rcp_f32_e32 v55, v55
	v_mul_f32_e32 v56, 0xbfb8aa3b, v56
	v_addc_co_u32_e32 v59, vcc, 0, v59, vcc
	v_exp_f32_e32 v56, v56
	v_mul_f32_e32 v57, 0xbfb8aa3b, v57
	flat_store_dwordx4 v[58:59], v[62:65]
	v_lshlrev_b32_e32 v58, 16, v100
	v_exp_f32_e32 v57, v57
	v_mul_f32_e32 v54, v54, v58
	v_and_b32_e32 v58, 0xffff0000, v100
	v_mul_f32_e32 v50, 0xbfb8aa3b, v50
	v_mul_f32_e32 v55, v55, v58
	v_exp_f32_e32 v50, v50
	v_mul_f32_e32 v51, 0xbfb8aa3b, v51
	v_cvt_pk_bf16_f32 v54, v54, v55
	v_add_f32_e32 v55, 1.0, v56
	v_exp_f32_e32 v51, v51
	v_rcp_f32_e32 v55, v55
	v_add_f32_e32 v56, 1.0, v57
	v_rcp_f32_e32 v56, v56
	v_add_f32_e32 v50, 1.0, v50
	v_lshlrev_b32_e32 v57, 16, v101
	v_rcp_f32_e32 v50, v50
	v_add_f32_e32 v51, 1.0, v51
	v_mul_f32_e32 v52, 0xbfb8aa3b, v52
	v_mul_f32_e32 v55, v55, v57
	v_and_b32_e32 v57, 0xffff0000, v101
	v_rcp_f32_e32 v51, v51
	v_exp_f32_e32 v52, v52
	v_mul_f32_e32 v53, 0xbfb8aa3b, v53
	v_mul_f32_e32 v56, v56, v57
	v_exp_f32_e32 v53, v53
	v_mul_f32_e32 v46, 0xbfb8aa3b, v46
	v_cvt_pk_bf16_f32 v55, v55, v56
	v_lshlrev_b32_e32 v56, 16, v102
	v_exp_f32_e32 v46, v46
	v_mul_f32_e32 v47, 0xbfb8aa3b, v47
	v_mul_f32_e32 v50, v50, v56
	v_and_b32_e32 v56, 0xffff0000, v102
	v_exp_f32_e32 v47, v47
	v_mul_f32_e32 v51, v51, v56
	v_cvt_pk_bf16_f32 v56, v50, v51
	v_add_f32_e32 v50, 1.0, v52
	v_rcp_f32_e32 v50, v50
	v_add_f32_e32 v51, 1.0, v53
	v_rcp_f32_e32 v51, v51
	v_add_f32_e32 v46, 1.0, v46
	v_rcp_f32_e32 v46, v46
	v_add_f32_e32 v47, 1.0, v47
	v_lshlrev_b32_e32 v52, 16, v103
	v_rcp_f32_e32 v47, v47
	v_mul_f32_e32 v48, 0xbfb8aa3b, v48
	v_mul_f32_e32 v50, v50, v52
	v_and_b32_e32 v52, 0xffff0000, v103
	v_exp_f32_e32 v48, v48
	v_mul_f32_e32 v49, 0xbfb8aa3b, v49
	v_mul_f32_e32 v51, v51, v52
	v_cvt_pk_bf16_f32 v57, v50, v51
	v_lshlrev_b32_e32 v50, 16, v86
	v_exp_f32_e32 v49, v49
	v_mul_f32_e32 v46, v46, v50
	v_and_b32_e32 v50, 0xffff0000, v86
	v_mul_f32_e32 v42, 0xbfb8aa3b, v42
	v_mul_f32_e32 v47, v47, v50
	v_exp_f32_e32 v42, v42
	v_mul_f32_e32 v43, 0xbfb8aa3b, v43
	flat_store_dwordx4 v[60:61], v[54:57] offset:256
	v_cvt_pk_bf16_f32 v46, v46, v47
	v_add_f32_e32 v47, 1.0, v48
	v_exp_f32_e32 v43, v43
	v_rcp_f32_e32 v47, v47
	v_add_f32_e32 v48, 1.0, v49
	v_rcp_f32_e32 v48, v48
	v_add_f32_e32 v42, 1.0, v42
	v_lshlrev_b32_e32 v49, 16, v87
	v_rcp_f32_e32 v42, v42
	v_add_f32_e32 v43, 1.0, v43
	v_mul_f32_e32 v44, 0xbfb8aa3b, v44
	v_mul_f32_e32 v47, v47, v49
	v_and_b32_e32 v49, 0xffff0000, v87
	v_rcp_f32_e32 v43, v43
	v_exp_f32_e32 v44, v44
	v_mul_f32_e32 v45, 0xbfb8aa3b, v45
	v_mul_f32_e32 v48, v48, v49
	v_exp_f32_e32 v45, v45
	v_cvt_pk_bf16_f32 v47, v47, v48
	v_lshlrev_b32_e32 v48, 16, v88
	v_mul_f32_e32 v42, v42, v48
	v_and_b32_e32 v48, 0xffff0000, v88
	v_mul_f32_e32 v43, v43, v48
	v_cvt_pk_bf16_f32 v48, v42, v43
	v_add_f32_e32 v42, 1.0, v44
	v_rcp_f32_e32 v42, v42
	v_add_f32_e32 v43, 1.0, v45
	v_rcp_f32_e32 v43, v43
	v_mul_f32_e32 v38, 0xbfb8aa3b, v38
	v_lshlrev_b32_e32 v44, 16, v89
	v_exp_f32_e32 v38, v38
	v_mul_f32_e32 v39, 0xbfb8aa3b, v39
	v_mul_f32_e32 v42, v42, v44
	v_and_b32_e32 v44, 0xffff0000, v89
	v_exp_f32_e32 v39, v39
	v_mul_f32_e32 v43, v43, v44
	v_cvt_pk_bf16_f32 v49, v42, v43
	v_lshlrev_b64 v[42:43], 13, v[94:95]
	v_lshl_add_u64 v[42:43], s[24:25], 0, v[42:43]
	v_add_f32_e32 v38, 1.0, v38
	v_lshl_add_u64 v[42:43], v[42:43], 0, v[178:179]
	v_rcp_f32_e32 v38, v38
	v_add_f32_e32 v39, 1.0, v39
	v_lshl_add_u64 v[44:45], v[42:43], 0, s[88:89]
	v_add_co_u32_e32 v42, vcc, s93, v42
	v_rcp_f32_e32 v39, v39
	v_mul_f32_e32 v40, 0xbfb8aa3b, v40
	v_addc_co_u32_e32 v43, vcc, 0, v43, vcc
	v_exp_f32_e32 v40, v40
	v_mul_f32_e32 v41, 0xbfb8aa3b, v41
	flat_store_dwordx4 v[42:43], v[46:49]
	v_lshlrev_b32_e32 v42, 16, v82
	v_exp_f32_e32 v41, v41
	v_mul_f32_e32 v38, v38, v42
	v_and_b32_e32 v42, 0xffff0000, v82
	v_mul_f32_e32 v34, 0xbfb8aa3b, v34
	v_mul_f32_e32 v39, v39, v42
	v_exp_f32_e32 v34, v34
	v_mul_f32_e32 v35, 0xbfb8aa3b, v35
	v_cvt_pk_bf16_f32 v38, v38, v39
	v_add_f32_e32 v39, 1.0, v40
	v_exp_f32_e32 v35, v35
	v_rcp_f32_e32 v39, v39
; __device__ __forceinline__ unsigned cvt_pk_bf16(float lo, float hi) { unsigned r; asm volatile("v_cvt_pk_bf16_f32 %0, %1, %2" : "=v"(r) : "v"(lo), "v"(hi)); return r; }
; __device__ __forceinline__ float bflo(unsigned w) { return __uint_as_float(w << 16); }
; __device__ __forceinline__ float bfhi(unsigned w) { return __uint_as_float(w & 0xffff0000u); }
; __device__ __forceinline__ float sigmoidf_(float x) { return __builtin_amdgcn_rcpf(1.0f + __expf(-x)); }
;     __device__ __forceinline__ void operator()(const f32x4 (&acc)[2][2][4][2], const Unit& u, int wr, int wc, int fr, int fq) const {
;     ...
;             for (int m = 0; m < 4; ++m) { const size_t row = (size_t)(row0 + ai * HALF + m * 16);
; #pragma unroll
;                 for (int bj = 0; bj < 2; ++bj) { const f32x4 v0 = acc[ai][bj][m][0], v1 = acc[ai][bj][m][1];
;                     const u32x4 gq = gv[m][bj];
;                     u32x4 w;
;                     w.x = cvt_pk_bf16(bflo(gq.x) * sigmoidf_(v0[0]), bfhi(gq.x) * sigmoidf_(v0[1]));
;                     w.y = cvt_pk_bf16(bflo(gq.y) * sigmoidf_(v0[2]), bfhi(gq.y) * sigmoidf_(v0[3]));
;                     w.z = cvt_pk_bf16(bflo(gq.z) * sigmoidf_(v1[0]), bfhi(gq.z) * sigmoidf_(v1[1]));
;                     w.w = cvt_pk_bf16(bflo(gq.w) * sigmoidf_(v1[2]), bfhi(gq.w) * sigmoidf_(v1[3]));
;                     *(u32x4*)(O + row * ldc + ocol0 + col0 + bj * HALF) = w; } }
	v_add_f32_e32 v40, 1.0, v41
	v_rcp_f32_e32 v40, v40
	v_add_f32_e32 v34, 1.0, v34
	v_lshlrev_b32_e32 v41, 16, v83
	v_rcp_f32_e32 v34, v34
	v_add_f32_e32 v35, 1.0, v35
	v_mul_f32_e32 v36, 0xbfb8aa3b, v36
	v_mul_f32_e32 v39, v39, v41
	v_and_b32_e32 v41, 0xffff0000, v83
	v_rcp_f32_e32 v35, v35
	v_exp_f32_e32 v36, v36
	v_mul_f32_e32 v37, 0xbfb8aa3b, v37
	v_mul_f32_e32 v40, v40, v41
	v_exp_f32_e32 v37, v37
	v_mul_f32_e32 v30, 0xbfb8aa3b, v30
	v_cvt_pk_bf16_f32 v39, v39, v40
	v_lshlrev_b32_e32 v40, 16, v84
	v_exp_f32_e32 v30, v30
	v_mul_f32_e32 v31, 0xbfb8aa3b, v31
	v_mul_f32_e32 v34, v34, v40
	v_and_b32_e32 v40, 0xffff0000, v84
	v_exp_f32_e32 v31, v31
	v_mul_f32_e32 v35, v35, v40
	v_cvt_pk_bf16_f32 v40, v34, v35
	v_add_f32_e32 v34, 1.0, v36
	v_rcp_f32_e32 v34, v34
	v_add_f32_e32 v35, 1.0, v37
	v_rcp_f32_e32 v35, v35
	v_add_f32_e32 v30, 1.0, v30
	v_rcp_f32_e32 v30, v30
	v_add_f32_e32 v31, 1.0, v31
	v_lshlrev_b32_e32 v36, 16, v85
	v_rcp_f32_e32 v31, v31
	v_mul_f32_e32 v32, 0xbfb8aa3b, v32
	v_mul_f32_e32 v34, v34, v36
	v_and_b32_e32 v36, 0xffff0000, v85
	v_exp_f32_e32 v32, v32
	v_mul_f32_e32 v33, 0xbfb8aa3b, v33
	v_mul_f32_e32 v35, v35, v36
	v_cvt_pk_bf16_f32 v41, v34, v35
	v_lshlrev_b32_e32 v34, 16, v78
	v_exp_f32_e32 v33, v33
	v_mul_f32_e32 v30, v30, v34
	v_and_b32_e32 v34, 0xffff0000, v78
	v_mul_f32_e32 v26, 0xbfb8aa3b, v26
	v_mul_f32_e32 v31, v31, v34
	v_exp_f32_e32 v26, v26
	v_mul_f32_e32 v27, 0xbfb8aa3b, v27
	flat_store_dwordx4 v[44:45], v[38:41] offset:256
	v_cvt_pk_bf16_f32 v30, v30, v31
	v_add_f32_e32 v31, 1.0, v32
	v_exp_f32_e32 v27, v27
	v_rcp_f32_e32 v31, v31
	v_add_f32_e32 v32, 1.0, v33
	v_rcp_f32_e32 v32, v32
	v_add_f32_e32 v26, 1.0, v26
	v_lshlrev_b32_e32 v33, 16, v79
	v_rcp_f32_e32 v26, v26
	v_add_f32_e32 v27, 1.0, v27
	v_mul_f32_e32 v28, 0xbfb8aa3b, v28
	v_mul_f32_e32 v31, v31, v33
	v_and_b32_e32 v33, 0xffff0000, v79
	v_rcp_f32_e32 v27, v27
	v_exp_f32_e32 v28, v28
	v_mul_f32_e32 v29, 0xbfb8aa3b, v29
	v_mul_f32_e32 v32, v32, v33
	v_exp_f32_e32 v29, v29
	v_cvt_pk_bf16_f32 v31, v31, v32
	v_lshlrev_b32_e32 v32, 16, v80
	v_mul_f32_e32 v26, v26, v32
	v_and_b32_e32 v32, 0xffff0000, v80
	v_mul_f32_e32 v27, v27, v32
	v_cvt_pk_bf16_f32 v32, v26, v27
	v_add_f32_e32 v26, 1.0, v28
	v_rcp_f32_e32 v26, v26
	v_add_f32_e32 v27, 1.0, v29
	v_rcp_f32_e32 v27, v27
	v_mul_f32_e32 v22, 0xbfb8aa3b, v22
	v_lshlrev_b32_e32 v28, 16, v81
	v_exp_f32_e32 v22, v22
	v_mul_f32_e32 v23, 0xbfb8aa3b, v23
	v_mul_f32_e32 v26, v26, v28
	v_and_b32_e32 v28, 0xffff0000, v81
	v_exp_f32_e32 v23, v23
	v_mul_f32_e32 v27, v27, v28
	v_cvt_pk_bf16_f32 v33, v26, v27
	v_lshlrev_b64 v[26:27], 13, v[92:93]
	v_lshl_add_u64 v[26:27], s[24:25], 0, v[26:27]
	v_add_f32_e32 v22, 1.0, v22
	v_lshl_add_u64 v[26:27], v[26:27], 0, v[178:179]
	v_rcp_f32_e32 v22, v22
	v_add_f32_e32 v23, 1.0, v23
	v_lshl_add_u64 v[28:29], v[26:27], 0, s[88:89]
	v_add_co_u32_e32 v26, vcc, s93, v26
	v_rcp_f32_e32 v23, v23
	v_mul_f32_e32 v24, 0xbfb8aa3b, v24
	v_addc_co_u32_e32 v27, vcc, 0, v27, vcc
	v_exp_f32_e32 v24, v24
	v_mul_f32_e32 v25, 0xbfb8aa3b, v25
	flat_store_dwordx4 v[26:27], v[30:33]
	v_lshlrev_b32_e32 v26, 16, v74
	v_exp_f32_e32 v25, v25
	v_mul_f32_e32 v22, v22, v26
	v_and_b32_e32 v26, 0xffff0000, v74
	v_mul_f32_e32 v18, 0xbfb8aa3b, v18
	v_mul_f32_e32 v23, v23, v26
	v_exp_f32_e32 v18, v18
	v_mul_f32_e32 v19, 0xbfb8aa3b, v19
	v_cvt_pk_bf16_f32 v22, v22, v23
	v_add_f32_e32 v23, 1.0, v24
	v_exp_f32_e32 v19, v19
	v_rcp_f32_e32 v23, v23
	v_add_f32_e32 v24, 1.0, v25
	v_rcp_f32_e32 v24, v24
	v_add_f32_e32 v18, 1.0, v18
	v_lshlrev_b32_e32 v25, 16, v75
	v_rcp_f32_e32 v18, v18
	v_add_f32_e32 v19, 1.0, v19
	v_mul_f32_e32 v20, 0xbfb8aa3b, v20
	v_mul_f32_e32 v23, v23, v25
	v_and_b32_e32 v25, 0xffff0000, v75
	v_rcp_f32_e32 v19, v19
	v_exp_f32_e32 v20, v20
	v_mul_f32_e32 v21, 0xbfb8aa3b, v21
	v_mul_f32_e32 v24, v24, v25
	v_exp_f32_e32 v21, v21
	v_mul_f32_e32 v14, 0xbfb8aa3b, v14
	v_cvt_pk_bf16_f32 v23, v23, v24
	v_lshlrev_b32_e32 v24, 16, v76
	v_exp_f32_e32 v14, v14
; __device__ __forceinline__ unsigned cvt_pk_bf16(float lo, float hi) { unsigned r; asm volatile("v_cvt_pk_bf16_f32 %0, %1, %2" : "=v"(r) : "v"(lo), "v"(hi)); return r; }
; __device__ __forceinline__ float bflo(unsigned w) { return __uint_as_float(w << 16); }
; __device__ __forceinline__ float bfhi(unsigned w) { return __uint_as_float(w & 0xffff0000u); }
; __device__ __forceinline__ float sigmoidf_(float x) { return __builtin_amdgcn_rcpf(1.0f + __expf(-x)); }
; #define PG8_BAR __builtin_amdgcn_s_barrier()
;     __device__ __forceinline__ void operator()(const f32x4 (&acc)[2][2][4][2], const Unit& u, int wr, int wc, int fr, int fq) const {
;     ...
;             for (int m = 0; m < 4; ++m) { const size_t row = (size_t)(row0 + ai * HALF + m * 16);
; #pragma unroll
;                 for (int bj = 0; bj < 2; ++bj) { const f32x4 v0 = acc[ai][bj][m][0], v1 = acc[ai][bj][m][1];
;                     const u32x4 gq = gv[m][bj];
;                     u32x4 w;
;                     w.x = cvt_pk_bf16(bflo(gq.x) * sigmoidf_(v0[0]), bfhi(gq.x) * sigmoidf_(v0[1]));
;                     w.y = cvt_pk_bf16(bflo(gq.y) * sigmoidf_(v0[2]), bfhi(gq.y) * sigmoidf_(v0[3]));
;                     w.z = cvt_pk_bf16(bflo(gq.z) * sigmoidf_(v1[0]), bfhi(gq.z) * sigmoidf_(v1[1]));
;                     w.w = cvt_pk_bf16(bflo(gq.w) * sigmoidf_(v1[2]), bfhi(gq.w) * sigmoidf_(v1[3]));
;                     *(u32x4*)(O + row * ldc + ocol0 + col0 + bj * HALF) = w; } }
; template <class Epi, class Sched, bool ALIGN_EPI = false, bool SP2 = false>
; __device__ __forceinline__ void gemm_phase(PG8_LAS unsigned char* lds, const Gemm g, const Sched& S, const Epi& E) {
;     ...
;         if constexpr (!Epi::AFTER_DRAIN) { E(acc, cur, wr, wc, fr, fq); S.done(cur); }
;         if (!has_next) break;
; #pragma unroll
;         for (int a = 0; a < 2; ++a)
; #pragma unroll
;             for (int b = 0; b < 2; ++b)
; #pragma unroll
;                 for (int m = 0; m < 4; ++m)
; #pragma unroll
;                     for (int n = 0; n < 2; ++n) acc[a][b][m][n] = (f32x4){0.f, 0.f, 0.f, 0.f};
;         cur = nxt; cA = nA; cB = nB; ++ui;
;         if constexpr (ALIGN_EPI) { if (wr == 1) PG8_BAR; }
	v_mul_f32_e32 v15, 0xbfb8aa3b, v15
	v_mul_f32_e32 v18, v18, v24
	v_and_b32_e32 v24, 0xffff0000, v76
	v_exp_f32_e32 v15, v15
	v_mul_f32_e32 v19, v19, v24
	v_cvt_pk_bf16_f32 v24, v18, v19
	v_add_f32_e32 v18, 1.0, v20
	v_rcp_f32_e32 v18, v18
	v_add_f32_e32 v19, 1.0, v21
	v_rcp_f32_e32 v19, v19
	v_add_f32_e32 v14, 1.0, v14
	v_rcp_f32_e32 v14, v14
	v_add_f32_e32 v15, 1.0, v15
	v_lshlrev_b32_e32 v20, 16, v77
	v_rcp_f32_e32 v15, v15
	v_mul_f32_e32 v16, 0xbfb8aa3b, v16
	v_mul_f32_e32 v18, v18, v20
	v_and_b32_e32 v20, 0xffff0000, v77
	v_exp_f32_e32 v16, v16
	v_mul_f32_e32 v17, 0xbfb8aa3b, v17
	v_mul_f32_e32 v19, v19, v20
	v_cvt_pk_bf16_f32 v25, v18, v19
	v_lshlrev_b32_e32 v18, 16, v70
	v_exp_f32_e32 v17, v17
	v_mul_f32_e32 v14, v14, v18
	v_and_b32_e32 v18, 0xffff0000, v70
	v_mul_f32_e32 v10, 0xbfb8aa3b, v10
	v_mul_f32_e32 v15, v15, v18
	v_exp_f32_e32 v10, v10
	v_mul_f32_e32 v11, 0xbfb8aa3b, v11
	flat_store_dwordx4 v[28:29], v[22:25] offset:256
	v_cvt_pk_bf16_f32 v14, v14, v15
	v_add_f32_e32 v15, 1.0, v16
	v_exp_f32_e32 v11, v11
	v_rcp_f32_e32 v15, v15
	v_add_f32_e32 v16, 1.0, v17
	v_rcp_f32_e32 v16, v16
	v_add_f32_e32 v10, 1.0, v10
	v_lshlrev_b32_e32 v17, 16, v71
	v_rcp_f32_e32 v10, v10
	v_add_f32_e32 v11, 1.0, v11
	v_mul_f32_e32 v12, 0xbfb8aa3b, v12
	v_mul_f32_e32 v15, v15, v17
	v_and_b32_e32 v17, 0xffff0000, v71
	v_rcp_f32_e32 v11, v11
	v_exp_f32_e32 v12, v12
	v_mul_f32_e32 v13, 0xbfb8aa3b, v13
	v_mul_f32_e32 v16, v16, v17
	v_exp_f32_e32 v13, v13
	v_cvt_pk_bf16_f32 v15, v15, v16
	v_lshlrev_b32_e32 v16, 16, v72
	v_mul_f32_e32 v10, v10, v16
	v_and_b32_e32 v16, 0xffff0000, v72
	v_mul_f32_e32 v11, v11, v16
	v_cvt_pk_bf16_f32 v16, v10, v11
	v_add_f32_e32 v10, 1.0, v12
	v_rcp_f32_e32 v10, v10
	v_add_f32_e32 v11, 1.0, v13
	v_rcp_f32_e32 v11, v11
	v_mul_f32_e32 v6, 0xbfb8aa3b, v6
	v_lshlrev_b32_e32 v12, 16, v73
	v_exp_f32_e32 v6, v6
	v_mul_f32_e32 v7, 0xbfb8aa3b, v7
	v_mul_f32_e32 v10, v10, v12
	v_and_b32_e32 v12, 0xffff0000, v73
	v_exp_f32_e32 v7, v7
	v_mul_f32_e32 v11, v11, v12
	v_cvt_pk_bf16_f32 v17, v10, v11
	v_lshlrev_b64 v[10:11], 13, v[90:91]
	v_lshl_add_u64 v[10:11], s[24:25], 0, v[10:11]
	v_add_f32_e32 v6, 1.0, v6
	v_lshl_add_u64 v[10:11], v[10:11], 0, v[178:179]
	v_rcp_f32_e32 v6, v6
	v_add_f32_e32 v7, 1.0, v7
	v_lshl_add_u64 v[12:13], v[10:11], 0, s[88:89]
	v_add_co_u32_e32 v10, vcc, s93, v10
	v_rcp_f32_e32 v7, v7
	v_mul_f32_e32 v8, 0xbfb8aa3b, v8
	v_addc_co_u32_e32 v11, vcc, 0, v11, vcc
	v_exp_f32_e32 v8, v8
	v_mul_f32_e32 v9, 0xbfb8aa3b, v9
	flat_store_dwordx4 v[10:11], v[14:17]
	v_lshlrev_b32_e32 v10, 16, v66
	v_exp_f32_e32 v9, v9
	v_mul_f32_e32 v6, v6, v10
	v_and_b32_e32 v10, 0xffff0000, v66
	v_mul_f32_e32 v2, 0xbfb8aa3b, v2
	v_mul_f32_e32 v7, v7, v10
	v_exp_f32_e32 v2, v2
	v_mul_f32_e32 v3, 0xbfb8aa3b, v3
	v_cvt_pk_bf16_f32 v6, v6, v7
	v_add_f32_e32 v7, 1.0, v8
	v_exp_f32_e32 v3, v3
	v_rcp_f32_e32 v7, v7
	v_add_f32_e32 v8, 1.0, v9
	v_rcp_f32_e32 v8, v8
	v_add_f32_e32 v2, 1.0, v2
	v_lshlrev_b32_e32 v9, 16, v67
	v_rcp_f32_e32 v2, v2
	v_add_f32_e32 v3, 1.0, v3
	v_mul_f32_e32 v4, 0xbfb8aa3b, v4
	v_mul_f32_e32 v7, v7, v9
	v_and_b32_e32 v9, 0xffff0000, v67
	v_rcp_f32_e32 v3, v3
	v_exp_f32_e32 v4, v4
	v_mul_f32_e32 v5, 0xbfb8aa3b, v5
	v_mul_f32_e32 v8, v8, v9
	v_exp_f32_e32 v5, v5
	v_cvt_pk_bf16_f32 v7, v7, v8
	v_lshlrev_b32_e32 v8, 16, v68
	v_mul_f32_e32 v2, v2, v8
	v_and_b32_e32 v8, 0xffff0000, v68
	v_mul_f32_e32 v3, v3, v8
	v_cvt_pk_bf16_f32 v8, v2, v3
	v_add_f32_e32 v2, 1.0, v4
	v_rcp_f32_e32 v2, v2
	v_add_f32_e32 v3, 1.0, v5
	v_rcp_f32_e32 v3, v3
	v_lshlrev_b32_e32 v4, 16, v69
	v_readlane_b32 s16, v255, 40
	v_mul_f32_e32 v2, v2, v4
	v_and_b32_e32 v4, 0xffff0000, v69
	s_andn2_b64 vcc, exec, s[42:43]
	s_mov_b64 s[26:27], -1
	v_readlane_b32 s17, v255, 41
	s_mov_b32 s34, 0x10000
	s_mov_b32 s35, 0x20000
	v_mul_f32_e32 v3, v3, v4
	v_cvt_pk_bf16_f32 v9, v2, v3
	flat_store_dwordx4 v[12:13], v[6:9] offset:256
	s_cbranch_vccnz .LBB0_404
	s_andn2_b64 vcc, exec, s[22:23]
	s_cbranch_vccnz .LBB0_403
	s_mov_b32 s32, 1
	s_branch .LBB0_403

;     __host__ __device__ bool next(int i, Unit& u) const { return at((long)i * G + c, u); }
; #define PG8_STAGE(bufoff, gbase, voff) do { _Pragma("unroll") for (int _i = 0; _i < 2; ++_i) \
;         __builtin_amdgcn_global_load_lds((const unsigned*)((const char*)(gbase) + (voff)[_i]), (PG8_LAS unsigned*)(lds + (bufoff) + ldsw + _i * 8192), 16, 0, 0); } while (0)
; #define PG8_LDA(dst, b, h) do { _Pragma("unroll") for (int m = 0; m < 4; ++m) _Pragma("unroll") for (int k = 0; k < 2; ++k) dst[m][k] = *(const PG8_LAS bf16x8*)(lds + PG8_SA(b, h) + aoff + m * 2048 + k * 1024); } while (0)
; #define PG8_LDB(dst, b, h) do { _Pragma("unroll") for (int n = 0; n < 2; ++n) _Pragma("unroll") for (int k = 0; k < 2; ++k) dst[n][k] = *(const PG8_LAS bf16x8*)(lds + PG8_SB(b, h) + boff + n * 2048 + k * 1024); } while (0)
; #define PG8_WAIT_V(n) asm volatile("s_waitcnt vmcnt(" #n ")" ::: "memory")
; #define PG8_BAR __builtin_amdgcn_s_barrier()
; template <class Epi, class Sched, bool ALIGN_EPI = false, bool SP2 = false>
; __device__ __forceinline__ void gemm_phase(PG8_LAS unsigned char* lds, const Gemm g, const Sched& S, const Epi& E) {
;     ...
;         const bool has_next = S.next(ui + 1, nxt);
;         const char* nA = has_next ? (const char*)g.A + (size_t)nxt.pm * tstep + (size_t)nxt.k0 * kstep : cA; const char* nB = has_next ? (const char*)g.Bt + (size_t)nxt.pn * tstep + (size_t)nxt.k0 * kstep : cB;
;         const int nt = cur.nt;
;         for (int t = 0; t < nt; t += 2) {
;             const bool last = (t == nt - 2);
;             const char* a1 = cA + (size_t)(t + 1) * kstep;
;             const char* a2 = last ? nA : cA + (size_t)(t + 2) * kstep; const char* b2 = last ? nB : cB + (size_t)(t + 2) * kstep;
;             const char* a3 = a2 + kstep; const char* b3 = b2 + kstep;
;             if (last && has_next) S.a_ready(nxt);
;             if constexpr (SP2) {
;             PG8_LDB(B0, 0, 0); PG8_LDB(B1, 0, 1); PG8_SCHED; PG8_LDA(At, 0, 0); PG8_STAGE(PG8_SA(1, 1), a1 + hstep, voffA);
;             PG8_WAIT_V(8); PG8_WAIT_L(0); PG8_BAR; PG8_MMA(0, 0, At, B0); PG8_MMA(0, 1, At, B1); PG8_BAR; PG8_SCHED;
;             PG8_LDA(At, 0, 1); PG8_STAGE(PG8_SB(0, 0), b2, voffB); PG8_STAGE(PG8_SB(0, 1), b2 + hstep, voffB); PG8_STAGE(PG8_SA(0, 0), a2, voffA);
;             PG8_WAIT_V(8); PG8_WAIT_L(0); PG8_BAR; PG8_MMA(1, 0, At, B0); PG8_MMA(1, 1, At, B1); PG8_BAR; PG8_SCHED;
.LBB0_529:
	s_add_i32 s14, s13, -2
	s_add_u32 s15, s58, 0x100
	s_addc_u32 s16, s59, 0
	s_add_u32 s24, s24, 0x100080
	s_addc_u32 s25, s25, 0
	s_mov_b32 s17, 0
	s_waitcnt vmcnt(0)
	s_waitcnt vmcnt(0)
	s_cmp_lg_u32 s32, 0
	s_cbranch_scc0 .Lrb_skip_2
	s_mov_b32 s32, 0
	s_barrier
.Lrb_skip_2:
	s_add_i32 s21, s17, 2
	s_add_u32 s23, s24, 0xfff00080
	s_addc_u32 s26, s25, -1
	s_add_i32 s30, 0, 0x10000
	s_cmp_eq_u32 s14, s17
	s_cselect_b32 s29, s55, s26
	s_cselect_b32 s28, s54, s23
	s_cselect_b32 s27, s57, s16
	s_cselect_b32 s26, s56, s15
	s_add_i32 s17, 0, 0x14000
	v_add_u32_e32 v142, s30, v190
	v_add_u32_e32 v170, s17, v190
	ds_read_b128 v[130:133], v142
	ds_read_b128 v[134:137], v142 offset:1024
	ds_read_b128 v[138:141], v142 offset:2048
	ds_read_b128 v[142:145], v142 offset:3072
	ds_read_b128 v[146:149], v170
	ds_read_b128 v[150:153], v170 offset:1024
	ds_read_b128 v[178:181], v170 offset:2048
	ds_read_b128 v[182:185], v170 offset:3072
	v_lshl_add_u64 v[170:171], s[24:25], 0, v[176:177]
	s_add_i32 m0, s35, 0xc000
	ds_read_b128 v[186:189], v192
	ds_read_b128 v[194:197], v192 offset:1024
	ds_read_b128 v[198:201], v192 offset:2048
	ds_read_b128 v[202:205], v192 offset:3072
	ds_read_b128 v[206:209], v192 offset:4096
	ds_read_b128 v[220:223], v192 offset:5120
	ds_read_b128 v[224:227], v192 offset:6144
	ds_read_b128 v[228:231], v192 offset:7168
	global_load_lds_dwordx4 v[170:171], off
	v_lshl_add_u64 v[170:171], s[24:25], 0, v[174:175]
	s_add_i32 m0, s35, 0xe000
	s_nop 0
	global_load_lds_dwordx4 v[170:171], off
	s_waitcnt vmcnt(8)
	s_waitcnt lgkmcnt(0)
	s_setprio 1
	s_barrier
	v_mfma_f32_16x16x32_bf16 v[126:129], v[130:133], v[186:189], 0
	v_mfma_f32_16x16x32_bf16 v[122:125], v[138:141], v[186:189], 0
	v_mfma_f32_16x16x32_bf16 v[118:121], v[130:133], v[198:201], 0
	v_mfma_f32_16x16x32_bf16 v[114:117], v[138:141], v[198:201], 0
	v_mfma_f32_16x16x32_bf16 v[102:105], v[130:133], v[206:209], 0
	v_mfma_f32_16x16x32_bf16 v[94:97], v[138:141], v[206:209], 0
	v_mfma_f32_16x16x32_bf16 v[86:89], v[130:133], v[224:227], 0
	v_mfma_f32_16x16x32_bf16 v[78:81], v[138:141], v[224:227], 0
	v_mfma_f32_16x16x32_bf16 v[126:129], v[134:137], v[194:197], v[126:129]
	v_mfma_f32_16x16x32_bf16 v[122:125], v[142:145], v[194:197], v[122:125]
	v_mfma_f32_16x16x32_bf16 v[118:121], v[134:137], v[202:205], v[118:121]
	v_mfma_f32_16x16x32_bf16 v[114:117], v[142:145], v[202:205], v[114:117]
	v_mfma_f32_16x16x32_bf16 v[102:105], v[134:137], v[220:223], v[102:105]
	v_mfma_f32_16x16x32_bf16 v[94:97], v[142:145], v[220:223], v[94:97]
	v_mfma_f32_16x16x32_bf16 v[86:89], v[134:137], v[228:231], v[86:89]
	v_mfma_f32_16x16x32_bf16 v[78:81], v[142:145], v[228:231], v[78:81]
	v_mfma_f32_16x16x32_bf16 v[110:113], v[146:149], v[186:189], 0
	v_mfma_f32_16x16x32_bf16 v[106:109], v[178:181], v[186:189], 0
	v_mfma_f32_16x16x32_bf16 v[98:101], v[146:149], v[198:201], 0
	v_mfma_f32_16x16x32_bf16 v[90:93], v[178:181], v[198:201], 0
	v_mfma_f32_16x16x32_bf16 v[82:85], v[146:149], v[206:209], 0
	v_mfma_f32_16x16x32_bf16 v[74:77], v[178:181], v[206:209], 0
	v_mfma_f32_16x16x32_bf16 v[70:73], v[146:149], v[224:227], 0
	v_mfma_f32_16x16x32_bf16 v[66:69], v[178:181], v[224:227], 0
	v_mfma_f32_16x16x32_bf16 v[110:113], v[150:153], v[194:197], v[110:113]
	v_mfma_f32_16x16x32_bf16 v[106:109], v[182:185], v[194:197], v[106:109]
	v_mfma_f32_16x16x32_bf16 v[98:101], v[150:153], v[202:205], v[98:101]
	v_mfma_f32_16x16x32_bf16 v[90:93], v[182:185], v[202:205], v[90:93]
	v_mfma_f32_16x16x32_bf16 v[82:85], v[150:153], v[220:223], v[82:85]
	v_mfma_f32_16x16x32_bf16 v[74:77], v[182:185], v[220:223], v[74:77]
	v_mfma_f32_16x16x32_bf16 v[70:73], v[150:153], v[228:231], v[70:73]
	v_mfma_f32_16x16x32_bf16 v[66:69], v[182:185], v[228:231], v[66:69]
	s_barrier
	s_setprio 0
	s_add_i32 s23, s30, s34
	v_lshl_add_u64 v[170:171], s[26:27], 0, v[158:159]
	s_mov_b32 m0, s23
	ds_read_b128 v[186:189], v192 offset:16384
	ds_read_b128 v[194:197], v192 offset:17408
	ds_read_b128 v[198:201], v192 offset:18432
	ds_read_b128 v[202:205], v192 offset:19456
	ds_read_b128 v[206:209], v192 offset:20480
	ds_read_b128 v[220:223], v192 offset:21504
	ds_read_b128 v[224:227], v192 offset:22528
	ds_read_b128 v[228:231], v192 offset:23552
	global_load_lds_dwordx4 v[170:171], off
	s_add_i32 m0, s23, 0x2000
	s_add_u32 s58, s26, 0x100000
	v_lshl_add_u64 v[210:211], s[26:27], 0, v[172:173]
	s_addc_u32 s59, s27, 0
	s_add_i32 s17, s17, s34
	global_load_lds_dwordx4 v[210:211], off
	v_lshl_add_u64 v[232:233], s[58:59], 0, v[158:159]
	s_mov_b32 m0, s17
	v_lshl_add_u64 v[234:235], s[28:29], 0, v[156:157]
	global_load_lds_dwordx4 v[232:233], off
	v_lshl_add_u64 v[232:233], s[58:59], 0, v[172:173]
	s_add_i32 m0, s17, 0x2000
	s_nop 0
	global_load_lds_dwordx4 v[232:233], off
	v_lshl_add_u64 v[232:233], s[28:29], 0, v[154:155]
	s_mov_b32 m0, s35
	s_nop 0
	global_load_lds_dwordx4 v[232:233], off
	s_mov_b32 m0, s4
	s_nop 0
	global_load_lds_dwordx4 v[234:235], off
	s_waitcnt vmcnt(8)
	s_waitcnt lgkmcnt(0)
	s_setprio 1
	s_barrier
; #define PG8_STAGE(bufoff, gbase, voff) do { _Pragma("unroll") for (int _i = 0; _i < 2; ++_i) \
;         __builtin_amdgcn_global_load_lds((const unsigned*)((const char*)(gbase) + (voff)[_i]), (PG8_LAS unsigned*)(lds + (bufoff) + ldsw + _i * 8192), 16, 0, 0); } while (0)
; #define PG8_LDA(dst, b, h) do { _Pragma("unroll") for (int m = 0; m < 4; ++m) _Pragma("unroll") for (int k = 0; k < 2; ++k) dst[m][k] = *(const PG8_LAS bf16x8*)(lds + PG8_SA(b, h) + aoff + m * 2048 + k * 1024); } while (0)
; #define PG8_LDB(dst, b, h) do { _Pragma("unroll") for (int n = 0; n < 2; ++n) _Pragma("unroll") for (int k = 0; k < 2; ++k) dst[n][k] = *(const PG8_LAS bf16x8*)(lds + PG8_SB(b, h) + boff + n * 2048 + k * 1024); } while (0)
; #define PG8_MMA(ai, bj, At, Bt) do { __builtin_amdgcn_s_setprio(1); _Pragma("unroll") for (int m = 0; m < 4; ++m) _Pragma("unroll") for (int n = 0; n < 2; ++n) _Pragma("unroll") for (int k = 0; k < 2; ++k) \
;         acc[ai][bj][m][n] = __builtin_amdgcn_mfma_f32_16x16x32_bf16(Bt[n][k], At[m][k], acc[ai][bj][m][n], 0, 0, 0); __builtin_amdgcn_s_setprio(0); } while (0)
; #define PG8_WAIT_V(n) asm volatile("s_waitcnt vmcnt(" #n ")" ::: "memory")
; #define PG8_WAIT_L(n) asm volatile("s_waitcnt lgkmcnt(" #n ")" ::: "memory")
; #define PG8_BAR __builtin_amdgcn_s_barrier()
; #define PG8_SCHED __builtin_amdgcn_sched_barrier(0)
; template <class Epi, class Sched, bool ALIGN_EPI = false, bool SP2 = false>
; __device__ __forceinline__ void gemm_phase(PG8_LAS unsigned char* lds, const Gemm g, const Sched& S, const Epi& E) {
;     ...
;             PG8_WAIT_V(8); PG8_WAIT_L(0); PG8_BAR; PG8_MMA(1, 0, At, B0); PG8_MMA(1, 1, At, B1); PG8_BAR; PG8_SCHED;
;             PG8_LDB(B0, 1, 0); PG8_LDB(B1, 1, 1); PG8_SCHED; PG8_LDA(At, 1, 0); PG8_STAGE(PG8_SA(0, 1), a2 + hstep, voffA);
;             PG8_WAIT_V(8); PG8_WAIT_L(0); PG8_BAR; PG8_MMA(0, 0, At, B0); PG8_MMA(0, 1, At, B1); PG8_BAR; PG8_SCHED;
	v_mfma_f32_16x16x32_bf16 v[62:65], v[130:133], v[186:189], 0
	v_mfma_f32_16x16x32_bf16 v[58:61], v[138:141], v[186:189], 0
	v_mfma_f32_16x16x32_bf16 v[54:57], v[130:133], v[198:201], 0
	v_mfma_f32_16x16x32_bf16 v[46:49], v[138:141], v[198:201], 0
	v_mfma_f32_16x16x32_bf16 v[38:41], v[130:133], v[206:209], 0
	v_mfma_f32_16x16x32_bf16 v[30:33], v[138:141], v[206:209], 0
	v_mfma_f32_16x16x32_bf16 v[22:25], v[130:133], v[224:227], 0
	v_mfma_f32_16x16x32_bf16 v[14:17], v[138:141], v[224:227], 0
	v_mfma_f32_16x16x32_bf16 v[62:65], v[134:137], v[194:197], v[62:65]
	v_mfma_f32_16x16x32_bf16 v[58:61], v[142:145], v[194:197], v[58:61]
	v_mfma_f32_16x16x32_bf16 v[54:57], v[134:137], v[202:205], v[54:57]
	v_mfma_f32_16x16x32_bf16 v[46:49], v[142:145], v[202:205], v[46:49]
	v_mfma_f32_16x16x32_bf16 v[38:41], v[134:137], v[220:223], v[38:41]
	v_mfma_f32_16x16x32_bf16 v[30:33], v[142:145], v[220:223], v[30:33]
	v_mfma_f32_16x16x32_bf16 v[22:25], v[134:137], v[228:231], v[22:25]
	v_mfma_f32_16x16x32_bf16 v[14:17], v[142:145], v[228:231], v[14:17]
	v_mfma_f32_16x16x32_bf16 v[50:53], v[146:149], v[186:189], 0
	v_mfma_f32_16x16x32_bf16 v[42:45], v[178:181], v[186:189], 0
	v_mfma_f32_16x16x32_bf16 v[34:37], v[146:149], v[198:201], 0
	v_mfma_f32_16x16x32_bf16 v[26:29], v[178:181], v[198:201], 0
	v_mfma_f32_16x16x32_bf16 v[18:21], v[146:149], v[206:209], 0
	v_mfma_f32_16x16x32_bf16 v[10:13], v[178:181], v[206:209], 0
	v_mfma_f32_16x16x32_bf16 v[6:9], v[146:149], v[224:227], 0
	v_mfma_f32_16x16x32_bf16 v[2:5], v[178:181], v[224:227], 0
	v_mfma_f32_16x16x32_bf16 v[50:53], v[150:153], v[194:197], v[50:53]
	v_mfma_f32_16x16x32_bf16 v[42:45], v[182:185], v[194:197], v[42:45]
	v_mfma_f32_16x16x32_bf16 v[34:37], v[150:153], v[202:205], v[34:37]
	v_mfma_f32_16x16x32_bf16 v[26:29], v[182:185], v[202:205], v[26:29]
	v_mfma_f32_16x16x32_bf16 v[18:21], v[150:153], v[220:223], v[18:21]
	v_mfma_f32_16x16x32_bf16 v[10:13], v[182:185], v[220:223], v[10:13]
	v_mfma_f32_16x16x32_bf16 v[6:9], v[150:153], v[228:231], v[6:9]
	v_mfma_f32_16x16x32_bf16 v[2:5], v[182:185], v[228:231], v[2:5]
	s_barrier
	s_setprio 0
	s_add_i32 s17, 0, 0x18000
	s_add_i32 s23, 0, 0x1c000
	v_add_u32_e32 v142, s17, v190
	v_add_u32_e32 v182, s23, v190
	ds_read_b128 v[130:133], v142
	ds_read_b128 v[134:137], v142 offset:1024
	ds_read_b128 v[138:141], v142 offset:2048
	ds_read_b128 v[142:145], v142 offset:3072
	ds_read_b128 v[146:149], v182
	ds_read_b128 v[150:153], v182 offset:1024
	ds_read_b128 v[178:181], v182 offset:2048
	ds_read_b128 v[182:185], v182 offset:3072
	s_add_u32 s28, s28, 0x100000
	s_addc_u32 s29, s29, 0
	s_mov_b32 m0, s5
	v_lshl_add_u64 v[236:237], s[28:29], 0, v[154:155]
	ds_read_b128 v[186:189], v192 offset:32768
	ds_read_b128 v[194:197], v192 offset:33792
	ds_read_b128 v[198:201], v192 offset:34816
	ds_read_b128 v[202:205], v192 offset:35840
	ds_read_b128 v[206:209], v192 offset:36864
	ds_read_b128 v[220:223], v192 offset:37888
	ds_read_b128 v[224:227], v192 offset:38912
	ds_read_b128 v[228:231], v192 offset:39936
	global_load_lds_dwordx4 v[236:237], off
	v_lshl_add_u64 v[236:237], s[28:29], 0, v[156:157]
	s_mov_b32 m0, s6
	s_nop 0
	global_load_lds_dwordx4 v[236:237], off
	s_waitcnt vmcnt(8)
	s_waitcnt lgkmcnt(0)
	s_setprio 1
	s_barrier
	v_mfma_f32_16x16x32_bf16 v[126:129], v[130:133], v[186:189], v[126:129]
	v_mfma_f32_16x16x32_bf16 v[122:125], v[138:141], v[186:189], v[122:125]
	v_mfma_f32_16x16x32_bf16 v[118:121], v[130:133], v[198:201], v[118:121]
	v_mfma_f32_16x16x32_bf16 v[114:117], v[138:141], v[198:201], v[114:117]
	v_mfma_f32_16x16x32_bf16 v[102:105], v[130:133], v[206:209], v[102:105]
	v_mfma_f32_16x16x32_bf16 v[94:97], v[138:141], v[206:209], v[94:97]
	v_mfma_f32_16x16x32_bf16 v[86:89], v[130:133], v[224:227], v[86:89]
	v_mfma_f32_16x16x32_bf16 v[78:81], v[138:141], v[224:227], v[78:81]
	v_mfma_f32_16x16x32_bf16 v[126:129], v[134:137], v[194:197], v[126:129]
	v_mfma_f32_16x16x32_bf16 v[122:125], v[142:145], v[194:197], v[122:125]
	v_mfma_f32_16x16x32_bf16 v[118:121], v[134:137], v[202:205], v[118:121]
	v_mfma_f32_16x16x32_bf16 v[114:117], v[142:145], v[202:205], v[114:117]
	v_mfma_f32_16x16x32_bf16 v[102:105], v[134:137], v[220:223], v[102:105]
	v_mfma_f32_16x16x32_bf16 v[94:97], v[142:145], v[220:223], v[94:97]
	v_mfma_f32_16x16x32_bf16 v[86:89], v[134:137], v[228:231], v[86:89]
	v_mfma_f32_16x16x32_bf16 v[78:81], v[142:145], v[228:231], v[78:81]
	v_mfma_f32_16x16x32_bf16 v[110:113], v[146:149], v[186:189], v[110:113]
	v_mfma_f32_16x16x32_bf16 v[106:109], v[178:181], v[186:189], v[106:109]
	v_mfma_f32_16x16x32_bf16 v[98:101], v[146:149], v[198:201], v[98:101]
	v_mfma_f32_16x16x32_bf16 v[90:93], v[178:181], v[198:201], v[90:93]
	v_mfma_f32_16x16x32_bf16 v[82:85], v[146:149], v[206:209], v[82:85]
	v_mfma_f32_16x16x32_bf16 v[74:77], v[178:181], v[206:209], v[74:77]
	v_mfma_f32_16x16x32_bf16 v[70:73], v[146:149], v[224:227], v[70:73]
	v_mfma_f32_16x16x32_bf16 v[66:69], v[178:181], v[224:227], v[66:69]
	v_mfma_f32_16x16x32_bf16 v[110:113], v[150:153], v[194:197], v[110:113]
	v_mfma_f32_16x16x32_bf16 v[106:109], v[182:185], v[194:197], v[106:109]
	v_mfma_f32_16x16x32_bf16 v[98:101], v[150:153], v[202:205], v[98:101]
	v_mfma_f32_16x16x32_bf16 v[90:93], v[182:185], v[202:205], v[90:93]
	v_mfma_f32_16x16x32_bf16 v[82:85], v[150:153], v[220:223], v[82:85]
	v_mfma_f32_16x16x32_bf16 v[74:77], v[182:185], v[220:223], v[74:77]
	v_mfma_f32_16x16x32_bf16 v[70:73], v[150:153], v[228:231], v[70:73]
	v_mfma_f32_16x16x32_bf16 v[66:69], v[182:185], v[228:231], v[66:69]
	s_barrier
; #define PG8_STAGE(bufoff, gbase, voff) do { _Pragma("unroll") for (int _i = 0; _i < 2; ++_i) \
;         __builtin_amdgcn_global_load_lds((const unsigned*)((const char*)(gbase) + (voff)[_i]), (PG8_LAS unsigned*)(lds + (bufoff) + ldsw + _i * 8192), 16, 0, 0); } while (0)
; #define PG8_LDA(dst, b, h) do { _Pragma("unroll") for (int m = 0; m < 4; ++m) _Pragma("unroll") for (int k = 0; k < 2; ++k) dst[m][k] = *(const PG8_LAS bf16x8*)(lds + PG8_SA(b, h) + aoff + m * 2048 + k * 1024); } while (0)
; #define PG8_LDB(dst, b, h) do { _Pragma("unroll") for (int n = 0; n < 2; ++n) _Pragma("unroll") for (int k = 0; k < 2; ++k) dst[n][k] = *(const PG8_LAS bf16x8*)(lds + PG8_SB(b, h) + boff + n * 2048 + k * 1024); } while (0)
; #define PG8_MMA(ai, bj, At, Bt) do { __builtin_amdgcn_s_setprio(1); _Pragma("unroll") for (int m = 0; m < 4; ++m) _Pragma("unroll") for (int n = 0; n < 2; ++n) _Pragma("unroll") for (int k = 0; k < 2; ++k) \
;         acc[ai][bj][m][n] = __builtin_amdgcn_mfma_f32_16x16x32_bf16(Bt[n][k], At[m][k], acc[ai][bj][m][n], 0, 0, 0); __builtin_amdgcn_s_setprio(0); } while (0)
; #define PG8_WAIT_V(n) asm volatile("s_waitcnt vmcnt(" #n ")" ::: "memory")
; #define PG8_WAIT_L(n) asm volatile("s_waitcnt lgkmcnt(" #n ")" ::: "memory")
; #define PG8_BAR __builtin_amdgcn_s_barrier()
; #define PG8_SCHED __builtin_amdgcn_sched_barrier(0)
; template <class Epi, class Sched, bool ALIGN_EPI = false, bool SP2 = false>
; __device__ __forceinline__ void gemm_phase(PG8_LAS unsigned char* lds, const Gemm g, const Sched& S, const Epi& E) {
;     ...
;             PG8_LDB(B0, 1, 0); PG8_LDB(B1, 1, 1); PG8_SCHED; PG8_LDA(At, 1, 0); PG8_STAGE(PG8_SA(0, 1), a2 + hstep, voffA);
;             PG8_WAIT_V(8); PG8_WAIT_L(0); PG8_BAR; PG8_MMA(0, 0, At, B0); PG8_MMA(0, 1, At, B1); PG8_BAR; PG8_SCHED;
;             PG8_LDA(At, 1, 1); PG8_STAGE(PG8_SB(1, 0), b3, voffB); PG8_STAGE(PG8_SB(1, 1), b3 + hstep, voffB); PG8_STAGE(PG8_SA(1, 0), a3, voffA);
;             PG8_WAIT_V(8); PG8_WAIT_L(0); PG8_BAR; PG8_MMA(1, 0, At, B0); PG8_MMA(1, 1, At, B1); PG8_BAR; PG8_SCHED;
	s_setprio 0
	s_add_i32 s17, s17, s34
	v_lshl_add_u64 v[170:171], v[170:171], 0, s[96:97]
	s_mov_b32 m0, s17
	ds_read_b128 v[186:189], v192 offset:49152
	ds_read_b128 v[194:197], v192 offset:50176
	ds_read_b128 v[198:201], v192 offset:51200
	ds_read_b128 v[202:205], v192 offset:52224
	ds_read_b128 v[206:209], v192 offset:53248
	ds_read_b128 v[220:223], v192 offset:54272
	ds_read_b128 v[224:227], v192 offset:55296
	ds_read_b128 v[228:231], v192 offset:56320
	global_load_lds_dwordx4 v[170:171], off
	s_add_i32 m0, s17, 0x2000
	s_add_u32 s26, s26, 0x100080
	v_lshl_add_u64 v[170:171], v[210:211], 0, s[96:97]
	s_addc_u32 s27, s27, 0
	s_add_i32 s17, s23, s34
	global_load_lds_dwordx4 v[170:171], off
	v_lshl_add_u64 v[170:171], s[26:27], 0, v[158:159]
	s_mov_b32 m0, s17
	s_nop 0
	global_load_lds_dwordx4 v[170:171], off
	v_lshl_add_u64 v[170:171], s[26:27], 0, v[172:173]
	s_add_i32 m0, s17, 0x2000
	s_nop 0
	global_load_lds_dwordx4 v[170:171], off
	v_lshl_add_u64 v[170:171], v[232:233], 0, s[96:97]
	s_mov_b32 m0, s9
	s_nop 0
	global_load_lds_dwordx4 v[170:171], off
	v_lshl_add_u64 v[170:171], v[234:235], 0, s[96:97]
	s_mov_b32 m0, s10
	s_nop 0
	global_load_lds_dwordx4 v[170:171], off
	s_waitcnt vmcnt(8)
	s_waitcnt lgkmcnt(0)
	s_setprio 1
	s_barrier
	v_mfma_f32_16x16x32_bf16 v[62:65], v[130:133], v[186:189], v[62:65]
	v_mfma_f32_16x16x32_bf16 v[58:61], v[138:141], v[186:189], v[58:61]
	v_mfma_f32_16x16x32_bf16 v[54:57], v[130:133], v[198:201], v[54:57]
	v_mfma_f32_16x16x32_bf16 v[46:49], v[138:141], v[198:201], v[46:49]
	v_mfma_f32_16x16x32_bf16 v[38:41], v[130:133], v[206:209], v[38:41]
	v_mfma_f32_16x16x32_bf16 v[30:33], v[138:141], v[206:209], v[30:33]
	v_mfma_f32_16x16x32_bf16 v[22:25], v[130:133], v[224:227], v[22:25]
	v_mfma_f32_16x16x32_bf16 v[14:17], v[138:141], v[224:227], v[14:17]
	v_mfma_f32_16x16x32_bf16 v[62:65], v[134:137], v[194:197], v[62:65]
	v_mfma_f32_16x16x32_bf16 v[58:61], v[142:145], v[194:197], v[58:61]
	v_mfma_f32_16x16x32_bf16 v[54:57], v[134:137], v[202:205], v[54:57]
	v_mfma_f32_16x16x32_bf16 v[46:49], v[142:145], v[202:205], v[46:49]
	v_mfma_f32_16x16x32_bf16 v[38:41], v[134:137], v[220:223], v[38:41]
	v_mfma_f32_16x16x32_bf16 v[30:33], v[142:145], v[220:223], v[30:33]
	v_mfma_f32_16x16x32_bf16 v[22:25], v[134:137], v[228:231], v[22:25]
	v_mfma_f32_16x16x32_bf16 v[14:17], v[142:145], v[228:231], v[14:17]
	v_mfma_f32_16x16x32_bf16 v[50:53], v[146:149], v[186:189], v[50:53]
	v_mfma_f32_16x16x32_bf16 v[42:45], v[178:181], v[186:189], v[42:45]
	v_mfma_f32_16x16x32_bf16 v[34:37], v[146:149], v[198:201], v[34:37]
	v_mfma_f32_16x16x32_bf16 v[26:29], v[178:181], v[198:201], v[26:29]
	v_mfma_f32_16x16x32_bf16 v[18:21], v[146:149], v[206:209], v[18:21]
	v_mfma_f32_16x16x32_bf16 v[10:13], v[178:181], v[206:209], v[10:13]
	v_mfma_f32_16x16x32_bf16 v[6:9], v[146:149], v[224:227], v[6:9]
	v_mfma_f32_16x16x32_bf16 v[2:5], v[178:181], v[224:227], v[2:5]
	v_mfma_f32_16x16x32_bf16 v[50:53], v[150:153], v[194:197], v[50:53]
	v_mfma_f32_16x16x32_bf16 v[42:45], v[182:185], v[194:197], v[42:45]
	v_mfma_f32_16x16x32_bf16 v[34:37], v[150:153], v[202:205], v[34:37]
	v_mfma_f32_16x16x32_bf16 v[26:29], v[182:185], v[202:205], v[26:29]
	v_mfma_f32_16x16x32_bf16 v[18:21], v[150:153], v[220:223], v[18:21]
	v_mfma_f32_16x16x32_bf16 v[10:13], v[182:185], v[220:223], v[10:13]
	v_mfma_f32_16x16x32_bf16 v[6:9], v[150:153], v[228:231], v[6:9]
	v_mfma_f32_16x16x32_bf16 v[2:5], v[182:185], v[228:231], v[2:5]
	s_barrier
	s_setprio 0
	s_add_u32 s15, s15, 0x100
	s_addc_u32 s16, s16, 0
	s_add_u32 s24, s24, 0x100
	s_addc_u32 s25, s25, 0
	s_cmp_ge_i32 s21, s13
	s_mov_b32 s17, s21
	s_cbranch_scc1 .Lpeel_exit_2

; #define PG8_BAR __builtin_amdgcn_s_barrier()
; template <class Epi, class Sched, bool ALIGN_EPI = false, bool SP2 = false>
; __device__ __forceinline__ void gemm_phase(PG8_LAS unsigned char* lds, const Gemm g, const Sched& S, const Epi& E) {
;     ...
;         if (!has_next) break;
; #pragma unroll
;         for (int a = 0; a < 2; ++a)
; #pragma unroll
;             for (int b = 0; b < 2; ++b)
; #pragma unroll
;                 for (int m = 0; m < 4; ++m)
; #pragma unroll
;                     for (int n = 0; n < 2; ++n) acc[a][b][m][n] = (f32x4){0.f, 0.f, 0.f, 0.f};
;         cur = nxt; cA = nA; cB = nB; ++ui;
;         if constexpr (ALIGN_EPI) { if (wr == 1) PG8_BAR; }
.LBB0_546:
	s_andn2_b64 vcc, exec, s[40:41]
	s_cbranch_vccnz .LBB0_508
	s_mov_b32 s32, 1
	s_branch .LBB0_508

;     __host__ __device__ bool next(int i, Unit& u) const { return at((long)i * G + c, u); }
; #define PG8_STAGE(bufoff, gbase, voff) do { _Pragma("unroll") for (int _i = 0; _i < 2; ++_i) \
;         __builtin_amdgcn_global_load_lds((const unsigned*)((const char*)(gbase) + (voff)[_i]), (PG8_LAS unsigned*)(lds + (bufoff) + ldsw + _i * 8192), 16, 0, 0); } while (0)
; #define PG8_LDA(dst, b, h) do { _Pragma("unroll") for (int m = 0; m < 4; ++m) _Pragma("unroll") for (int k = 0; k < 2; ++k) dst[m][k] = *(const PG8_LAS bf16x8*)(lds + PG8_SA(b, h) + aoff + m * 2048 + k * 1024); } while (0)
; #define PG8_LDB(dst, b, h) do { _Pragma("unroll") for (int n = 0; n < 2; ++n) _Pragma("unroll") for (int k = 0; k < 2; ++k) dst[n][k] = *(const PG8_LAS bf16x8*)(lds + PG8_SB(b, h) + boff + n * 2048 + k * 1024); } while (0)
; #define PG8_WAIT_V(n) asm volatile("s_waitcnt vmcnt(" #n ")" ::: "memory")
; #define PG8_BAR __builtin_amdgcn_s_barrier()
; template <class Epi, class Sched, bool ALIGN_EPI = false, bool SP2 = false>
; __device__ __forceinline__ void gemm_phase(PG8_LAS unsigned char* lds, const Gemm g, const Sched& S, const Epi& E) {
;     ...
;         const bool has_next = S.next(ui + 1, nxt);
;         const char* nA = has_next ? (const char*)g.A + (size_t)nxt.pm * tstep + (size_t)nxt.k0 * kstep : cA; const char* nB = has_next ? (const char*)g.Bt + (size_t)nxt.pn * tstep + (size_t)nxt.k0 * kstep : cB;
;         const int nt = cur.nt;
;         for (int t = 0; t < nt; t += 2) {
;             const bool last = (t == nt - 2);
;             const char* a1 = cA + (size_t)(t + 1) * kstep;
;             const char* a2 = last ? nA : cA + (size_t)(t + 2) * kstep; const char* b2 = last ? nB : cB + (size_t)(t + 2) * kstep;
;             const char* a3 = a2 + kstep; const char* b3 = b2 + kstep;
;             if (last && has_next) S.a_ready(nxt);
;             if constexpr (SP2) {
;             PG8_LDB(B0, 0, 0); PG8_LDB(B1, 0, 1); PG8_SCHED; PG8_LDA(At, 0, 0); PG8_STAGE(PG8_SA(1, 1), a1 + hstep, voffA);
;             PG8_WAIT_V(8); PG8_WAIT_L(0); PG8_BAR; PG8_MMA(0, 0, At, B0); PG8_MMA(0, 1, At, B1); PG8_BAR; PG8_SCHED;
;             PG8_LDA(At, 0, 1); PG8_STAGE(PG8_SB(0, 0), b2, voffB); PG8_STAGE(PG8_SB(0, 1), b2 + hstep, voffB); PG8_STAGE(PG8_SA(0, 0), a2, voffA);
;             PG8_WAIT_V(8); PG8_WAIT_L(0); PG8_BAR; PG8_MMA(1, 0, At, B0); PG8_MMA(1, 1, At, B1); PG8_BAR; PG8_SCHED;
.LBB0_709:
	s_ashr_i32 s63, s62, 31
	s_lshl_b64 s[16:17], s[62:63], 21
	s_add_u32 s28, s4, s16
	s_addc_u32 s29, s5, s17
	s_and_b64 s[16:17], s[20:21], exec
	s_cselect_b32 s30, s29, s23
	s_cselect_b32 s31, s28, s22
	s_ashr_i32 s61, s60, 31
	s_lshl_b64 s[16:17], s[60:61], 21
	s_add_u32 s26, s6, s16
	s_addc_u32 s27, s7, s17
	s_and_b64 s[16:17], s[20:21], exec
	s_cselect_b32 s61, s27, s25
	s_cselect_b32 s63, s26, s24
	s_add_u32 s16, s24, 0x100
	s_addc_u32 s17, s25, 0
	s_add_u32 vcc_lo, s22, 0x100080
	s_addc_u32 vcc_hi, s23, 0
	s_mov_b32 s65, -2
	s_waitcnt vmcnt(0)
	s_cmp_lg_u32 s32, 0
	s_cbranch_scc0 .Lrb_skip_3
	s_mov_b32 s32, 0
	s_barrier
.Lrb_skip_3:
	s_add_u32 s22, vcc_lo, 0xfff00080
	s_addc_u32 s23, vcc_hi, -1
	s_add_i32 s68, 0, 0x10000
	s_cmp_eq_u32 s65, 60
	s_cselect_b32 s25, s30, s23
	s_cselect_b32 s24, s31, s22
	s_cselect_b32 s23, s61, s17
	s_cselect_b32 s22, s63, s16
	s_add_i32 s70, 0, 0x14000
	v_add_u32_e32 v70, s68, v220
	v_add_u32_e32 v170, s70, v220
	ds_read_b128 v[50:53], v70
	ds_read_b128 v[54:57], v70 offset:1024
	ds_read_b128 v[66:69], v70 offset:2048
	ds_read_b128 v[70:73], v70 offset:3072
	ds_read_b128 v[74:77], v170
	ds_read_b128 v[86:89], v170 offset:1024
	ds_read_b128 v[154:157], v170 offset:2048
	ds_read_b128 v[188:191], v170 offset:3072
	v_lshl_add_u64 v[170:171], vcc, 0, v[186:187]
	s_add_i32 m0, s10, 0xc000
	ds_read_b128 v[192:195], v222
	ds_read_b128 v[196:199], v222 offset:1024
	ds_read_b128 v[200:203], v222 offset:2048
	ds_read_b128 v[204:207], v222 offset:3072
	ds_read_b128 v[224:227], v222 offset:4096
	ds_read_b128 v[228:231], v222 offset:5120
	ds_read_b128 v[232:235], v222 offset:6144
	ds_read_b128 v[236:239], v222 offset:7168
	global_load_lds_dwordx4 v[170:171], off
	v_lshl_add_u64 v[170:171], vcc, 0, v[184:185]
	s_add_i32 m0, s10, 0xe000
	s_nop 0
	global_load_lds_dwordx4 v[170:171], off
	s_waitcnt vmcnt(8)
	s_waitcnt lgkmcnt(0)
	s_setprio 1
	s_barrier
	v_mfma_f32_16x16x32_bf16 v[142:145], v[50:53], v[192:195], 0
	v_mfma_f32_16x16x32_bf16 v[130:133], v[66:69], v[192:195], 0
	v_mfma_f32_16x16x32_bf16 v[138:141], v[50:53], v[200:203], 0
	v_mfma_f32_16x16x32_bf16 v[126:129], v[66:69], v[200:203], 0
	v_mfma_f32_16x16x32_bf16 v[118:121], v[50:53], v[224:227], 0
	v_mfma_f32_16x16x32_bf16 v[110:113], v[66:69], v[224:227], 0
	v_mfma_f32_16x16x32_bf16 v[98:101], v[50:53], v[232:235], 0
	v_mfma_f32_16x16x32_bf16 v[94:97], v[66:69], v[232:235], 0
	v_mfma_f32_16x16x32_bf16 v[142:145], v[54:57], v[196:199], v[142:145]
	v_mfma_f32_16x16x32_bf16 v[130:133], v[70:73], v[196:199], v[130:133]
	v_mfma_f32_16x16x32_bf16 v[138:141], v[54:57], v[204:207], v[138:141]
	v_mfma_f32_16x16x32_bf16 v[126:129], v[70:73], v[204:207], v[126:129]
	v_mfma_f32_16x16x32_bf16 v[118:121], v[54:57], v[228:231], v[118:121]
	v_mfma_f32_16x16x32_bf16 v[110:113], v[70:73], v[228:231], v[110:113]
	v_mfma_f32_16x16x32_bf16 v[98:101], v[54:57], v[236:239], v[98:101]
	v_mfma_f32_16x16x32_bf16 v[94:97], v[70:73], v[236:239], v[94:97]
	v_mfma_f32_16x16x32_bf16 v[150:153], v[74:77], v[192:195], 0
	v_mfma_f32_16x16x32_bf16 v[146:149], v[154:157], v[192:195], 0
	v_mfma_f32_16x16x32_bf16 v[134:137], v[74:77], v[200:203], 0
	v_mfma_f32_16x16x32_bf16 v[122:125], v[154:157], v[200:203], 0
	v_mfma_f32_16x16x32_bf16 v[114:117], v[74:77], v[224:227], 0
	v_mfma_f32_16x16x32_bf16 v[106:109], v[154:157], v[224:227], 0
	v_mfma_f32_16x16x32_bf16 v[102:105], v[74:77], v[232:235], 0
	v_mfma_f32_16x16x32_bf16 v[90:93], v[154:157], v[232:235], 0
	v_mfma_f32_16x16x32_bf16 v[150:153], v[86:89], v[196:199], v[150:153]
	v_mfma_f32_16x16x32_bf16 v[146:149], v[188:191], v[196:199], v[146:149]
	v_mfma_f32_16x16x32_bf16 v[134:137], v[86:89], v[204:207], v[134:137]
	v_mfma_f32_16x16x32_bf16 v[122:125], v[188:191], v[204:207], v[122:125]
	v_mfma_f32_16x16x32_bf16 v[114:117], v[86:89], v[228:231], v[114:117]
	v_mfma_f32_16x16x32_bf16 v[106:109], v[188:191], v[228:231], v[106:109]
	v_mfma_f32_16x16x32_bf16 v[102:105], v[86:89], v[236:239], v[102:105]
	v_mfma_f32_16x16x32_bf16 v[90:93], v[188:191], v[236:239], v[90:93]
	s_barrier
	s_setprio 0
	s_add_i32 s68, s68, s9
	v_lshl_add_u64 v[170:171], s[22:23], 0, v[158:159]
	s_mov_b32 m0, s68
	ds_read_b128 v[192:195], v222 offset:16384
	ds_read_b128 v[196:199], v222 offset:17408
	ds_read_b128 v[200:203], v222 offset:18432
	ds_read_b128 v[204:207], v222 offset:19456
	ds_read_b128 v[224:227], v222 offset:20480
	ds_read_b128 v[228:231], v222 offset:21504
	ds_read_b128 v[232:235], v222 offset:22528
	ds_read_b128 v[236:239], v222 offset:23552
	global_load_lds_dwordx4 v[170:171], off
	s_add_i32 m0, s68, 0x2000
	s_add_u32 s68, s22, 0x100000
	v_lshl_add_u64 v[208:209], s[22:23], 0, v[172:173]
	s_addc_u32 s69, s23, 0
	s_add_i32 s70, s70, s9
	global_load_lds_dwordx4 v[208:209], off
	v_lshl_add_u64 v[210:211], s[68:69], 0, v[158:159]
	s_mov_b32 m0, s70
	v_lshl_add_u64 v[244:245], s[24:25], 0, v[174:175]
	global_load_lds_dwordx4 v[210:211], off
	v_lshl_add_u64 v[210:211], s[68:69], 0, v[172:173]
	s_add_i32 m0, s70, 0x2000
	s_nop 0
	global_load_lds_dwordx4 v[210:211], off
	v_lshl_add_u64 v[210:211], s[24:25], 0, v[176:177]
	s_mov_b32 m0, s10
	s_nop 0
	global_load_lds_dwordx4 v[210:211], off
	s_mov_b32 m0, s11
	s_nop 0
	global_load_lds_dwordx4 v[244:245], off
	s_waitcnt vmcnt(8)
	s_waitcnt lgkmcnt(0)
	s_setprio 1
	s_barrier
; #define PG8_STAGE(bufoff, gbase, voff) do { _Pragma("unroll") for (int _i = 0; _i < 2; ++_i) \
;         __builtin_amdgcn_global_load_lds((const unsigned*)((const char*)(gbase) + (voff)[_i]), (PG8_LAS unsigned*)(lds + (bufoff) + ldsw + _i * 8192), 16, 0, 0); } while (0)
; #define PG8_LDA(dst, b, h) do { _Pragma("unroll") for (int m = 0; m < 4; ++m) _Pragma("unroll") for (int k = 0; k < 2; ++k) dst[m][k] = *(const PG8_LAS bf16x8*)(lds + PG8_SA(b, h) + aoff + m * 2048 + k * 1024); } while (0)
; #define PG8_LDB(dst, b, h) do { _Pragma("unroll") for (int n = 0; n < 2; ++n) _Pragma("unroll") for (int k = 0; k < 2; ++k) dst[n][k] = *(const PG8_LAS bf16x8*)(lds + PG8_SB(b, h) + boff + n * 2048 + k * 1024); } while (0)
; #define PG8_MMA(ai, bj, At, Bt) do { __builtin_amdgcn_s_setprio(1); _Pragma("unroll") for (int m = 0; m < 4; ++m) _Pragma("unroll") for (int n = 0; n < 2; ++n) _Pragma("unroll") for (int k = 0; k < 2; ++k) \
;         acc[ai][bj][m][n] = __builtin_amdgcn_mfma_f32_16x16x32_bf16(Bt[n][k], At[m][k], acc[ai][bj][m][n], 0, 0, 0); __builtin_amdgcn_s_setprio(0); } while (0)
; #define PG8_WAIT_V(n) asm volatile("s_waitcnt vmcnt(" #n ")" ::: "memory")
; #define PG8_WAIT_L(n) asm volatile("s_waitcnt lgkmcnt(" #n ")" ::: "memory")
; #define PG8_BAR __builtin_amdgcn_s_barrier()
; #define PG8_SCHED __builtin_amdgcn_sched_barrier(0)
; template <class Epi, class Sched, bool ALIGN_EPI = false, bool SP2 = false>
; __device__ __forceinline__ void gemm_phase(PG8_LAS unsigned char* lds, const Gemm g, const Sched& S, const Epi& E) {
;     ...
;             PG8_WAIT_V(8); PG8_WAIT_L(0); PG8_BAR; PG8_MMA(1, 0, At, B0); PG8_MMA(1, 1, At, B1); PG8_BAR; PG8_SCHED;
;             PG8_LDB(B0, 1, 0); PG8_LDB(B1, 1, 1); PG8_SCHED; PG8_LDA(At, 1, 0); PG8_STAGE(PG8_SA(0, 1), a2 + hstep, voffA);
;             PG8_WAIT_V(8); PG8_WAIT_L(0); PG8_BAR; PG8_MMA(0, 0, At, B0); PG8_MMA(0, 1, At, B1); PG8_BAR; PG8_SCHED;
	v_mfma_f32_16x16x32_bf16 v[62:65], v[50:53], v[192:195], 0
	v_mfma_f32_16x16x32_bf16 v[42:45], v[66:69], v[192:195], 0
	v_mfma_f32_16x16x32_bf16 v[58:61], v[50:53], v[200:203], 0
	v_mfma_f32_16x16x32_bf16 v[38:41], v[66:69], v[200:203], 0
	v_mfma_f32_16x16x32_bf16 v[30:33], v[50:53], v[224:227], 0
	v_mfma_f32_16x16x32_bf16 v[22:25], v[66:69], v[224:227], 0
	v_mfma_f32_16x16x32_bf16 v[10:13], v[50:53], v[232:235], 0
	v_mfma_f32_16x16x32_bf16 v[6:9], v[66:69], v[232:235], 0
	v_mfma_f32_16x16x32_bf16 v[62:65], v[54:57], v[196:199], v[62:65]
	v_mfma_f32_16x16x32_bf16 v[42:45], v[70:73], v[196:199], v[42:45]
	v_mfma_f32_16x16x32_bf16 v[58:61], v[54:57], v[204:207], v[58:61]
	v_mfma_f32_16x16x32_bf16 v[38:41], v[70:73], v[204:207], v[38:41]
	v_mfma_f32_16x16x32_bf16 v[30:33], v[54:57], v[228:231], v[30:33]
	v_mfma_f32_16x16x32_bf16 v[22:25], v[70:73], v[228:231], v[22:25]
	v_mfma_f32_16x16x32_bf16 v[10:13], v[54:57], v[236:239], v[10:13]
	v_mfma_f32_16x16x32_bf16 v[6:9], v[70:73], v[236:239], v[6:9]
	v_mfma_f32_16x16x32_bf16 v[46:49], v[74:77], v[200:203], 0
	v_mfma_f32_16x16x32_bf16 v[34:37], v[154:157], v[200:203], 0
	v_mfma_f32_16x16x32_bf16 v[26:29], v[74:77], v[224:227], 0
	v_mfma_f32_16x16x32_bf16 v[18:21], v[154:157], v[224:227], 0
	v_mfma_f32_16x16x32_bf16 v[14:17], v[74:77], v[232:235], 0
	v_mfma_f32_16x16x32_bf16 v[2:5], v[154:157], v[232:235], 0
	v_mfma_f32_16x16x32_bf16 v[50:53], v[74:77], v[192:195], 0
	v_mfma_f32_16x16x32_bf16 v[54:57], v[154:157], v[192:195], 0
	v_mfma_f32_16x16x32_bf16 v[46:49], v[86:89], v[204:207], v[46:49]
	v_mfma_f32_16x16x32_bf16 v[34:37], v[188:191], v[204:207], v[34:37]
	v_mfma_f32_16x16x32_bf16 v[26:29], v[86:89], v[228:231], v[26:29]
	v_mfma_f32_16x16x32_bf16 v[18:21], v[188:191], v[228:231], v[18:21]
	v_mfma_f32_16x16x32_bf16 v[14:17], v[86:89], v[236:239], v[14:17]
	v_mfma_f32_16x16x32_bf16 v[2:5], v[188:191], v[236:239], v[2:5]
	v_mfma_f32_16x16x32_bf16 v[50:53], v[86:89], v[196:199], v[50:53]
	v_mfma_f32_16x16x32_bf16 v[54:57], v[188:191], v[196:199], v[54:57]
	s_barrier
	s_setprio 0
	s_add_i32 s68, 0, 0x18000
	s_add_i32 s69, 0, 0x1c000
	v_add_u32_e32 v78, s68, v220
	v_add_u32_e32 v82, s69, v220
	ds_read_b128 v[66:69], v78
	ds_read_b128 v[70:73], v78 offset:1024
	ds_read_b128 v[74:77], v78 offset:2048
	ds_read_b128 v[78:81], v78 offset:3072
	ds_read_b128 v[86:89], v82
	ds_read_b128 v[154:157], v82 offset:1024
	ds_read_b128 v[188:191], v82 offset:2048
	ds_read_b128 v[192:195], v82 offset:3072
	s_add_u32 s24, s24, 0x100000
	s_addc_u32 s25, s25, 0
	s_mov_b32 m0, s12
	v_lshl_add_u64 v[240:241], s[24:25], 0, v[176:177]
	ds_read_b128 v[82:85], v222 offset:32768
	ds_read_b128 v[196:199], v222 offset:33792
	ds_read_b128 v[200:203], v222 offset:34816
	ds_read_b128 v[204:207], v222 offset:35840
	ds_read_b128 v[224:227], v222 offset:36864
	ds_read_b128 v[228:231], v222 offset:37888
	ds_read_b128 v[232:235], v222 offset:38912
	ds_read_b128 v[236:239], v222 offset:39936
	global_load_lds_dwordx4 v[240:241], off
	v_lshl_add_u64 v[240:241], s[24:25], 0, v[174:175]
	s_mov_b32 m0, s13
	s_nop 0
	global_load_lds_dwordx4 v[240:241], off
	s_waitcnt vmcnt(8)
	s_waitcnt lgkmcnt(0)
	s_setprio 1
	s_barrier
	v_mfma_f32_16x16x32_bf16 v[142:145], v[66:69], v[82:85], v[142:145]
	v_mfma_f32_16x16x32_bf16 v[130:133], v[74:77], v[82:85], v[130:133]
	v_mfma_f32_16x16x32_bf16 v[138:141], v[66:69], v[200:203], v[138:141]
	v_mfma_f32_16x16x32_bf16 v[126:129], v[74:77], v[200:203], v[126:129]
	v_mfma_f32_16x16x32_bf16 v[118:121], v[66:69], v[224:227], v[118:121]
	v_mfma_f32_16x16x32_bf16 v[110:113], v[74:77], v[224:227], v[110:113]
	v_mfma_f32_16x16x32_bf16 v[98:101], v[66:69], v[232:235], v[98:101]
	v_mfma_f32_16x16x32_bf16 v[94:97], v[74:77], v[232:235], v[94:97]
	v_mfma_f32_16x16x32_bf16 v[142:145], v[70:73], v[196:199], v[142:145]
	v_mfma_f32_16x16x32_bf16 v[130:133], v[78:81], v[196:199], v[130:133]
	v_mfma_f32_16x16x32_bf16 v[138:141], v[70:73], v[204:207], v[138:141]
	v_mfma_f32_16x16x32_bf16 v[126:129], v[78:81], v[204:207], v[126:129]
	v_mfma_f32_16x16x32_bf16 v[118:121], v[70:73], v[228:231], v[118:121]
	v_mfma_f32_16x16x32_bf16 v[110:113], v[78:81], v[228:231], v[110:113]
	v_mfma_f32_16x16x32_bf16 v[98:101], v[70:73], v[236:239], v[98:101]
	v_mfma_f32_16x16x32_bf16 v[94:97], v[78:81], v[236:239], v[94:97]
	v_mfma_f32_16x16x32_bf16 v[150:153], v[86:89], v[82:85], v[150:153]
	v_mfma_f32_16x16x32_bf16 v[146:149], v[188:191], v[82:85], v[146:149]
	v_mfma_f32_16x16x32_bf16 v[134:137], v[86:89], v[200:203], v[134:137]
	v_mfma_f32_16x16x32_bf16 v[122:125], v[188:191], v[200:203], v[122:125]
	v_mfma_f32_16x16x32_bf16 v[114:117], v[86:89], v[224:227], v[114:117]
	v_mfma_f32_16x16x32_bf16 v[106:109], v[188:191], v[224:227], v[106:109]
	v_mfma_f32_16x16x32_bf16 v[102:105], v[86:89], v[232:235], v[102:105]
	v_mfma_f32_16x16x32_bf16 v[90:93], v[188:191], v[232:235], v[90:93]
	v_mfma_f32_16x16x32_bf16 v[150:153], v[154:157], v[196:199], v[150:153]
	v_mfma_f32_16x16x32_bf16 v[146:149], v[192:195], v[196:199], v[146:149]
	v_mfma_f32_16x16x32_bf16 v[134:137], v[154:157], v[204:207], v[134:137]
	v_mfma_f32_16x16x32_bf16 v[122:125], v[192:195], v[204:207], v[122:125]
	v_mfma_f32_16x16x32_bf16 v[114:117], v[154:157], v[228:231], v[114:117]
	v_mfma_f32_16x16x32_bf16 v[106:109], v[192:195], v[228:231], v[106:109]
	v_mfma_f32_16x16x32_bf16 v[102:105], v[154:157], v[236:239], v[102:105]
	v_mfma_f32_16x16x32_bf16 v[90:93], v[192:195], v[236:239], v[90:93]
	s_barrier
; #define PG8_STAGE(bufoff, gbase, voff) do { _Pragma("unroll") for (int _i = 0; _i < 2; ++_i) \
;         __builtin_amdgcn_global_load_lds((const unsigned*)((const char*)(gbase) + (voff)[_i]), (PG8_LAS unsigned*)(lds + (bufoff) + ldsw + _i * 8192), 16, 0, 0); } while (0)
; #define PG8_LDA(dst, b, h) do { _Pragma("unroll") for (int m = 0; m < 4; ++m) _Pragma("unroll") for (int k = 0; k < 2; ++k) dst[m][k] = *(const PG8_LAS bf16x8*)(lds + PG8_SA(b, h) + aoff + m * 2048 + k * 1024); } while (0)
; #define PG8_LDB(dst, b, h) do { _Pragma("unroll") for (int n = 0; n < 2; ++n) _Pragma("unroll") for (int k = 0; k < 2; ++k) dst[n][k] = *(const PG8_LAS bf16x8*)(lds + PG8_SB(b, h) + boff + n * 2048 + k * 1024); } while (0)
; #define PG8_MMA(ai, bj, At, Bt) do { __builtin_amdgcn_s_setprio(1); _Pragma("unroll") for (int m = 0; m < 4; ++m) _Pragma("unroll") for (int n = 0; n < 2; ++n) _Pragma("unroll") for (int k = 0; k < 2; ++k) \
;         acc[ai][bj][m][n] = __builtin_amdgcn_mfma_f32_16x16x32_bf16(Bt[n][k], At[m][k], acc[ai][bj][m][n], 0, 0, 0); __builtin_amdgcn_s_setprio(0); } while (0)
; #define PG8_WAIT_V(n) asm volatile("s_waitcnt vmcnt(" #n ")" ::: "memory")
; #define PG8_WAIT_L(n) asm volatile("s_waitcnt lgkmcnt(" #n ")" ::: "memory")
; #define PG8_BAR __builtin_amdgcn_s_barrier()
; #define PG8_SCHED __builtin_amdgcn_sched_barrier(0)
; template <class Epi, class Sched, bool ALIGN_EPI = false, bool SP2 = false>
; __device__ __forceinline__ void gemm_phase(PG8_LAS unsigned char* lds, const Gemm g, const Sched& S, const Epi& E) {
;     ...
;             PG8_LDB(B0, 1, 0); PG8_LDB(B1, 1, 1); PG8_SCHED; PG8_LDA(At, 1, 0); PG8_STAGE(PG8_SA(0, 1), a2 + hstep, voffA);
;             PG8_WAIT_V(8); PG8_WAIT_L(0); PG8_BAR; PG8_MMA(0, 0, At, B0); PG8_MMA(0, 1, At, B1); PG8_BAR; PG8_SCHED;
;             PG8_LDA(At, 1, 1); PG8_STAGE(PG8_SB(1, 0), b3, voffB); PG8_STAGE(PG8_SB(1, 1), b3 + hstep, voffB); PG8_STAGE(PG8_SA(1, 0), a3, voffA);
;             PG8_WAIT_V(8); PG8_WAIT_L(0); PG8_BAR; PG8_MMA(1, 0, At, B0); PG8_MMA(1, 1, At, B1); PG8_BAR; PG8_SCHED;
	s_setprio 0
	s_add_i32 s24, s68, s9
	s_nop 2
	v_lshl_add_u64 v[82:83], v[170:171], 0, s[96:97]
	s_mov_b32 m0, s24
	ds_read_b128 v[196:199], v222 offset:49152
	ds_read_b128 v[200:203], v222 offset:50176
	ds_read_b128 v[204:207], v222 offset:51200
	ds_read_b128 v[224:227], v222 offset:52224
	ds_read_b128 v[228:231], v222 offset:53248
	ds_read_b128 v[232:235], v222 offset:54272
	ds_read_b128 v[236:239], v222 offset:55296
	ds_read_b128 v[240:243], v222 offset:56320
	global_load_lds_dwordx4 v[82:83], off
	s_add_i32 m0, s24, 0x2000
	s_add_u32 s22, s22, 0x100080
	v_lshl_add_u64 v[82:83], v[208:209], 0, s[96:97]
	s_addc_u32 s23, s23, 0
	s_add_i32 s24, s69, s9
	global_load_lds_dwordx4 v[82:83], off
	v_lshl_add_u64 v[82:83], s[22:23], 0, v[158:159]
	s_mov_b32 m0, s24
	s_nop 0
	global_load_lds_dwordx4 v[82:83], off
	v_lshl_add_u64 v[82:83], s[22:23], 0, v[172:173]
	s_add_i32 m0, s24, 0x2000
	s_nop 0
	global_load_lds_dwordx4 v[82:83], off
	v_lshl_add_u64 v[82:83], v[210:211], 0, s[96:97]
	s_mov_b32 m0, s0
	s_nop 0
	global_load_lds_dwordx4 v[82:83], off
	v_lshl_add_u64 v[82:83], v[244:245], 0, s[96:97]
	s_mov_b32 m0, s34
	s_nop 0
	global_load_lds_dwordx4 v[82:83], off
	s_waitcnt vmcnt(8)
	s_waitcnt lgkmcnt(0)
	s_setprio 1
	s_barrier
	v_mfma_f32_16x16x32_bf16 v[62:65], v[66:69], v[196:199], v[62:65]
	v_mfma_f32_16x16x32_bf16 v[42:45], v[74:77], v[196:199], v[42:45]
	v_mfma_f32_16x16x32_bf16 v[58:61], v[66:69], v[204:207], v[58:61]
	v_mfma_f32_16x16x32_bf16 v[38:41], v[74:77], v[204:207], v[38:41]
	v_mfma_f32_16x16x32_bf16 v[30:33], v[66:69], v[228:231], v[30:33]
	v_mfma_f32_16x16x32_bf16 v[22:25], v[74:77], v[228:231], v[22:25]
	v_mfma_f32_16x16x32_bf16 v[10:13], v[66:69], v[236:239], v[10:13]
	v_mfma_f32_16x16x32_bf16 v[6:9], v[74:77], v[236:239], v[6:9]
	v_mfma_f32_16x16x32_bf16 v[62:65], v[70:73], v[200:203], v[62:65]
	v_mfma_f32_16x16x32_bf16 v[42:45], v[78:81], v[200:203], v[42:45]
	v_mfma_f32_16x16x32_bf16 v[58:61], v[70:73], v[224:227], v[58:61]
	v_mfma_f32_16x16x32_bf16 v[38:41], v[78:81], v[224:227], v[38:41]
	v_mfma_f32_16x16x32_bf16 v[30:33], v[70:73], v[232:235], v[30:33]
	v_mfma_f32_16x16x32_bf16 v[22:25], v[78:81], v[232:235], v[22:25]
	v_mfma_f32_16x16x32_bf16 v[10:13], v[70:73], v[240:243], v[10:13]
	v_mfma_f32_16x16x32_bf16 v[6:9], v[78:81], v[240:243], v[6:9]
	v_mfma_f32_16x16x32_bf16 v[50:53], v[86:89], v[196:199], v[50:53]
	v_mfma_f32_16x16x32_bf16 v[54:57], v[188:191], v[196:199], v[54:57]
	v_mfma_f32_16x16x32_bf16 v[46:49], v[86:89], v[204:207], v[46:49]
	v_mfma_f32_16x16x32_bf16 v[34:37], v[188:191], v[204:207], v[34:37]
	v_mfma_f32_16x16x32_bf16 v[26:29], v[86:89], v[228:231], v[26:29]
	v_mfma_f32_16x16x32_bf16 v[18:21], v[188:191], v[228:231], v[18:21]
	v_mfma_f32_16x16x32_bf16 v[14:17], v[86:89], v[236:239], v[14:17]
	v_mfma_f32_16x16x32_bf16 v[2:5], v[188:191], v[236:239], v[2:5]
	v_mfma_f32_16x16x32_bf16 v[82:85], v[154:157], v[200:203], v[50:53]
	v_mfma_f32_16x16x32_bf16 v[78:81], v[192:195], v[200:203], v[54:57]
	v_mfma_f32_16x16x32_bf16 v[46:49], v[154:157], v[224:227], v[46:49]
	v_mfma_f32_16x16x32_bf16 v[34:37], v[192:195], v[224:227], v[34:37]
	v_mfma_f32_16x16x32_bf16 v[26:29], v[154:157], v[232:235], v[26:29]
	v_mfma_f32_16x16x32_bf16 v[18:21], v[192:195], v[232:235], v[18:21]
	v_mfma_f32_16x16x32_bf16 v[14:17], v[154:157], v[240:243], v[14:17]
	v_mfma_f32_16x16x32_bf16 v[2:5], v[192:195], v[240:243], v[2:5]
	s_barrier
	s_setprio 0
	s_add_i32 s65, s65, 2
	s_add_u32 s16, s16, 0x100
	s_addc_u32 s17, s17, 0
	s_add_u32 vcc_lo, vcc_lo, 0x100
	s_addc_u32 vcc_hi, vcc_hi, 0
	s_cmp_gt_u32 s65, 61
	s_cbranch_scc1 .Lpeel_exit_3

;     __device__ __forceinline__ void operator()(const f32x4 (&acc)[2][2][4][2], const Unit& u, int wr, int wc, int fr, int fq) const {
;         const int ch0 = u.pn * 128 + wc * 32 + 8 * fq;
;         f32x4 w0[2], w1[2], w2[2];
; #pragma unroll
;         for (int n = 0; n < 2; ++n) { w0[n] = *(const f32x4*)(cw + ch0 + 4 * n); w1[n] = *(const f32x4*)(cw + ldh + ch0 + 4 * n); w2[n] = *(const f32x4*)(cw + 2 * ldh + ch0 + 4 * n); }
;         const bool f1 = fr >= 1, f2 = fr >= 2;
; #pragma unroll
;         for (int ai = 0; ai < 2; ++ai) {
;             const int blk = u.pm * 4 + ai * 2 + wr;
; #pragma unroll
;             for (int m = 0; m < 4; ++m) {
;                 const size_t row = (size_t)(u.pm * BM + ai * HALF + wr * 64 + m * 16 + fr);
;                 float hg[8];
; #pragma unroll
;                 for (int n = 0; n < 2; ++n)
; #pragma unroll
;                     for (int i = 0; i < 4; ++i) {
;                         const float cur = acc[ai][0][m][n][i], prv = (m > 0) ? acc[ai][0][m > 0 ? m - 1 : 0][n][i] : cur;
;                         const float r1c = dpp_ror1(cur), r1p = dpp_ror1(prv), r2c = dpp_ror2(cur), r2p = dpp_ror2(prv);
;                         const float tm1 = f1 ? r1c : r1p, tm2 = f2 ? r2c : r2p;
;                         const float cv = w0[n][i] * tm2 + w1[n][i] * tm1 + w2[n][i] * cur;
;                         hg[4 * n + i] = cv * sigmoidf_(cv) * acc[ai][1][m][n][i];
;                     }
;                 if (m == 0 && fr < 2) {
;                     const f32x4 a0 = acc[ai][0][0][0], a1 = acc[ai][0][0][1], v0 = acc[ai][1][0][0], v1 = acc[ai][1][0][1];
;                     u32x4 wa, wv; wa.x = cvt_pk_bf16(a0[0], a0[1]); wa.y = cvt_pk_bf16(a0[2], a0[3]); wa.z = cvt_pk_bf16(a1[0], a1[1]); wa.w = cvt_pk_bf16(a1[2], a1[3]);
;                     wv.x = cvt_pk_bf16(v0[0], v0[1]); wv.y = cvt_pk_bf16(v0[2], v0[3]); wv.z = cvt_pk_bf16(v1[0], v1[1]); wv.w = cvt_pk_bf16(v1[2], v1[3]);
;                     *(u32x4*)(side + ((size_t)blk * 6 + 2 + fr) * ldh + ch0) = wa; *(u32x4*)(side + ((size_t)blk * 6 + 4 + fr) * ldh + ch0) = wv;
;                 } else {
;                     u32x4 w; w.x = cvt_pk_bf16(hg[0], hg[1]); w.y = cvt_pk_bf16(hg[2], hg[3]); w.z = cvt_pk_bf16(hg[4], hg[5]); w.w = cvt_pk_bf16(hg[6], hg[7]);
;                     *(u32x4*)(HG + row * ldh + ch0) = w;
;                 }
.LBB0_713:
	v_lshl_or_b32 v70, s15, 7, v221
	v_lshlrev_b32_e32 v71, 2, v70
	global_load_dwordx4 v[224:227], v71, s[52:53]
	global_load_dwordx4 v[228:231], v71, s[52:53] offset:16
	global_load_dwordx4 v[232:235], v71, s[56:57]
	global_load_dwordx4 v[236:239], v71, s[56:57] offset:16
	global_load_dwordx4 v[192:195], v71, s[58:59]
	global_load_dwordx4 v[196:199], v71, s[58:59] offset:16
	s_mov_b32 s65, 0x100000
	v_and_b32_e32 v72, 15, v161
	v_cmp_eq_u32_e64 s[16:17], 15, v72
	v_lshlrev_b32_e32 v188, 1, v70
	v_mov_b32_e32 v189, 0
	v_lshl_add_u32 v73, s14, 8, v161
	v_mad_u64_u32 v[170:171], vcc, v73, s92, v[188:189]
	s_lshl_b32 s14, s14, 2
	s_add_i32 s14, s14, s8
	s_mul_i32 s14, s14, 6
	v_add_u32_e32 v73, s14, v72
	v_lshl_add_u64 v[170:171], s[50:51], 0, v[170:171]
	v_mad_u64_u32 v[190:191], vcc, v73, s92, v[188:189]
	s_mov_b64 s[22:23], exec
	s_mov_b32 s14, 0xbfb8aa3b
	s_mov_b32 s15, 0xbfb8aa3b
	s_mov_b32 s24, 1.0
	s_mov_b32 s25, 1.0
	v_lshl_add_u64 v[190:191], s[48:49], 0, v[190:191]
	s_waitcnt vmcnt(0)
	v_cvt_pk_bf16_f32 v154, v142, v143
	v_cvt_pk_bf16_f32 v155, v144, v145
	v_cvt_pk_bf16_f32 v156, v130, v131
	v_cvt_pk_bf16_f32 v157, v132, v133
	v_cvt_pk_bf16_f32 v204, v150, v151
	v_cvt_pk_bf16_f32 v205, v152, v153
	v_cvt_pk_bf16_f32 v206, v146, v147
	v_cvt_pk_bf16_f32 v207, v148, v149
	v_add_co_u32_e32 v188, vcc, 0xac00, v190
	v_addc_co_u32_e32 v189, vcc, 0, v191, vcc
	v_add_co_u32_e32 v208, vcc, 0x15800, v190
	v_addc_co_u32_e32 v209, vcc, 0, v191, vcc
	s_andn2_b64 exec, s[22:23], s[40:41]
	global_store_dwordx4 v[188:189], v[154:157], off
	global_store_dwordx4 v[208:209], v[204:207], off
	s_mov_b64 exec, s[22:23]
	s_nop 4
	v_pk_mul_f32 v[70:71], v[192:193], v[142:143]
	v_pk_mul_f32 v[72:73], v[194:195], v[144:145]
	v_fmac_f32_dpp v70, v142, v232 row_ror:1 row_mask:0xf bank_mask:0xf
	v_fmac_f32_dpp v71, v143, v233 row_ror:1 row_mask:0xf bank_mask:0xf
	v_fmac_f32_dpp v72, v144, v234 row_ror:1 row_mask:0xf bank_mask:0xf
	v_fmac_f32_dpp v73, v145, v235 row_ror:1 row_mask:0xf bank_mask:0xf
	v_fmac_f32_dpp v70, v142, v224 row_ror:2 row_mask:0xf bank_mask:0xf
	v_fmac_f32_dpp v71, v143, v225 row_ror:2 row_mask:0xf bank_mask:0xf
	v_fmac_f32_dpp v72, v144, v226 row_ror:2 row_mask:0xf bank_mask:0xf
	v_fmac_f32_dpp v73, v145, v227 row_ror:2 row_mask:0xf bank_mask:0xf
	v_pk_mul_f32 v[200:201], v[70:71], s[14:15]
	v_pk_mul_f32 v[202:203], v[72:73], s[14:15]
	v_exp_f32_e32 v200, v200
	v_exp_f32_e32 v201, v201
	v_exp_f32_e32 v202, v202
	v_exp_f32_e32 v203, v203
	v_pk_add_f32 v[200:201], v[200:201], s[24:25]
	v_pk_add_f32 v[202:203], v[202:203], s[24:25]
	v_rcp_f32_e32 v200, v200
	v_rcp_f32_e32 v201, v201
	v_rcp_f32_e32 v202, v202
	v_rcp_f32_e32 v203, v203
	v_pk_mul_f32 v[70:71], v[70:71], v[200:201]
	v_pk_mul_f32 v[72:73], v[72:73], v[202:203]
	v_pk_mul_f32 v[150:151], v[150:151], v[70:71]
	v_pk_mul_f32 v[152:153], v[152:153], v[72:73]
	v_pk_mul_f32 v[70:71], v[196:197], v[130:131]
	v_pk_mul_f32 v[72:73], v[198:199], v[132:133]
	v_fmac_f32_dpp v70, v130, v236 row_ror:1 row_mask:0xf bank_mask:0xf
	v_fmac_f32_dpp v71, v131, v237 row_ror:1 row_mask:0xf bank_mask:0xf
	v_fmac_f32_dpp v72, v132, v238 row_ror:1 row_mask:0xf bank_mask:0xf
	v_fmac_f32_dpp v73, v133, v239 row_ror:1 row_mask:0xf bank_mask:0xf
	v_fmac_f32_dpp v70, v130, v228 row_ror:2 row_mask:0xf bank_mask:0xf
	v_fmac_f32_dpp v71, v131, v229 row_ror:2 row_mask:0xf bank_mask:0xf
	v_fmac_f32_dpp v72, v132, v230 row_ror:2 row_mask:0xf bank_mask:0xf
	v_fmac_f32_dpp v73, v133, v231 row_ror:2 row_mask:0xf bank_mask:0xf
	v_pk_mul_f32 v[200:201], v[70:71], s[14:15]
	v_pk_mul_f32 v[202:203], v[72:73], s[14:15]
	v_exp_f32_e32 v200, v200
	v_exp_f32_e32 v201, v201
	v_exp_f32_e32 v202, v202
	v_exp_f32_e32 v203, v203
	v_pk_add_f32 v[200:201], v[200:201], s[24:25]
	v_pk_add_f32 v[202:203], v[202:203], s[24:25]
	v_rcp_f32_e32 v200, v200
	v_rcp_f32_e32 v201, v201
	v_rcp_f32_e32 v202, v202
	v_rcp_f32_e32 v203, v203
	v_pk_mul_f32 v[70:71], v[70:71], v[200:201]
	v_pk_mul_f32 v[72:73], v[72:73], v[202:203]
	v_pk_mul_f32 v[146:147], v[146:147], v[70:71]
	v_pk_mul_f32 v[148:149], v[148:149], v[72:73]
	v_cvt_pk_bf16_f32 v150, v150, v151
	v_cvt_pk_bf16_f32 v151, v152, v153
	v_cvt_pk_bf16_f32 v152, v146, v147
	v_cvt_pk_bf16_f32 v153, v148, v149
	s_and_b64 exec, s[22:23], s[40:41]
	global_store_dwordx4 v[170:171], v[150:153], off
	s_mov_b64 exec, s[22:23]
	v_cndmask_b32_e64 v200, v138, v142, s[16:17]
	v_cndmask_b32_e64 v201, v139, v143, s[16:17]
	v_cndmask_b32_e64 v202, v140, v144, s[16:17]
	v_cndmask_b32_e64 v203, v141, v145, s[16:17]
	v_cndmask_b32_e64 v204, v138, v142, s[42:43]
	v_cndmask_b32_e64 v205, v139, v143, s[42:43]
	v_cndmask_b32_e64 v206, v140, v144, s[42:43]
	v_cndmask_b32_e64 v207, v141, v145, s[42:43]
	v_pk_mul_f32 v[70:71], v[192:193], v[138:139]
	v_pk_mul_f32 v[72:73], v[194:195], v[140:141]
	v_fmac_f32_dpp v70, v200, v232 row_ror:1 row_mask:0xf bank_mask:0xf
	v_fmac_f32_dpp v71, v201, v233 row_ror:1 row_mask:0xf bank_mask:0xf
	v_fmac_f32_dpp v72, v202, v234 row_ror:1 row_mask:0xf bank_mask:0xf
	v_fmac_f32_dpp v73, v203, v235 row_ror:1 row_mask:0xf bank_mask:0xf
	v_fmac_f32_dpp v70, v204, v224 row_ror:2 row_mask:0xf bank_mask:0xf
	v_fmac_f32_dpp v71, v205, v225 row_ror:2 row_mask:0xf bank_mask:0xf
	v_fmac_f32_dpp v72, v206, v226 row_ror:2 row_mask:0xf bank_mask:0xf
	v_fmac_f32_dpp v73, v207, v227 row_ror:2 row_mask:0xf bank_mask:0xf
	v_pk_mul_f32 v[200:201], v[70:71], s[14:15]
	v_pk_mul_f32 v[202:203], v[72:73], s[14:15]
	v_exp_f32_e32 v200, v200
	v_exp_f32_e32 v201, v201
	v_exp_f32_e32 v202, v202
	v_exp_f32_e32 v203, v203
	v_pk_add_f32 v[200:201], v[200:201], s[24:25]
	v_pk_add_f32 v[202:203], v[202:203], s[24:25]
; __device__ __forceinline__ float sigmoidf_(float x) { return __builtin_amdgcn_rcpf(1.0f + __expf(-x)); }
;     __device__ __forceinline__ void operator()(const f32x4 (&acc)[2][2][4][2], const Unit& u, int wr, int wc, int fr, int fq) const {
;     ...
;             for (int m = 0; m < 4; ++m) {
;                 const size_t row = (size_t)(u.pm * BM + ai * HALF + wr * 64 + m * 16 + fr);
;                 float hg[8];
; #pragma unroll
;                 for (int n = 0; n < 2; ++n)
; #pragma unroll
;                     for (int i = 0; i < 4; ++i) {
;                         const float cur = acc[ai][0][m][n][i], prv = (m > 0) ? acc[ai][0][m > 0 ? m - 1 : 0][n][i] : cur;
;                         const float r1c = dpp_ror1(cur), r1p = dpp_ror1(prv), r2c = dpp_ror2(cur), r2p = dpp_ror2(prv);
;                         const float tm1 = f1 ? r1c : r1p, tm2 = f2 ? r2c : r2p;
;                         const float cv = w0[n][i] * tm2 + w1[n][i] * tm1 + w2[n][i] * cur;
;                         hg[4 * n + i] = cv * sigmoidf_(cv) * acc[ai][1][m][n][i];
;                     }
;                 if (m == 0 && fr < 2) {
;                     const f32x4 a0 = acc[ai][0][0][0], a1 = acc[ai][0][0][1], v0 = acc[ai][1][0][0], v1 = acc[ai][1][0][1];
;                     u32x4 wa, wv; wa.x = cvt_pk_bf16(a0[0], a0[1]); wa.y = cvt_pk_bf16(a0[2], a0[3]); wa.z = cvt_pk_bf16(a1[0], a1[1]); wa.w = cvt_pk_bf16(a1[2], a1[3]);
;                     wv.x = cvt_pk_bf16(v0[0], v0[1]); wv.y = cvt_pk_bf16(v0[2], v0[3]); wv.z = cvt_pk_bf16(v1[0], v1[1]); wv.w = cvt_pk_bf16(v1[2], v1[3]);
;                     *(u32x4*)(side + ((size_t)blk * 6 + 2 + fr) * ldh + ch0) = wa; *(u32x4*)(side + ((size_t)blk * 6 + 4 + fr) * ldh + ch0) = wv;
;                 } else {
;                     u32x4 w; w.x = cvt_pk_bf16(hg[0], hg[1]); w.y = cvt_pk_bf16(hg[2], hg[3]); w.z = cvt_pk_bf16(hg[4], hg[5]); w.w = cvt_pk_bf16(hg[6], hg[7]);
;                     *(u32x4*)(HG + row * ldh + ch0) = w;
;                 }
;                 if (m == 3 && fr >= 14) {
;                     const f32x4 a0 = acc[ai][0][3][0], a1 = acc[ai][0][3][1];
;                     u32x4 wa; wa.x = cvt_pk_bf16(a0[0], a0[1]); wa.y = cvt_pk_bf16(a0[2], a0[3]); wa.z = cvt_pk_bf16(a1[0], a1[1]); wa.w = cvt_pk_bf16(a1[2], a1[3]);
;                     *(u32x4*)(side + ((size_t)blk * 6 + (fr - 14)) * ldh + ch0) = wa;
;                 }
	v_rcp_f32_e32 v200, v200
	v_rcp_f32_e32 v201, v201
	v_rcp_f32_e32 v202, v202
	v_rcp_f32_e32 v203, v203
	v_pk_mul_f32 v[70:71], v[70:71], v[200:201]
	v_pk_mul_f32 v[72:73], v[72:73], v[202:203]
	v_pk_mul_f32 v[134:135], v[134:135], v[70:71]
	v_pk_mul_f32 v[136:137], v[136:137], v[72:73]
	v_cndmask_b32_e64 v200, v126, v130, s[16:17]
	v_cndmask_b32_e64 v201, v127, v131, s[16:17]
	v_cndmask_b32_e64 v202, v128, v132, s[16:17]
	v_cndmask_b32_e64 v203, v129, v133, s[16:17]
	v_cndmask_b32_e64 v204, v126, v130, s[42:43]
	v_cndmask_b32_e64 v205, v127, v131, s[42:43]
	v_cndmask_b32_e64 v206, v128, v132, s[42:43]
	v_cndmask_b32_e64 v207, v129, v133, s[42:43]
	v_pk_mul_f32 v[70:71], v[196:197], v[126:127]
	v_pk_mul_f32 v[72:73], v[198:199], v[128:129]
	v_fmac_f32_dpp v70, v200, v236 row_ror:1 row_mask:0xf bank_mask:0xf
	v_fmac_f32_dpp v71, v201, v237 row_ror:1 row_mask:0xf bank_mask:0xf
	v_fmac_f32_dpp v72, v202, v238 row_ror:1 row_mask:0xf bank_mask:0xf
	v_fmac_f32_dpp v73, v203, v239 row_ror:1 row_mask:0xf bank_mask:0xf
	v_fmac_f32_dpp v70, v204, v228 row_ror:2 row_mask:0xf bank_mask:0xf
	v_fmac_f32_dpp v71, v205, v229 row_ror:2 row_mask:0xf bank_mask:0xf
	v_fmac_f32_dpp v72, v206, v230 row_ror:2 row_mask:0xf bank_mask:0xf
	v_fmac_f32_dpp v73, v207, v231 row_ror:2 row_mask:0xf bank_mask:0xf
	v_pk_mul_f32 v[200:201], v[70:71], s[14:15]
	v_pk_mul_f32 v[202:203], v[72:73], s[14:15]
	v_exp_f32_e32 v200, v200
	v_exp_f32_e32 v201, v201
	v_exp_f32_e32 v202, v202
	v_exp_f32_e32 v203, v203
	v_pk_add_f32 v[200:201], v[200:201], s[24:25]
	v_pk_add_f32 v[202:203], v[202:203], s[24:25]
	v_rcp_f32_e32 v200, v200
	v_rcp_f32_e32 v201, v201
	v_rcp_f32_e32 v202, v202
	v_rcp_f32_e32 v203, v203
	v_pk_mul_f32 v[70:71], v[70:71], v[200:201]
	v_pk_mul_f32 v[72:73], v[72:73], v[202:203]
	v_pk_mul_f32 v[122:123], v[122:123], v[70:71]
	v_pk_mul_f32 v[124:125], v[124:125], v[72:73]
	v_cvt_pk_bf16_f32 v134, v134, v135
	v_cvt_pk_bf16_f32 v135, v136, v137
	v_cvt_pk_bf16_f32 v136, v122, v123
	v_cvt_pk_bf16_f32 v137, v124, v125
	v_add_co_u32_e32 v170, vcc, 0x56000, v170
	v_addc_co_u32_e32 v171, vcc, 0, v171, vcc
	global_store_dwordx4 v[170:171], v[134:137], off
	v_cndmask_b32_e64 v200, v118, v138, s[16:17]
	v_cndmask_b32_e64 v201, v119, v139, s[16:17]
	v_cndmask_b32_e64 v202, v120, v140, s[16:17]
	v_cndmask_b32_e64 v203, v121, v141, s[16:17]
	v_cndmask_b32_e64 v204, v118, v138, s[42:43]
	v_cndmask_b32_e64 v205, v119, v139, s[42:43]
	v_cndmask_b32_e64 v206, v120, v140, s[42:43]
	v_cndmask_b32_e64 v207, v121, v141, s[42:43]
	v_pk_mul_f32 v[70:71], v[192:193], v[118:119]
	v_pk_mul_f32 v[72:73], v[194:195], v[120:121]
	v_fmac_f32_dpp v70, v200, v232 row_ror:1 row_mask:0xf bank_mask:0xf
	v_fmac_f32_dpp v71, v201, v233 row_ror:1 row_mask:0xf bank_mask:0xf
	v_fmac_f32_dpp v72, v202, v234 row_ror:1 row_mask:0xf bank_mask:0xf
	v_fmac_f32_dpp v73, v203, v235 row_ror:1 row_mask:0xf bank_mask:0xf
	v_fmac_f32_dpp v70, v204, v224 row_ror:2 row_mask:0xf bank_mask:0xf
	v_fmac_f32_dpp v71, v205, v225 row_ror:2 row_mask:0xf bank_mask:0xf
	v_fmac_f32_dpp v72, v206, v226 row_ror:2 row_mask:0xf bank_mask:0xf
	v_fmac_f32_dpp v73, v207, v227 row_ror:2 row_mask:0xf bank_mask:0xf
	v_pk_mul_f32 v[200:201], v[70:71], s[14:15]
	v_pk_mul_f32 v[202:203], v[72:73], s[14:15]
	v_exp_f32_e32 v200, v200
	v_exp_f32_e32 v201, v201
	v_exp_f32_e32 v202, v202
	v_exp_f32_e32 v203, v203
	v_pk_add_f32 v[200:201], v[200:201], s[24:25]
	v_pk_add_f32 v[202:203], v[202:203], s[24:25]
	v_rcp_f32_e32 v200, v200
	v_rcp_f32_e32 v201, v201
	v_rcp_f32_e32 v202, v202
	v_rcp_f32_e32 v203, v203
	v_pk_mul_f32 v[70:71], v[70:71], v[200:201]
	v_pk_mul_f32 v[72:73], v[72:73], v[202:203]
	v_pk_mul_f32 v[114:115], v[114:115], v[70:71]
	v_pk_mul_f32 v[116:117], v[116:117], v[72:73]
	v_cndmask_b32_e64 v200, v110, v126, s[16:17]
	v_cndmask_b32_e64 v201, v111, v127, s[16:17]
	v_cndmask_b32_e64 v202, v112, v128, s[16:17]
	v_cndmask_b32_e64 v203, v113, v129, s[16:17]
	v_cndmask_b32_e64 v204, v110, v126, s[42:43]
	v_cndmask_b32_e64 v205, v111, v127, s[42:43]
	v_cndmask_b32_e64 v206, v112, v128, s[42:43]
	v_cndmask_b32_e64 v207, v113, v129, s[42:43]
	v_pk_mul_f32 v[70:71], v[196:197], v[110:111]
	v_pk_mul_f32 v[72:73], v[198:199], v[112:113]
	v_fmac_f32_dpp v70, v200, v236 row_ror:1 row_mask:0xf bank_mask:0xf
	v_fmac_f32_dpp v71, v201, v237 row_ror:1 row_mask:0xf bank_mask:0xf
	v_fmac_f32_dpp v72, v202, v238 row_ror:1 row_mask:0xf bank_mask:0xf
	v_fmac_f32_dpp v73, v203, v239 row_ror:1 row_mask:0xf bank_mask:0xf
	v_fmac_f32_dpp v70, v204, v228 row_ror:2 row_mask:0xf bank_mask:0xf
	v_fmac_f32_dpp v71, v205, v229 row_ror:2 row_mask:0xf bank_mask:0xf
	v_fmac_f32_dpp v72, v206, v230 row_ror:2 row_mask:0xf bank_mask:0xf
	v_fmac_f32_dpp v73, v207, v231 row_ror:2 row_mask:0xf bank_mask:0xf
	v_pk_mul_f32 v[200:201], v[70:71], s[14:15]
	v_pk_mul_f32 v[202:203], v[72:73], s[14:15]
	v_exp_f32_e32 v200, v200
	v_exp_f32_e32 v201, v201
	v_exp_f32_e32 v202, v202
	v_exp_f32_e32 v203, v203
	v_pk_add_f32 v[200:201], v[200:201], s[24:25]
	v_pk_add_f32 v[202:203], v[202:203], s[24:25]
	v_rcp_f32_e32 v200, v200
	v_rcp_f32_e32 v201, v201
	v_rcp_f32_e32 v202, v202
	v_rcp_f32_e32 v203, v203
	v_pk_mul_f32 v[70:71], v[70:71], v[200:201]
	v_pk_mul_f32 v[72:73], v[72:73], v[202:203]
	v_pk_mul_f32 v[106:107], v[106:107], v[70:71]
	v_pk_mul_f32 v[108:109], v[108:109], v[72:73]
	v_cvt_pk_bf16_f32 v114, v114, v115
	v_cvt_pk_bf16_f32 v115, v116, v117
	v_cvt_pk_bf16_f32 v116, v106, v107
	v_cvt_pk_bf16_f32 v117, v108, v109
	v_add_co_u32_e32 v170, vcc, 0x56000, v170
	v_addc_co_u32_e32 v171, vcc, 0, v171, vcc
	global_store_dwordx4 v[170:171], v[114:117], off
; __device__ __forceinline__ float sigmoidf_(float x) { return __builtin_amdgcn_rcpf(1.0f + __expf(-x)); }
;     __device__ __forceinline__ void operator()(const f32x4 (&acc)[2][2][4][2], const Unit& u, int wr, int wc, int fr, int fq) const {
;     ...
;             for (int m = 0; m < 4; ++m) {
;                 const size_t row = (size_t)(u.pm * BM + ai * HALF + wr * 64 + m * 16 + fr);
;                 float hg[8];
; #pragma unroll
;                 for (int n = 0; n < 2; ++n)
; #pragma unroll
;                     for (int i = 0; i < 4; ++i) {
;                         const float cur = acc[ai][0][m][n][i], prv = (m > 0) ? acc[ai][0][m > 0 ? m - 1 : 0][n][i] : cur;
;                         const float r1c = dpp_ror1(cur), r1p = dpp_ror1(prv), r2c = dpp_ror2(cur), r2p = dpp_ror2(prv);
;                         const float tm1 = f1 ? r1c : r1p, tm2 = f2 ? r2c : r2p;
;                         const float cv = w0[n][i] * tm2 + w1[n][i] * tm1 + w2[n][i] * cur;
;                         hg[4 * n + i] = cv * sigmoidf_(cv) * acc[ai][1][m][n][i];
;                     }
;                 if (m == 0 && fr < 2) {
;                     const f32x4 a0 = acc[ai][0][0][0], a1 = acc[ai][0][0][1], v0 = acc[ai][1][0][0], v1 = acc[ai][1][0][1];
;                     u32x4 wa, wv; wa.x = cvt_pk_bf16(a0[0], a0[1]); wa.y = cvt_pk_bf16(a0[2], a0[3]); wa.z = cvt_pk_bf16(a1[0], a1[1]); wa.w = cvt_pk_bf16(a1[2], a1[3]);
;                     wv.x = cvt_pk_bf16(v0[0], v0[1]); wv.y = cvt_pk_bf16(v0[2], v0[3]); wv.z = cvt_pk_bf16(v1[0], v1[1]); wv.w = cvt_pk_bf16(v1[2], v1[3]);
;                     *(u32x4*)(side + ((size_t)blk * 6 + 2 + fr) * ldh + ch0) = wa; *(u32x4*)(side + ((size_t)blk * 6 + 4 + fr) * ldh + ch0) = wv;
;                 } else {
;                     u32x4 w; w.x = cvt_pk_bf16(hg[0], hg[1]); w.y = cvt_pk_bf16(hg[2], hg[3]); w.z = cvt_pk_bf16(hg[4], hg[5]); w.w = cvt_pk_bf16(hg[6], hg[7]);
;                     *(u32x4*)(HG + row * ldh + ch0) = w;
;                 }
;                 if (m == 3 && fr >= 14) {
;                     const f32x4 a0 = acc[ai][0][3][0], a1 = acc[ai][0][3][1];
;                     u32x4 wa; wa.x = cvt_pk_bf16(a0[0], a0[1]); wa.y = cvt_pk_bf16(a0[2], a0[3]); wa.z = cvt_pk_bf16(a1[0], a1[1]); wa.w = cvt_pk_bf16(a1[2], a1[3]);
;                     *(u32x4*)(side + ((size_t)blk * 6 + (fr - 14)) * ldh + ch0) = wa;
;                 }
	v_cndmask_b32_e64 v200, v98, v118, s[16:17]
	v_cndmask_b32_e64 v201, v99, v119, s[16:17]
	v_cndmask_b32_e64 v202, v100, v120, s[16:17]
	v_cndmask_b32_e64 v203, v101, v121, s[16:17]
	v_cndmask_b32_e64 v204, v98, v118, s[42:43]
	v_cndmask_b32_e64 v205, v99, v119, s[42:43]
	v_cndmask_b32_e64 v206, v100, v120, s[42:43]
	v_cndmask_b32_e64 v207, v101, v121, s[42:43]
	v_pk_mul_f32 v[70:71], v[192:193], v[98:99]
	v_pk_mul_f32 v[72:73], v[194:195], v[100:101]
	v_fmac_f32_dpp v70, v200, v232 row_ror:1 row_mask:0xf bank_mask:0xf
	v_fmac_f32_dpp v71, v201, v233 row_ror:1 row_mask:0xf bank_mask:0xf
	v_fmac_f32_dpp v72, v202, v234 row_ror:1 row_mask:0xf bank_mask:0xf
	v_fmac_f32_dpp v73, v203, v235 row_ror:1 row_mask:0xf bank_mask:0xf
	v_fmac_f32_dpp v70, v204, v224 row_ror:2 row_mask:0xf bank_mask:0xf
	v_fmac_f32_dpp v71, v205, v225 row_ror:2 row_mask:0xf bank_mask:0xf
	v_fmac_f32_dpp v72, v206, v226 row_ror:2 row_mask:0xf bank_mask:0xf
	v_fmac_f32_dpp v73, v207, v227 row_ror:2 row_mask:0xf bank_mask:0xf
	v_pk_mul_f32 v[200:201], v[70:71], s[14:15]
	v_pk_mul_f32 v[202:203], v[72:73], s[14:15]
	v_exp_f32_e32 v200, v200
	v_exp_f32_e32 v201, v201
	v_exp_f32_e32 v202, v202
	v_exp_f32_e32 v203, v203
	v_pk_add_f32 v[200:201], v[200:201], s[24:25]
	v_pk_add_f32 v[202:203], v[202:203], s[24:25]
	v_rcp_f32_e32 v200, v200
	v_rcp_f32_e32 v201, v201
	v_rcp_f32_e32 v202, v202
	v_rcp_f32_e32 v203, v203
	v_pk_mul_f32 v[70:71], v[70:71], v[200:201]
	v_pk_mul_f32 v[72:73], v[72:73], v[202:203]
	v_pk_mul_f32 v[102:103], v[102:103], v[70:71]
	v_pk_mul_f32 v[104:105], v[104:105], v[72:73]
	v_cndmask_b32_e64 v200, v94, v110, s[16:17]
	v_cndmask_b32_e64 v201, v95, v111, s[16:17]
	v_cndmask_b32_e64 v202, v96, v112, s[16:17]
	v_cndmask_b32_e64 v203, v97, v113, s[16:17]
	v_cndmask_b32_e64 v204, v94, v110, s[42:43]
	v_cndmask_b32_e64 v205, v95, v111, s[42:43]
	v_cndmask_b32_e64 v206, v96, v112, s[42:43]
	v_cndmask_b32_e64 v207, v97, v113, s[42:43]
	v_pk_mul_f32 v[70:71], v[196:197], v[94:95]
	v_pk_mul_f32 v[72:73], v[198:199], v[96:97]
	v_fmac_f32_dpp v70, v200, v236 row_ror:1 row_mask:0xf bank_mask:0xf
	v_fmac_f32_dpp v71, v201, v237 row_ror:1 row_mask:0xf bank_mask:0xf
	v_fmac_f32_dpp v72, v202, v238 row_ror:1 row_mask:0xf bank_mask:0xf
	v_fmac_f32_dpp v73, v203, v239 row_ror:1 row_mask:0xf bank_mask:0xf
	v_fmac_f32_dpp v70, v204, v228 row_ror:2 row_mask:0xf bank_mask:0xf
	v_fmac_f32_dpp v71, v205, v229 row_ror:2 row_mask:0xf bank_mask:0xf
	v_fmac_f32_dpp v72, v206, v230 row_ror:2 row_mask:0xf bank_mask:0xf
	v_fmac_f32_dpp v73, v207, v231 row_ror:2 row_mask:0xf bank_mask:0xf
	v_pk_mul_f32 v[200:201], v[70:71], s[14:15]
	v_pk_mul_f32 v[202:203], v[72:73], s[14:15]
	v_exp_f32_e32 v200, v200
	v_exp_f32_e32 v201, v201
	v_exp_f32_e32 v202, v202
	v_exp_f32_e32 v203, v203
	v_pk_add_f32 v[200:201], v[200:201], s[24:25]
	v_pk_add_f32 v[202:203], v[202:203], s[24:25]
	v_rcp_f32_e32 v200, v200
	v_rcp_f32_e32 v201, v201
	v_rcp_f32_e32 v202, v202
	v_rcp_f32_e32 v203, v203
	v_pk_mul_f32 v[70:71], v[70:71], v[200:201]
	v_pk_mul_f32 v[72:73], v[72:73], v[202:203]
	v_pk_mul_f32 v[90:91], v[90:91], v[70:71]
	v_pk_mul_f32 v[92:93], v[92:93], v[72:73]
	v_cvt_pk_bf16_f32 v102, v102, v103
	v_cvt_pk_bf16_f32 v103, v104, v105
	v_cvt_pk_bf16_f32 v104, v90, v91
	v_cvt_pk_bf16_f32 v105, v92, v93
	v_add_co_u32_e32 v170, vcc, 0x56000, v170
	v_addc_co_u32_e32 v171, vcc, 0, v171, vcc
	global_store_dwordx4 v[170:171], v[102:105], off
	v_cvt_pk_bf16_f32 v154, v98, v99
	v_cvt_pk_bf16_f32 v155, v100, v101
	v_cvt_pk_bf16_f32 v156, v94, v95
	v_cvt_pk_bf16_f32 v157, v96, v97
	v_add_co_u32_e32 v188, vcc, 0xfffb4c00, v190
	v_addc_co_u32_e32 v189, vcc, -1, v191, vcc
	s_and_b64 exec, s[22:23], s[42:43]
	global_store_dwordx4 v[188:189], v[154:157], off
	s_mov_b64 exec, s[22:23]
	v_cvt_pk_bf16_f32 v154, v62, v63
	v_cvt_pk_bf16_f32 v155, v64, v65
	v_cvt_pk_bf16_f32 v156, v42, v43
	v_cvt_pk_bf16_f32 v157, v44, v45
	v_cvt_pk_bf16_f32 v204, v82, v83
	v_cvt_pk_bf16_f32 v205, v84, v85
	v_cvt_pk_bf16_f32 v206, v78, v79
	v_cvt_pk_bf16_f32 v207, v80, v81
	v_add_co_u32_e32 v188, vcc, 0x4b400, v190
	v_addc_co_u32_e32 v189, vcc, 0, v191, vcc
	v_add_co_u32_e32 v208, vcc, 0x56000, v190
	v_addc_co_u32_e32 v209, vcc, 0, v191, vcc
	s_andn2_b64 exec, s[22:23], s[40:41]
	global_store_dwordx4 v[188:189], v[154:157], off
	global_store_dwordx4 v[208:209], v[204:207], off
	s_mov_b64 exec, s[22:23]
	s_nop 4
	v_pk_mul_f32 v[70:71], v[192:193], v[62:63]
	v_pk_mul_f32 v[72:73], v[194:195], v[64:65]
	v_fmac_f32_dpp v70, v62, v232 row_ror:1 row_mask:0xf bank_mask:0xf
	v_fmac_f32_dpp v71, v63, v233 row_ror:1 row_mask:0xf bank_mask:0xf
	v_fmac_f32_dpp v72, v64, v234 row_ror:1 row_mask:0xf bank_mask:0xf
	v_fmac_f32_dpp v73, v65, v235 row_ror:1 row_mask:0xf bank_mask:0xf
	v_fmac_f32_dpp v70, v62, v224 row_ror:2 row_mask:0xf bank_mask:0xf
	v_fmac_f32_dpp v71, v63, v225 row_ror:2 row_mask:0xf bank_mask:0xf
	v_fmac_f32_dpp v72, v64, v226 row_ror:2 row_mask:0xf bank_mask:0xf
	v_fmac_f32_dpp v73, v65, v227 row_ror:2 row_mask:0xf bank_mask:0xf
	v_pk_mul_f32 v[200:201], v[70:71], s[14:15]
	v_pk_mul_f32 v[202:203], v[72:73], s[14:15]
	v_exp_f32_e32 v200, v200
	v_exp_f32_e32 v201, v201
	v_exp_f32_e32 v202, v202
	v_exp_f32_e32 v203, v203
	v_pk_add_f32 v[200:201], v[200:201], s[24:25]
	v_pk_add_f32 v[202:203], v[202:203], s[24:25]
	v_rcp_f32_e32 v200, v200
	v_rcp_f32_e32 v201, v201
	v_rcp_f32_e32 v202, v202
	v_rcp_f32_e32 v203, v203
	v_pk_mul_f32 v[70:71], v[70:71], v[200:201]
	v_pk_mul_f32 v[72:73], v[72:73], v[202:203]
	v_pk_mul_f32 v[82:83], v[82:83], v[70:71]
	v_pk_mul_f32 v[84:85], v[84:85], v[72:73]
	v_pk_mul_f32 v[70:71], v[196:197], v[42:43]
; __device__ __forceinline__ float sigmoidf_(float x) { return __builtin_amdgcn_rcpf(1.0f + __expf(-x)); }
;     __device__ __forceinline__ void operator()(const f32x4 (&acc)[2][2][4][2], const Unit& u, int wr, int wc, int fr, int fq) const {
;     ...
;             for (int m = 0; m < 4; ++m) {
;                 const size_t row = (size_t)(u.pm * BM + ai * HALF + wr * 64 + m * 16 + fr);
;                 float hg[8];
; #pragma unroll
;                 for (int n = 0; n < 2; ++n)
; #pragma unroll
;                     for (int i = 0; i < 4; ++i) {
;                         const float cur = acc[ai][0][m][n][i], prv = (m > 0) ? acc[ai][0][m > 0 ? m - 1 : 0][n][i] : cur;
;                         const float r1c = dpp_ror1(cur), r1p = dpp_ror1(prv), r2c = dpp_ror2(cur), r2p = dpp_ror2(prv);
;                         const float tm1 = f1 ? r1c : r1p, tm2 = f2 ? r2c : r2p;
;                         const float cv = w0[n][i] * tm2 + w1[n][i] * tm1 + w2[n][i] * cur;
;                         hg[4 * n + i] = cv * sigmoidf_(cv) * acc[ai][1][m][n][i];
;                     }
;                 if (m == 0 && fr < 2) {
;                     const f32x4 a0 = acc[ai][0][0][0], a1 = acc[ai][0][0][1], v0 = acc[ai][1][0][0], v1 = acc[ai][1][0][1];
;                     u32x4 wa, wv; wa.x = cvt_pk_bf16(a0[0], a0[1]); wa.y = cvt_pk_bf16(a0[2], a0[3]); wa.z = cvt_pk_bf16(a1[0], a1[1]); wa.w = cvt_pk_bf16(a1[2], a1[3]);
;                     wv.x = cvt_pk_bf16(v0[0], v0[1]); wv.y = cvt_pk_bf16(v0[2], v0[3]); wv.z = cvt_pk_bf16(v1[0], v1[1]); wv.w = cvt_pk_bf16(v1[2], v1[3]);
;                     *(u32x4*)(side + ((size_t)blk * 6 + 2 + fr) * ldh + ch0) = wa; *(u32x4*)(side + ((size_t)blk * 6 + 4 + fr) * ldh + ch0) = wv;
;                 } else {
;                     u32x4 w; w.x = cvt_pk_bf16(hg[0], hg[1]); w.y = cvt_pk_bf16(hg[2], hg[3]); w.z = cvt_pk_bf16(hg[4], hg[5]); w.w = cvt_pk_bf16(hg[6], hg[7]);
;                     *(u32x4*)(HG + row * ldh + ch0) = w;
;                 }
;                 if (m == 3 && fr >= 14) {
;                     const f32x4 a0 = acc[ai][0][3][0], a1 = acc[ai][0][3][1];
;                     u32x4 wa; wa.x = cvt_pk_bf16(a0[0], a0[1]); wa.y = cvt_pk_bf16(a0[2], a0[3]); wa.z = cvt_pk_bf16(a1[0], a1[1]); wa.w = cvt_pk_bf16(a1[2], a1[3]);
;                     *(u32x4*)(side + ((size_t)blk * 6 + (fr - 14)) * ldh + ch0) = wa;
;                 }
	v_pk_mul_f32 v[72:73], v[198:199], v[44:45]
	v_fmac_f32_dpp v70, v42, v236 row_ror:1 row_mask:0xf bank_mask:0xf
	v_fmac_f32_dpp v71, v43, v237 row_ror:1 row_mask:0xf bank_mask:0xf
	v_fmac_f32_dpp v72, v44, v238 row_ror:1 row_mask:0xf bank_mask:0xf
	v_fmac_f32_dpp v73, v45, v239 row_ror:1 row_mask:0xf bank_mask:0xf
	v_fmac_f32_dpp v70, v42, v228 row_ror:2 row_mask:0xf bank_mask:0xf
	v_fmac_f32_dpp v71, v43, v229 row_ror:2 row_mask:0xf bank_mask:0xf
	v_fmac_f32_dpp v72, v44, v230 row_ror:2 row_mask:0xf bank_mask:0xf
	v_fmac_f32_dpp v73, v45, v231 row_ror:2 row_mask:0xf bank_mask:0xf
	v_pk_mul_f32 v[200:201], v[70:71], s[14:15]
	v_pk_mul_f32 v[202:203], v[72:73], s[14:15]
	v_exp_f32_e32 v200, v200
	v_exp_f32_e32 v201, v201
	v_exp_f32_e32 v202, v202
	v_exp_f32_e32 v203, v203
	v_pk_add_f32 v[200:201], v[200:201], s[24:25]
	v_pk_add_f32 v[202:203], v[202:203], s[24:25]
	v_rcp_f32_e32 v200, v200
	v_rcp_f32_e32 v201, v201
	v_rcp_f32_e32 v202, v202
	v_rcp_f32_e32 v203, v203
	v_pk_mul_f32 v[70:71], v[70:71], v[200:201]
	v_pk_mul_f32 v[72:73], v[72:73], v[202:203]
	v_pk_mul_f32 v[78:79], v[78:79], v[70:71]
	v_pk_mul_f32 v[80:81], v[80:81], v[72:73]
	v_cvt_pk_bf16_f32 v82, v82, v83
	v_cvt_pk_bf16_f32 v83, v84, v85
	v_cvt_pk_bf16_f32 v84, v78, v79
	v_cvt_pk_bf16_f32 v85, v80, v81
	v_add_co_u32_e32 v170, vcc, 0x1ae000, v170
	v_addc_co_u32_e32 v171, vcc, 0, v171, vcc
	s_and_b64 exec, s[22:23], s[40:41]
	global_store_dwordx4 v[170:171], v[82:85], off
	s_mov_b64 exec, s[22:23]
	v_cndmask_b32_e64 v200, v58, v62, s[16:17]
	v_cndmask_b32_e64 v201, v59, v63, s[16:17]
	v_cndmask_b32_e64 v202, v60, v64, s[16:17]
	v_cndmask_b32_e64 v203, v61, v65, s[16:17]
	v_cndmask_b32_e64 v204, v58, v62, s[42:43]
	v_cndmask_b32_e64 v205, v59, v63, s[42:43]
	v_cndmask_b32_e64 v206, v60, v64, s[42:43]
	v_cndmask_b32_e64 v207, v61, v65, s[42:43]
	v_pk_mul_f32 v[70:71], v[192:193], v[58:59]
	v_pk_mul_f32 v[72:73], v[194:195], v[60:61]
	v_fmac_f32_dpp v70, v200, v232 row_ror:1 row_mask:0xf bank_mask:0xf
	v_fmac_f32_dpp v71, v201, v233 row_ror:1 row_mask:0xf bank_mask:0xf
	v_fmac_f32_dpp v72, v202, v234 row_ror:1 row_mask:0xf bank_mask:0xf
	v_fmac_f32_dpp v73, v203, v235 row_ror:1 row_mask:0xf bank_mask:0xf
	v_fmac_f32_dpp v70, v204, v224 row_ror:2 row_mask:0xf bank_mask:0xf
	v_fmac_f32_dpp v71, v205, v225 row_ror:2 row_mask:0xf bank_mask:0xf
	v_fmac_f32_dpp v72, v206, v226 row_ror:2 row_mask:0xf bank_mask:0xf
	v_fmac_f32_dpp v73, v207, v227 row_ror:2 row_mask:0xf bank_mask:0xf
	v_pk_mul_f32 v[200:201], v[70:71], s[14:15]
	v_pk_mul_f32 v[202:203], v[72:73], s[14:15]
	v_exp_f32_e32 v200, v200
	v_exp_f32_e32 v201, v201
	v_exp_f32_e32 v202, v202
	v_exp_f32_e32 v203, v203
	v_pk_add_f32 v[200:201], v[200:201], s[24:25]
	v_pk_add_f32 v[202:203], v[202:203], s[24:25]
	v_rcp_f32_e32 v200, v200
	v_rcp_f32_e32 v201, v201
	v_rcp_f32_e32 v202, v202
	v_rcp_f32_e32 v203, v203
	v_pk_mul_f32 v[70:71], v[70:71], v[200:201]
	v_pk_mul_f32 v[72:73], v[72:73], v[202:203]
	v_pk_mul_f32 v[46:47], v[46:47], v[70:71]
	v_pk_mul_f32 v[48:49], v[48:49], v[72:73]
	v_cndmask_b32_e64 v200, v38, v42, s[16:17]
	v_cndmask_b32_e64 v201, v39, v43, s[16:17]
	v_cndmask_b32_e64 v202, v40, v44, s[16:17]
	v_cndmask_b32_e64 v203, v41, v45, s[16:17]
	v_cndmask_b32_e64 v204, v38, v42, s[42:43]
	v_cndmask_b32_e64 v205, v39, v43, s[42:43]
	v_cndmask_b32_e64 v206, v40, v44, s[42:43]
	v_cndmask_b32_e64 v207, v41, v45, s[42:43]
	v_pk_mul_f32 v[70:71], v[196:197], v[38:39]
	v_pk_mul_f32 v[72:73], v[198:199], v[40:41]
	v_fmac_f32_dpp v70, v200, v236 row_ror:1 row_mask:0xf bank_mask:0xf
	v_fmac_f32_dpp v71, v201, v237 row_ror:1 row_mask:0xf bank_mask:0xf
	v_fmac_f32_dpp v72, v202, v238 row_ror:1 row_mask:0xf bank_mask:0xf
	v_fmac_f32_dpp v73, v203, v239 row_ror:1 row_mask:0xf bank_mask:0xf
	v_fmac_f32_dpp v70, v204, v228 row_ror:2 row_mask:0xf bank_mask:0xf
	v_fmac_f32_dpp v71, v205, v229 row_ror:2 row_mask:0xf bank_mask:0xf
	v_fmac_f32_dpp v72, v206, v230 row_ror:2 row_mask:0xf bank_mask:0xf
	v_fmac_f32_dpp v73, v207, v231 row_ror:2 row_mask:0xf bank_mask:0xf
	v_pk_mul_f32 v[200:201], v[70:71], s[14:15]
	v_pk_mul_f32 v[202:203], v[72:73], s[14:15]
	v_exp_f32_e32 v200, v200
	v_exp_f32_e32 v201, v201
	v_exp_f32_e32 v202, v202
	v_exp_f32_e32 v203, v203
	v_pk_add_f32 v[200:201], v[200:201], s[24:25]
	v_pk_add_f32 v[202:203], v[202:203], s[24:25]
	v_rcp_f32_e32 v200, v200
	v_rcp_f32_e32 v201, v201
	v_rcp_f32_e32 v202, v202
	v_rcp_f32_e32 v203, v203
	v_pk_mul_f32 v[70:71], v[70:71], v[200:201]
	v_pk_mul_f32 v[72:73], v[72:73], v[202:203]
	v_pk_mul_f32 v[34:35], v[34:35], v[70:71]
	v_pk_mul_f32 v[36:37], v[36:37], v[72:73]
	v_cvt_pk_bf16_f32 v46, v46, v47
	v_cvt_pk_bf16_f32 v47, v48, v49
	v_cvt_pk_bf16_f32 v48, v34, v35
	v_cvt_pk_bf16_f32 v49, v36, v37
	v_add_co_u32_e32 v170, vcc, 0x56000, v170
	v_addc_co_u32_e32 v171, vcc, 0, v171, vcc
	global_store_dwordx4 v[170:171], v[46:49], off
	v_cndmask_b32_e64 v200, v30, v58, s[16:17]
	v_cndmask_b32_e64 v201, v31, v59, s[16:17]
	v_cndmask_b32_e64 v202, v32, v60, s[16:17]
	v_cndmask_b32_e64 v203, v33, v61, s[16:17]
	v_cndmask_b32_e64 v204, v30, v58, s[42:43]
	v_cndmask_b32_e64 v205, v31, v59, s[42:43]
	v_cndmask_b32_e64 v206, v32, v60, s[42:43]
	v_cndmask_b32_e64 v207, v33, v61, s[42:43]
	v_pk_mul_f32 v[70:71], v[192:193], v[30:31]
	v_pk_mul_f32 v[72:73], v[194:195], v[32:33]
	v_fmac_f32_dpp v70, v200, v232 row_ror:1 row_mask:0xf bank_mask:0xf
	v_fmac_f32_dpp v71, v201, v233 row_ror:1 row_mask:0xf bank_mask:0xf
	v_fmac_f32_dpp v72, v202, v234 row_ror:1 row_mask:0xf bank_mask:0xf
	v_fmac_f32_dpp v73, v203, v235 row_ror:1 row_mask:0xf bank_mask:0xf
	v_fmac_f32_dpp v70, v204, v224 row_ror:2 row_mask:0xf bank_mask:0xf
;     __device__ __forceinline__ void operator()(const f32x4 (&acc)[2][2][4][2], const Unit& u, int wr, int wc, int fr, int fq) const {
;     ...
;                 for (int n = 0; n < 2; ++n)
; #pragma unroll
;                     for (int i = 0; i < 4; ++i) {
;                         const float cur = acc[ai][0][m][n][i], prv = (m > 0) ? acc[ai][0][m > 0 ? m - 1 : 0][n][i] : cur;
;                         const float r1c = dpp_ror1(cur), r1p = dpp_ror1(prv), r2c = dpp_ror2(cur), r2p = dpp_ror2(prv);
;                         const float tm1 = f1 ? r1c : r1p, tm2 = f2 ? r2c : r2p;
;                         const float cv = w0[n][i] * tm2 + w1[n][i] * tm1 + w2[n][i] * cur;
;                         hg[4 * n + i] = cv * sigmoidf_(cv) * acc[ai][1][m][n][i];
;                     }
;                 if (m == 0 && fr < 2) {
;                     const f32x4 a0 = acc[ai][0][0][0], a1 = acc[ai][0][0][1], v0 = acc[ai][1][0][0], v1 = acc[ai][1][0][1];
;                     u32x4 wa, wv; wa.x = cvt_pk_bf16(a0[0], a0[1]); wa.y = cvt_pk_bf16(a0[2], a0[3]); wa.z = cvt_pk_bf16(a1[0], a1[1]); wa.w = cvt_pk_bf16(a1[2], a1[3]);
;                     wv.x = cvt_pk_bf16(v0[0], v0[1]); wv.y = cvt_pk_bf16(v0[2], v0[3]); wv.z = cvt_pk_bf16(v1[0], v1[1]); wv.w = cvt_pk_bf16(v1[2], v1[3]);
;                     *(u32x4*)(side + ((size_t)blk * 6 + 2 + fr) * ldh + ch0) = wa; *(u32x4*)(side + ((size_t)blk * 6 + 4 + fr) * ldh + ch0) = wv;
;                 } else {
;                     u32x4 w; w.x = cvt_pk_bf16(hg[0], hg[1]); w.y = cvt_pk_bf16(hg[2], hg[3]); w.z = cvt_pk_bf16(hg[4], hg[5]); w.w = cvt_pk_bf16(hg[6], hg[7]);
;                     *(u32x4*)(HG + row * ldh + ch0) = w;
;                 }
;                 if (m == 3 && fr >= 14) {
;                     const f32x4 a0 = acc[ai][0][3][0], a1 = acc[ai][0][3][1];
;                     u32x4 wa; wa.x = cvt_pk_bf16(a0[0], a0[1]); wa.y = cvt_pk_bf16(a0[2], a0[3]); wa.z = cvt_pk_bf16(a1[0], a1[1]); wa.w = cvt_pk_bf16(a1[2], a1[3]);
;                     *(u32x4*)(side + ((size_t)blk * 6 + (fr - 14)) * ldh + ch0) = wa;
;                 }
; template <class Epi, class Sched, bool ALIGN_EPI = false, bool SP2 = false>
; __device__ __forceinline__ void gemm_phase(PG8_LAS unsigned char* lds, const Gemm g, const Sched& S, const Epi& E) {
;     ...
;         if (!has_next) break;
; #pragma unroll
;         for (int a = 0; a < 2; ++a)
; #pragma unroll
	v_fmac_f32_dpp v71, v205, v225 row_ror:2 row_mask:0xf bank_mask:0xf
	v_fmac_f32_dpp v72, v206, v226 row_ror:2 row_mask:0xf bank_mask:0xf
	v_fmac_f32_dpp v73, v207, v227 row_ror:2 row_mask:0xf bank_mask:0xf
	v_pk_mul_f32 v[200:201], v[70:71], s[14:15]
	v_pk_mul_f32 v[202:203], v[72:73], s[14:15]
	v_exp_f32_e32 v200, v200
	v_exp_f32_e32 v201, v201
	v_exp_f32_e32 v202, v202
	v_exp_f32_e32 v203, v203
	v_pk_add_f32 v[200:201], v[200:201], s[24:25]
	v_pk_add_f32 v[202:203], v[202:203], s[24:25]
	v_rcp_f32_e32 v200, v200
	v_rcp_f32_e32 v201, v201
	v_rcp_f32_e32 v202, v202
	v_rcp_f32_e32 v203, v203
	v_pk_mul_f32 v[70:71], v[70:71], v[200:201]
	v_pk_mul_f32 v[72:73], v[72:73], v[202:203]
	v_pk_mul_f32 v[26:27], v[26:27], v[70:71]
	v_pk_mul_f32 v[28:29], v[28:29], v[72:73]
	v_cndmask_b32_e64 v200, v22, v38, s[16:17]
	v_cndmask_b32_e64 v201, v23, v39, s[16:17]
	v_cndmask_b32_e64 v202, v24, v40, s[16:17]
	v_cndmask_b32_e64 v203, v25, v41, s[16:17]
	v_cndmask_b32_e64 v204, v22, v38, s[42:43]
	v_cndmask_b32_e64 v205, v23, v39, s[42:43]
	v_cndmask_b32_e64 v206, v24, v40, s[42:43]
	v_cndmask_b32_e64 v207, v25, v41, s[42:43]
	v_pk_mul_f32 v[70:71], v[196:197], v[22:23]
	v_pk_mul_f32 v[72:73], v[198:199], v[24:25]
	v_fmac_f32_dpp v70, v200, v236 row_ror:1 row_mask:0xf bank_mask:0xf
	v_fmac_f32_dpp v71, v201, v237 row_ror:1 row_mask:0xf bank_mask:0xf
	v_fmac_f32_dpp v72, v202, v238 row_ror:1 row_mask:0xf bank_mask:0xf
	v_fmac_f32_dpp v73, v203, v239 row_ror:1 row_mask:0xf bank_mask:0xf
	v_fmac_f32_dpp v70, v204, v228 row_ror:2 row_mask:0xf bank_mask:0xf
	v_fmac_f32_dpp v71, v205, v229 row_ror:2 row_mask:0xf bank_mask:0xf
	v_fmac_f32_dpp v72, v206, v230 row_ror:2 row_mask:0xf bank_mask:0xf
	v_fmac_f32_dpp v73, v207, v231 row_ror:2 row_mask:0xf bank_mask:0xf
	v_pk_mul_f32 v[200:201], v[70:71], s[14:15]
	v_pk_mul_f32 v[202:203], v[72:73], s[14:15]
	v_exp_f32_e32 v200, v200
	v_exp_f32_e32 v201, v201
	v_exp_f32_e32 v202, v202
	v_exp_f32_e32 v203, v203
	v_pk_add_f32 v[200:201], v[200:201], s[24:25]
	v_pk_add_f32 v[202:203], v[202:203], s[24:25]
	v_rcp_f32_e32 v200, v200
	v_rcp_f32_e32 v201, v201
	v_rcp_f32_e32 v202, v202
	v_rcp_f32_e32 v203, v203
	v_pk_mul_f32 v[70:71], v[70:71], v[200:201]
	v_pk_mul_f32 v[72:73], v[72:73], v[202:203]
	v_pk_mul_f32 v[18:19], v[18:19], v[70:71]
	v_pk_mul_f32 v[20:21], v[20:21], v[72:73]
	v_cvt_pk_bf16_f32 v26, v26, v27
	v_cvt_pk_bf16_f32 v27, v28, v29
	v_cvt_pk_bf16_f32 v28, v18, v19
	v_cvt_pk_bf16_f32 v29, v20, v21
	v_add_co_u32_e32 v170, vcc, 0x56000, v170
	v_addc_co_u32_e32 v171, vcc, 0, v171, vcc
	global_store_dwordx4 v[170:171], v[26:29], off
	v_cndmask_b32_e64 v200, v10, v30, s[16:17]
	v_cndmask_b32_e64 v201, v11, v31, s[16:17]
	v_cndmask_b32_e64 v202, v12, v32, s[16:17]
	v_cndmask_b32_e64 v203, v13, v33, s[16:17]
	v_cndmask_b32_e64 v204, v10, v30, s[42:43]
	v_cndmask_b32_e64 v205, v11, v31, s[42:43]
	v_cndmask_b32_e64 v206, v12, v32, s[42:43]
	v_cndmask_b32_e64 v207, v13, v33, s[42:43]
	v_pk_mul_f32 v[70:71], v[192:193], v[10:11]
	v_pk_mul_f32 v[72:73], v[194:195], v[12:13]
	v_fmac_f32_dpp v70, v200, v232 row_ror:1 row_mask:0xf bank_mask:0xf
	v_fmac_f32_dpp v71, v201, v233 row_ror:1 row_mask:0xf bank_mask:0xf
	v_fmac_f32_dpp v72, v202, v234 row_ror:1 row_mask:0xf bank_mask:0xf
	v_fmac_f32_dpp v73, v203, v235 row_ror:1 row_mask:0xf bank_mask:0xf
	v_fmac_f32_dpp v70, v204, v224 row_ror:2 row_mask:0xf bank_mask:0xf
	v_fmac_f32_dpp v71, v205, v225 row_ror:2 row_mask:0xf bank_mask:0xf
	v_fmac_f32_dpp v72, v206, v226 row_ror:2 row_mask:0xf bank_mask:0xf
	v_fmac_f32_dpp v73, v207, v227 row_ror:2 row_mask:0xf bank_mask:0xf
	v_pk_mul_f32 v[200:201], v[70:71], s[14:15]
	v_pk_mul_f32 v[202:203], v[72:73], s[14:15]
	v_exp_f32_e32 v200, v200
	v_exp_f32_e32 v201, v201
	v_exp_f32_e32 v202, v202
	v_exp_f32_e32 v203, v203
	v_pk_add_f32 v[200:201], v[200:201], s[24:25]
	v_pk_add_f32 v[202:203], v[202:203], s[24:25]
	v_rcp_f32_e32 v200, v200
	v_rcp_f32_e32 v201, v201
	v_rcp_f32_e32 v202, v202
	v_rcp_f32_e32 v203, v203
	v_pk_mul_f32 v[70:71], v[70:71], v[200:201]
	v_pk_mul_f32 v[72:73], v[72:73], v[202:203]
	v_pk_mul_f32 v[14:15], v[14:15], v[70:71]
	v_pk_mul_f32 v[16:17], v[16:17], v[72:73]
	v_cndmask_b32_e64 v200, v6, v22, s[16:17]
	v_cndmask_b32_e64 v201, v7, v23, s[16:17]
	v_cndmask_b32_e64 v202, v8, v24, s[16:17]
	v_cndmask_b32_e64 v203, v9, v25, s[16:17]
	v_cndmask_b32_e64 v204, v6, v22, s[42:43]
	v_cndmask_b32_e64 v205, v7, v23, s[42:43]
	v_cndmask_b32_e64 v206, v8, v24, s[42:43]
	v_cndmask_b32_e64 v207, v9, v25, s[42:43]
	v_pk_mul_f32 v[70:71], v[196:197], v[6:7]
	v_pk_mul_f32 v[72:73], v[198:199], v[8:9]
	v_fmac_f32_dpp v70, v200, v236 row_ror:1 row_mask:0xf bank_mask:0xf
	v_fmac_f32_dpp v71, v201, v237 row_ror:1 row_mask:0xf bank_mask:0xf
	v_fmac_f32_dpp v72, v202, v238 row_ror:1 row_mask:0xf bank_mask:0xf
	v_fmac_f32_dpp v73, v203, v239 row_ror:1 row_mask:0xf bank_mask:0xf
	v_fmac_f32_dpp v70, v204, v228 row_ror:2 row_mask:0xf bank_mask:0xf
	v_fmac_f32_dpp v71, v205, v229 row_ror:2 row_mask:0xf bank_mask:0xf
	v_fmac_f32_dpp v72, v206, v230 row_ror:2 row_mask:0xf bank_mask:0xf
	v_fmac_f32_dpp v73, v207, v231 row_ror:2 row_mask:0xf bank_mask:0xf
	v_pk_mul_f32 v[200:201], v[70:71], s[14:15]
	v_pk_mul_f32 v[202:203], v[72:73], s[14:15]
	v_exp_f32_e32 v200, v200
	v_exp_f32_e32 v201, v201
	v_exp_f32_e32 v202, v202
	v_exp_f32_e32 v203, v203
	v_pk_add_f32 v[200:201], v[200:201], s[24:25]
	v_pk_add_f32 v[202:203], v[202:203], s[24:25]
	v_rcp_f32_e32 v200, v200
	v_rcp_f32_e32 v201, v201
	v_rcp_f32_e32 v202, v202
	v_rcp_f32_e32 v203, v203
	v_pk_mul_f32 v[70:71], v[70:71], v[200:201]
	v_pk_mul_f32 v[72:73], v[72:73], v[202:203]
	v_pk_mul_f32 v[2:3], v[2:3], v[70:71]
	v_pk_mul_f32 v[4:5], v[4:5], v[72:73]
	v_cvt_pk_bf16_f32 v14, v14, v15
	v_cvt_pk_bf16_f32 v15, v16, v17
	v_cvt_pk_bf16_f32 v16, v2, v3
	v_cvt_pk_bf16_f32 v17, v4, v5
	v_add_co_u32_e32 v170, vcc, 0x56000, v170
	v_addc_co_u32_e32 v171, vcc, 0, v171, vcc
	global_store_dwordx4 v[170:171], v[14:17], off
	v_cvt_pk_bf16_f32 v154, v10, v11
	v_cvt_pk_bf16_f32 v155, v12, v13
	v_cvt_pk_bf16_f32 v156, v6, v7
	v_cvt_pk_bf16_f32 v157, v8, v9
	v_add_co_u32_e32 v188, vcc, 0xffff5400, v190
	v_addc_co_u32_e32 v189, vcc, -1, v191, vcc
	s_and_b64 exec, s[22:23], s[42:43]
	global_store_dwordx4 v[188:189], v[154:157], off
	s_mov_b64 exec, s[22:23]
	s_andn2_b64 vcc, exec, s[20:21]
	s_mov_b64 s[20:21], -1
	s_cbranch_vccnz .LBB0_699
	s_andn2_b64 vcc, exec, s[46:47]
	s_cbranch_vccnz .LBB0_698
	s_mov_b32 s32, 1
	s_branch .LBB0_698

;     __host__ __device__ bool next(int i, Unit& u) const { return at((long)i * G + c, u); }
; #define PG8_STAGE(bufoff, gbase, voff) do { _Pragma("unroll") for (int _i = 0; _i < 2; ++_i) \
;         __builtin_amdgcn_global_load_lds((const unsigned*)((const char*)(gbase) + (voff)[_i]), (PG8_LAS unsigned*)(lds + (bufoff) + ldsw + _i * 8192), 16, 0, 0); } while (0)
; #define PG8_LDA(dst, b, h) do { _Pragma("unroll") for (int m = 0; m < 4; ++m) _Pragma("unroll") for (int k = 0; k < 2; ++k) dst[m][k] = *(const PG8_LAS bf16x8*)(lds + PG8_SA(b, h) + aoff + m * 2048 + k * 1024); } while (0)
; #define PG8_LDB(dst, b, h) do { _Pragma("unroll") for (int n = 0; n < 2; ++n) _Pragma("unroll") for (int k = 0; k < 2; ++k) dst[n][k] = *(const PG8_LAS bf16x8*)(lds + PG8_SB(b, h) + boff + n * 2048 + k * 1024); } while (0)
; #define PG8_WAIT_V(n) asm volatile("s_waitcnt vmcnt(" #n ")" ::: "memory")
; #define PG8_BAR __builtin_amdgcn_s_barrier()
; template <class Epi, class Sched, bool ALIGN_EPI = false, bool SP2 = false>
; __device__ __forceinline__ void gemm_phase(PG8_LAS unsigned char* lds, const Gemm g, const Sched& S, const Epi& E) {
;     ...
;         const bool has_next = S.next(ui + 1, nxt);
;         const char* nA = has_next ? (const char*)g.A + (size_t)nxt.pm * tstep + (size_t)nxt.k0 * kstep : cA; const char* nB = has_next ? (const char*)g.Bt + (size_t)nxt.pn * tstep + (size_t)nxt.k0 * kstep : cB;
;         const int nt = cur.nt;
;         for (int t = 0; t < nt; t += 2) {
;             const bool last = (t == nt - 2);
;             const char* a1 = cA + (size_t)(t + 1) * kstep;
;             const char* a2 = last ? nA : cA + (size_t)(t + 2) * kstep; const char* b2 = last ? nB : cB + (size_t)(t + 2) * kstep;
;             const char* a3 = a2 + kstep; const char* b3 = b2 + kstep;
;             if (last && has_next) S.a_ready(nxt);
;             if constexpr (SP2) {
;             PG8_LDB(B0, 0, 0); PG8_LDB(B1, 0, 1); PG8_SCHED; PG8_LDA(At, 0, 0); PG8_STAGE(PG8_SA(1, 1), a1 + hstep, voffA);
;             PG8_WAIT_V(8); PG8_WAIT_L(0); PG8_BAR; PG8_MMA(0, 0, At, B0); PG8_MMA(0, 1, At, B1); PG8_BAR; PG8_SCHED;
;             PG8_LDA(At, 0, 1); PG8_STAGE(PG8_SB(0, 0), b2, voffB); PG8_STAGE(PG8_SB(0, 1), b2 + hstep, voffB); PG8_STAGE(PG8_SA(0, 0), a2, voffA);
;             PG8_WAIT_V(8); PG8_WAIT_L(0); PG8_BAR; PG8_MMA(1, 0, At, B0); PG8_MMA(1, 1, At, B1); PG8_BAR; PG8_SCHED;
.LBB0_914:
	s_add_i32 s15, s14, -2
	s_add_u32 s16, s50, 0x100
	s_addc_u32 s17, s51, 0
	s_mov_b32 s28, 0
	s_waitcnt vmcnt(0)
	s_waitcnt vmcnt(0)
	s_cmp_lg_u32 s32, 0
	s_cbranch_scc0 .Lrb_skip_4
	s_mov_b32 s32, 0
	s_barrier
.Lrb_skip_4:
	s_add_i32 s30, s28, 2
	s_add_u32 s26, s48, 0x100
	s_addc_u32 s27, s49, 0
	s_add_i32 s43, 0, 0x10000
	s_cmp_eq_u32 s15, s28
	s_cselect_b32 s51, s45, s27
	s_cselect_b32 s50, s44, s26
	s_cselect_b32 s29, s47, s17
	s_cselect_b32 s28, s46, s16
	s_add_i32 s59, 0, 0x14000
	v_add_u32_e32 v142, s43, v188
	v_add_u32_e32 v170, s59, v188
	ds_read_b128 v[130:133], v142
	ds_read_b128 v[134:137], v142 offset:1024
	ds_read_b128 v[138:141], v142 offset:2048
	ds_read_b128 v[142:145], v142 offset:3072
	ds_read_b128 v[146:149], v170
	ds_read_b128 v[150:153], v170 offset:1024
	ds_read_b128 v[178:181], v170 offset:2048
	ds_read_b128 v[182:185], v170 offset:3072
	v_lshl_add_u64 v[170:171], s[48:49], 0, v[176:177]
	s_add_i32 m0, s9, 0xc000
	ds_read_b128 v[192:195], v190
	ds_read_b128 v[196:199], v190 offset:1024
	ds_read_b128 v[200:203], v190 offset:2048
	ds_read_b128 v[204:207], v190 offset:3072
	ds_read_b128 v[220:223], v190 offset:4096
	ds_read_b128 v[224:227], v190 offset:5120
	ds_read_b128 v[228:231], v190 offset:6144
	ds_read_b128 v[232:235], v190 offset:7168
	global_load_lds_dwordx4 v[170:171], off
	v_lshl_add_u64 v[170:171], s[48:49], 0, v[174:175]
	s_add_i32 m0, s9, 0xe000
	s_nop 0
	global_load_lds_dwordx4 v[170:171], off
	s_waitcnt vmcnt(8)
	s_waitcnt lgkmcnt(0)
	s_setprio 1
	s_barrier
	v_mfma_f32_16x16x32_bf16 v[126:129], v[130:133], v[192:195], 0
	v_mfma_f32_16x16x32_bf16 v[122:125], v[138:141], v[192:195], 0
	v_mfma_f32_16x16x32_bf16 v[118:121], v[130:133], v[200:203], 0
	v_mfma_f32_16x16x32_bf16 v[114:117], v[138:141], v[200:203], 0
	v_mfma_f32_16x16x32_bf16 v[102:105], v[130:133], v[220:223], 0
	v_mfma_f32_16x16x32_bf16 v[94:97], v[138:141], v[220:223], 0
	v_mfma_f32_16x16x32_bf16 v[86:89], v[130:133], v[228:231], 0
	v_mfma_f32_16x16x32_bf16 v[78:81], v[138:141], v[228:231], 0
	v_mfma_f32_16x16x32_bf16 v[126:129], v[134:137], v[196:199], v[126:129]
	v_mfma_f32_16x16x32_bf16 v[122:125], v[142:145], v[196:199], v[122:125]
	v_mfma_f32_16x16x32_bf16 v[118:121], v[134:137], v[204:207], v[118:121]
	v_mfma_f32_16x16x32_bf16 v[114:117], v[142:145], v[204:207], v[114:117]
	v_mfma_f32_16x16x32_bf16 v[102:105], v[134:137], v[224:227], v[102:105]
	v_mfma_f32_16x16x32_bf16 v[94:97], v[142:145], v[224:227], v[94:97]
	v_mfma_f32_16x16x32_bf16 v[86:89], v[134:137], v[232:235], v[86:89]
	v_mfma_f32_16x16x32_bf16 v[78:81], v[142:145], v[232:235], v[78:81]
	v_mfma_f32_16x16x32_bf16 v[110:113], v[146:149], v[192:195], 0
	v_mfma_f32_16x16x32_bf16 v[106:109], v[178:181], v[192:195], 0
	v_mfma_f32_16x16x32_bf16 v[98:101], v[146:149], v[200:203], 0
	v_mfma_f32_16x16x32_bf16 v[90:93], v[178:181], v[200:203], 0
	v_mfma_f32_16x16x32_bf16 v[82:85], v[146:149], v[220:223], 0
	v_mfma_f32_16x16x32_bf16 v[74:77], v[178:181], v[220:223], 0
	v_mfma_f32_16x16x32_bf16 v[70:73], v[146:149], v[228:231], 0
	v_mfma_f32_16x16x32_bf16 v[66:69], v[178:181], v[228:231], 0
	v_mfma_f32_16x16x32_bf16 v[110:113], v[150:153], v[196:199], v[110:113]
	v_mfma_f32_16x16x32_bf16 v[106:109], v[182:185], v[196:199], v[106:109]
	v_mfma_f32_16x16x32_bf16 v[98:101], v[150:153], v[204:207], v[98:101]
	v_mfma_f32_16x16x32_bf16 v[90:93], v[182:185], v[204:207], v[90:93]
	v_mfma_f32_16x16x32_bf16 v[82:85], v[150:153], v[224:227], v[82:85]
	v_mfma_f32_16x16x32_bf16 v[74:77], v[182:185], v[224:227], v[74:77]
	v_mfma_f32_16x16x32_bf16 v[70:73], v[150:153], v[232:235], v[70:73]
	v_mfma_f32_16x16x32_bf16 v[66:69], v[182:185], v[232:235], v[66:69]
	s_barrier
	s_setprio 0
	s_add_i32 s43, s43, s8
	v_lshl_add_u64 v[170:171], s[28:29], 0, v[158:159]
	s_mov_b32 m0, s43
	ds_read_b128 v[192:195], v190 offset:16384
	ds_read_b128 v[196:199], v190 offset:17408
	ds_read_b128 v[200:203], v190 offset:18432
	ds_read_b128 v[204:207], v190 offset:19456
	ds_read_b128 v[220:223], v190 offset:20480
	ds_read_b128 v[224:227], v190 offset:21504
	ds_read_b128 v[228:231], v190 offset:22528
	ds_read_b128 v[232:235], v190 offset:23552
	global_load_lds_dwordx4 v[170:171], off
	s_add_i32 m0, s43, 0x2000
	s_add_u32 s48, s28, 0x2b0000
	v_lshl_add_u64 v[186:187], s[28:29], 0, v[172:173]
	s_addc_u32 s49, s29, 0
	s_add_i32 s43, s59, s8
	global_load_lds_dwordx4 v[186:187], off
	v_lshl_add_u64 v[208:209], s[48:49], 0, v[158:159]
	s_mov_b32 m0, s43
	v_lshl_add_u64 v[210:211], s[50:51], 0, v[156:157]
	global_load_lds_dwordx4 v[208:209], off
	v_lshl_add_u64 v[208:209], s[48:49], 0, v[172:173]
	s_add_i32 m0, s43, 0x2000
	s_nop 0
	global_load_lds_dwordx4 v[208:209], off
	v_lshl_add_u64 v[208:209], s[50:51], 0, v[154:155]
	s_mov_b32 m0, s9
	s_nop 0
	global_load_lds_dwordx4 v[208:209], off
	s_mov_b32 m0, s10
	s_nop 0
	global_load_lds_dwordx4 v[210:211], off
	s_waitcnt vmcnt(8)
	s_waitcnt lgkmcnt(0)
	s_setprio 1
	s_barrier
; #define PG8_STAGE(bufoff, gbase, voff) do { _Pragma("unroll") for (int _i = 0; _i < 2; ++_i) \
;         __builtin_amdgcn_global_load_lds((const unsigned*)((const char*)(gbase) + (voff)[_i]), (PG8_LAS unsigned*)(lds + (bufoff) + ldsw + _i * 8192), 16, 0, 0); } while (0)
; #define PG8_LDA(dst, b, h) do { _Pragma("unroll") for (int m = 0; m < 4; ++m) _Pragma("unroll") for (int k = 0; k < 2; ++k) dst[m][k] = *(const PG8_LAS bf16x8*)(lds + PG8_SA(b, h) + aoff + m * 2048 + k * 1024); } while (0)
; #define PG8_LDB(dst, b, h) do { _Pragma("unroll") for (int n = 0; n < 2; ++n) _Pragma("unroll") for (int k = 0; k < 2; ++k) dst[n][k] = *(const PG8_LAS bf16x8*)(lds + PG8_SB(b, h) + boff + n * 2048 + k * 1024); } while (0)
; #define PG8_MMA(ai, bj, At, Bt) do { __builtin_amdgcn_s_setprio(1); _Pragma("unroll") for (int m = 0; m < 4; ++m) _Pragma("unroll") for (int n = 0; n < 2; ++n) _Pragma("unroll") for (int k = 0; k < 2; ++k) \
;         acc[ai][bj][m][n] = __builtin_amdgcn_mfma_f32_16x16x32_bf16(Bt[n][k], At[m][k], acc[ai][bj][m][n], 0, 0, 0); __builtin_amdgcn_s_setprio(0); } while (0)
; #define PG8_WAIT_V(n) asm volatile("s_waitcnt vmcnt(" #n ")" ::: "memory")
; #define PG8_WAIT_L(n) asm volatile("s_waitcnt lgkmcnt(" #n ")" ::: "memory")
; #define PG8_BAR __builtin_amdgcn_s_barrier()
; #define PG8_SCHED __builtin_amdgcn_sched_barrier(0)
; template <class Epi, class Sched, bool ALIGN_EPI = false, bool SP2 = false>
; __device__ __forceinline__ void gemm_phase(PG8_LAS unsigned char* lds, const Gemm g, const Sched& S, const Epi& E) {
;     ...
;             PG8_WAIT_V(8); PG8_WAIT_L(0); PG8_BAR; PG8_MMA(1, 0, At, B0); PG8_MMA(1, 1, At, B1); PG8_BAR; PG8_SCHED;
;             PG8_LDB(B0, 1, 0); PG8_LDB(B1, 1, 1); PG8_SCHED; PG8_LDA(At, 1, 0); PG8_STAGE(PG8_SA(0, 1), a2 + hstep, voffA);
;             PG8_WAIT_V(8); PG8_WAIT_L(0); PG8_BAR; PG8_MMA(0, 0, At, B0); PG8_MMA(0, 1, At, B1); PG8_BAR; PG8_SCHED;
	v_mfma_f32_16x16x32_bf16 v[62:65], v[130:133], v[192:195], 0
	v_mfma_f32_16x16x32_bf16 v[58:61], v[138:141], v[192:195], 0
	v_mfma_f32_16x16x32_bf16 v[54:57], v[130:133], v[200:203], 0
	v_mfma_f32_16x16x32_bf16 v[46:49], v[138:141], v[200:203], 0
	v_mfma_f32_16x16x32_bf16 v[38:41], v[130:133], v[220:223], 0
	v_mfma_f32_16x16x32_bf16 v[30:33], v[138:141], v[220:223], 0
	v_mfma_f32_16x16x32_bf16 v[22:25], v[130:133], v[228:231], 0
	v_mfma_f32_16x16x32_bf16 v[14:17], v[138:141], v[228:231], 0
	v_mfma_f32_16x16x32_bf16 v[62:65], v[134:137], v[196:199], v[62:65]
	v_mfma_f32_16x16x32_bf16 v[58:61], v[142:145], v[196:199], v[58:61]
	v_mfma_f32_16x16x32_bf16 v[54:57], v[134:137], v[204:207], v[54:57]
	v_mfma_f32_16x16x32_bf16 v[46:49], v[142:145], v[204:207], v[46:49]
	v_mfma_f32_16x16x32_bf16 v[38:41], v[134:137], v[224:227], v[38:41]
	v_mfma_f32_16x16x32_bf16 v[30:33], v[142:145], v[224:227], v[30:33]
	v_mfma_f32_16x16x32_bf16 v[22:25], v[134:137], v[232:235], v[22:25]
	v_mfma_f32_16x16x32_bf16 v[14:17], v[142:145], v[232:235], v[14:17]
	v_mfma_f32_16x16x32_bf16 v[50:53], v[146:149], v[192:195], 0
	v_mfma_f32_16x16x32_bf16 v[42:45], v[178:181], v[192:195], 0
	v_mfma_f32_16x16x32_bf16 v[34:37], v[146:149], v[200:203], 0
	v_mfma_f32_16x16x32_bf16 v[26:29], v[178:181], v[200:203], 0
	v_mfma_f32_16x16x32_bf16 v[18:21], v[146:149], v[220:223], 0
	v_mfma_f32_16x16x32_bf16 v[10:13], v[178:181], v[220:223], 0
	v_mfma_f32_16x16x32_bf16 v[6:9], v[146:149], v[228:231], 0
	v_mfma_f32_16x16x32_bf16 v[2:5], v[178:181], v[228:231], 0
	v_mfma_f32_16x16x32_bf16 v[50:53], v[150:153], v[196:199], v[50:53]
	v_mfma_f32_16x16x32_bf16 v[42:45], v[182:185], v[196:199], v[42:45]
	v_mfma_f32_16x16x32_bf16 v[34:37], v[150:153], v[204:207], v[34:37]
	v_mfma_f32_16x16x32_bf16 v[26:29], v[182:185], v[204:207], v[26:29]
	v_mfma_f32_16x16x32_bf16 v[18:21], v[150:153], v[224:227], v[18:21]
	v_mfma_f32_16x16x32_bf16 v[10:13], v[182:185], v[224:227], v[10:13]
	v_mfma_f32_16x16x32_bf16 v[6:9], v[150:153], v[232:235], v[6:9]
	v_mfma_f32_16x16x32_bf16 v[2:5], v[182:185], v[232:235], v[2:5]
	s_barrier
	s_setprio 0
	s_add_i32 s43, 0, 0x18000
	s_add_i32 s59, 0, 0x1c000
	v_add_u32_e32 v142, s43, v188
	v_add_u32_e32 v182, s59, v188
	ds_read_b128 v[130:133], v142
	ds_read_b128 v[134:137], v142 offset:1024
	ds_read_b128 v[138:141], v142 offset:2048
	ds_read_b128 v[142:145], v142 offset:3072
	ds_read_b128 v[146:149], v182
	ds_read_b128 v[150:153], v182 offset:1024
	ds_read_b128 v[178:181], v182 offset:2048
	ds_read_b128 v[182:185], v182 offset:3072
	s_add_u32 s48, s50, 0x2b0000
	s_addc_u32 s49, s51, 0
	s_mov_b32 m0, s11
	v_lshl_add_u64 v[236:237], s[48:49], 0, v[154:155]
	ds_read_b128 v[192:195], v190 offset:32768
	ds_read_b128 v[196:199], v190 offset:33792
	ds_read_b128 v[200:203], v190 offset:34816
	ds_read_b128 v[204:207], v190 offset:35840
	ds_read_b128 v[220:223], v190 offset:36864
	ds_read_b128 v[224:227], v190 offset:37888
	ds_read_b128 v[228:231], v190 offset:38912
	ds_read_b128 v[232:235], v190 offset:39936
	global_load_lds_dwordx4 v[236:237], off
	v_lshl_add_u64 v[236:237], s[48:49], 0, v[156:157]
	s_mov_b32 m0, s12
	s_nop 0
	global_load_lds_dwordx4 v[236:237], off
	s_waitcnt vmcnt(8)
	s_waitcnt lgkmcnt(0)
	s_setprio 1
	s_barrier
	v_mfma_f32_16x16x32_bf16 v[126:129], v[130:133], v[192:195], v[126:129]
	v_mfma_f32_16x16x32_bf16 v[122:125], v[138:141], v[192:195], v[122:125]
	v_mfma_f32_16x16x32_bf16 v[118:121], v[130:133], v[200:203], v[118:121]
	v_mfma_f32_16x16x32_bf16 v[114:117], v[138:141], v[200:203], v[114:117]
	v_mfma_f32_16x16x32_bf16 v[102:105], v[130:133], v[220:223], v[102:105]
	v_mfma_f32_16x16x32_bf16 v[94:97], v[138:141], v[220:223], v[94:97]
	v_mfma_f32_16x16x32_bf16 v[86:89], v[130:133], v[228:231], v[86:89]
	v_mfma_f32_16x16x32_bf16 v[78:81], v[138:141], v[228:231], v[78:81]
	v_mfma_f32_16x16x32_bf16 v[126:129], v[134:137], v[196:199], v[126:129]
	v_mfma_f32_16x16x32_bf16 v[122:125], v[142:145], v[196:199], v[122:125]
	v_mfma_f32_16x16x32_bf16 v[118:121], v[134:137], v[204:207], v[118:121]
	v_mfma_f32_16x16x32_bf16 v[114:117], v[142:145], v[204:207], v[114:117]
	v_mfma_f32_16x16x32_bf16 v[102:105], v[134:137], v[224:227], v[102:105]
	v_mfma_f32_16x16x32_bf16 v[94:97], v[142:145], v[224:227], v[94:97]
	v_mfma_f32_16x16x32_bf16 v[86:89], v[134:137], v[232:235], v[86:89]
	v_mfma_f32_16x16x32_bf16 v[78:81], v[142:145], v[232:235], v[78:81]
	v_mfma_f32_16x16x32_bf16 v[110:113], v[146:149], v[192:195], v[110:113]
	v_mfma_f32_16x16x32_bf16 v[106:109], v[178:181], v[192:195], v[106:109]
	v_mfma_f32_16x16x32_bf16 v[98:101], v[146:149], v[200:203], v[98:101]
	v_mfma_f32_16x16x32_bf16 v[90:93], v[178:181], v[200:203], v[90:93]
	v_mfma_f32_16x16x32_bf16 v[82:85], v[146:149], v[220:223], v[82:85]
	v_mfma_f32_16x16x32_bf16 v[74:77], v[178:181], v[220:223], v[74:77]
	v_mfma_f32_16x16x32_bf16 v[70:73], v[146:149], v[228:231], v[70:73]
	v_mfma_f32_16x16x32_bf16 v[66:69], v[178:181], v[228:231], v[66:69]
	v_mfma_f32_16x16x32_bf16 v[110:113], v[150:153], v[196:199], v[110:113]
	v_mfma_f32_16x16x32_bf16 v[106:109], v[182:185], v[196:199], v[106:109]
	v_mfma_f32_16x16x32_bf16 v[98:101], v[150:153], v[204:207], v[98:101]
	v_mfma_f32_16x16x32_bf16 v[90:93], v[182:185], v[204:207], v[90:93]
	v_mfma_f32_16x16x32_bf16 v[82:85], v[150:153], v[224:227], v[82:85]
	v_mfma_f32_16x16x32_bf16 v[74:77], v[182:185], v[224:227], v[74:77]
	v_mfma_f32_16x16x32_bf16 v[70:73], v[150:153], v[232:235], v[70:73]
	v_mfma_f32_16x16x32_bf16 v[66:69], v[182:185], v[232:235], v[66:69]
	s_barrier
; #define PG8_STAGE(bufoff, gbase, voff) do { _Pragma("unroll") for (int _i = 0; _i < 2; ++_i) \
;         __builtin_amdgcn_global_load_lds((const unsigned*)((const char*)(gbase) + (voff)[_i]), (PG8_LAS unsigned*)(lds + (bufoff) + ldsw + _i * 8192), 16, 0, 0); } while (0)
; #define PG8_LDA(dst, b, h) do { _Pragma("unroll") for (int m = 0; m < 4; ++m) _Pragma("unroll") for (int k = 0; k < 2; ++k) dst[m][k] = *(const PG8_LAS bf16x8*)(lds + PG8_SA(b, h) + aoff + m * 2048 + k * 1024); } while (0)
; #define PG8_LDB(dst, b, h) do { _Pragma("unroll") for (int n = 0; n < 2; ++n) _Pragma("unroll") for (int k = 0; k < 2; ++k) dst[n][k] = *(const PG8_LAS bf16x8*)(lds + PG8_SB(b, h) + boff + n * 2048 + k * 1024); } while (0)
; #define PG8_MMA(ai, bj, At, Bt) do { __builtin_amdgcn_s_setprio(1); _Pragma("unroll") for (int m = 0; m < 4; ++m) _Pragma("unroll") for (int n = 0; n < 2; ++n) _Pragma("unroll") for (int k = 0; k < 2; ++k) \
;         acc[ai][bj][m][n] = __builtin_amdgcn_mfma_f32_16x16x32_bf16(Bt[n][k], At[m][k], acc[ai][bj][m][n], 0, 0, 0); __builtin_amdgcn_s_setprio(0); } while (0)
; #define PG8_WAIT_V(n) asm volatile("s_waitcnt vmcnt(" #n ")" ::: "memory")
; #define PG8_WAIT_L(n) asm volatile("s_waitcnt lgkmcnt(" #n ")" ::: "memory")
; #define PG8_BAR __builtin_amdgcn_s_barrier()
; #define PG8_SCHED __builtin_amdgcn_sched_barrier(0)
; template <class Epi, class Sched, bool ALIGN_EPI = false, bool SP2 = false>
; __device__ __forceinline__ void gemm_phase(PG8_LAS unsigned char* lds, const Gemm g, const Sched& S, const Epi& E) {
;     ...
;             PG8_LDB(B0, 1, 0); PG8_LDB(B1, 1, 1); PG8_SCHED; PG8_LDA(At, 1, 0); PG8_STAGE(PG8_SA(0, 1), a2 + hstep, voffA);
;             PG8_WAIT_V(8); PG8_WAIT_L(0); PG8_BAR; PG8_MMA(0, 0, At, B0); PG8_MMA(0, 1, At, B1); PG8_BAR; PG8_SCHED;
;             PG8_LDA(At, 1, 1); PG8_STAGE(PG8_SB(1, 0), b3, voffB); PG8_STAGE(PG8_SB(1, 1), b3 + hstep, voffB); PG8_STAGE(PG8_SA(1, 0), a3, voffA);
;             PG8_WAIT_V(8); PG8_WAIT_L(0); PG8_BAR; PG8_MMA(1, 0, At, B0); PG8_MMA(1, 1, At, B1); PG8_BAR; PG8_SCHED;
	s_setprio 0
	s_add_i32 s43, s43, s8
	v_lshl_add_u64 v[170:171], v[170:171], 0, s[96:97]
	s_mov_b32 m0, s43
	ds_read_b128 v[192:195], v190 offset:49152
	ds_read_b128 v[196:199], v190 offset:50176
	ds_read_b128 v[200:203], v190 offset:51200
	ds_read_b128 v[204:207], v190 offset:52224
	ds_read_b128 v[220:223], v190 offset:53248
	ds_read_b128 v[224:227], v190 offset:54272
	ds_read_b128 v[228:231], v190 offset:55296
	ds_read_b128 v[232:235], v190 offset:56320
	global_load_lds_dwordx4 v[170:171], off
	s_add_i32 m0, s43, 0x2000
	s_add_u32 s28, s28, 0x2b0080
	v_lshl_add_u64 v[170:171], v[186:187], 0, s[96:97]
	s_addc_u32 s29, s29, 0
	s_add_i32 s43, s59, s8
	global_load_lds_dwordx4 v[170:171], off
	v_lshl_add_u64 v[170:171], s[28:29], 0, v[158:159]
	s_mov_b32 m0, s43
	s_nop 0
	global_load_lds_dwordx4 v[170:171], off
	v_lshl_add_u64 v[170:171], s[28:29], 0, v[172:173]
	s_add_i32 m0, s43, 0x2000
	s_nop 0
	global_load_lds_dwordx4 v[170:171], off
	v_lshl_add_u64 v[170:171], v[208:209], 0, s[96:97]
	s_mov_b32 m0, s35
	s_nop 0
	global_load_lds_dwordx4 v[170:171], off
	v_lshl_add_u64 v[170:171], v[210:211], 0, s[96:97]
	s_mov_b32 m0, s52
	s_nop 0
	global_load_lds_dwordx4 v[170:171], off
	s_waitcnt vmcnt(8)
	s_waitcnt lgkmcnt(0)
	s_setprio 1
	s_barrier
	v_mfma_f32_16x16x32_bf16 v[62:65], v[130:133], v[192:195], v[62:65]
	v_mfma_f32_16x16x32_bf16 v[58:61], v[138:141], v[192:195], v[58:61]
	v_mfma_f32_16x16x32_bf16 v[54:57], v[130:133], v[200:203], v[54:57]
	v_mfma_f32_16x16x32_bf16 v[46:49], v[138:141], v[200:203], v[46:49]
	v_mfma_f32_16x16x32_bf16 v[38:41], v[130:133], v[220:223], v[38:41]
	v_mfma_f32_16x16x32_bf16 v[30:33], v[138:141], v[220:223], v[30:33]
	v_mfma_f32_16x16x32_bf16 v[22:25], v[130:133], v[228:231], v[22:25]
	v_mfma_f32_16x16x32_bf16 v[14:17], v[138:141], v[228:231], v[14:17]
	v_mfma_f32_16x16x32_bf16 v[62:65], v[134:137], v[196:199], v[62:65]
	v_mfma_f32_16x16x32_bf16 v[58:61], v[142:145], v[196:199], v[58:61]
	v_mfma_f32_16x16x32_bf16 v[54:57], v[134:137], v[204:207], v[54:57]
	v_mfma_f32_16x16x32_bf16 v[46:49], v[142:145], v[204:207], v[46:49]
	v_mfma_f32_16x16x32_bf16 v[38:41], v[134:137], v[224:227], v[38:41]
	v_mfma_f32_16x16x32_bf16 v[30:33], v[142:145], v[224:227], v[30:33]
	v_mfma_f32_16x16x32_bf16 v[22:25], v[134:137], v[232:235], v[22:25]
	v_mfma_f32_16x16x32_bf16 v[14:17], v[142:145], v[232:235], v[14:17]
	v_mfma_f32_16x16x32_bf16 v[50:53], v[146:149], v[192:195], v[50:53]
	v_mfma_f32_16x16x32_bf16 v[42:45], v[178:181], v[192:195], v[42:45]
	v_mfma_f32_16x16x32_bf16 v[34:37], v[146:149], v[200:203], v[34:37]
	v_mfma_f32_16x16x32_bf16 v[26:29], v[178:181], v[200:203], v[26:29]
	v_mfma_f32_16x16x32_bf16 v[18:21], v[146:149], v[220:223], v[18:21]
	v_mfma_f32_16x16x32_bf16 v[10:13], v[178:181], v[220:223], v[10:13]
	v_mfma_f32_16x16x32_bf16 v[6:9], v[146:149], v[228:231], v[6:9]
	v_mfma_f32_16x16x32_bf16 v[2:5], v[178:181], v[228:231], v[2:5]
	v_mfma_f32_16x16x32_bf16 v[50:53], v[150:153], v[196:199], v[50:53]
	v_mfma_f32_16x16x32_bf16 v[42:45], v[182:185], v[196:199], v[42:45]
	v_mfma_f32_16x16x32_bf16 v[34:37], v[150:153], v[204:207], v[34:37]
	v_mfma_f32_16x16x32_bf16 v[26:29], v[182:185], v[204:207], v[26:29]
	v_mfma_f32_16x16x32_bf16 v[18:21], v[150:153], v[224:227], v[18:21]
	v_mfma_f32_16x16x32_bf16 v[10:13], v[182:185], v[224:227], v[10:13]
	v_mfma_f32_16x16x32_bf16 v[6:9], v[150:153], v[232:235], v[6:9]
	v_mfma_f32_16x16x32_bf16 v[2:5], v[182:185], v[232:235], v[2:5]
	s_barrier
	s_setprio 0
	s_add_u32 s16, s16, 0x100
	s_addc_u32 s17, s17, 0
	s_cmp_ge_i32 s30, s14
	s_mov_b64 s[48:49], s[26:27]
	s_mov_b32 s28, s30
	s_cbranch_scc1 .Lpeel_exit_4

; #define PG8_BAR __builtin_amdgcn_s_barrier()
; template <class Epi, class Sched, bool ALIGN_EPI = false, bool SP2 = false>
; __device__ __forceinline__ void gemm_phase(PG8_LAS unsigned char* lds, const Gemm g, const Sched& S, const Epi& E) {
;     ...
;         if (!has_next) break;
; #pragma unroll
;         for (int a = 0; a < 2; ++a)
; #pragma unroll
;             for (int b = 0; b < 2; ++b)
; #pragma unroll
;                 for (int m = 0; m < 4; ++m)
; #pragma unroll
;                     for (int n = 0; n < 2; ++n) acc[a][b][m][n] = (f32x4){0.f, 0.f, 0.f, 0.f};
;         cur = nxt; cA = nA; cB = nB; ++ui;
;         if constexpr (ALIGN_EPI) { if (wr == 1) PG8_BAR; }
.LBB0_923:
	s_andn2_b64 vcc, exec, s[20:21]
	s_cbranch_vccnz .LBB0_893
	s_mov_b32 s32, 1
	s_branch .LBB0_893
